# nt also on the normalised-activation (hn) stores and on the prologue's once-read f32 weight / adaLN weight loads
# speedup vs baseline: 1.0103x; 1.0015x over previous
.LBB0_8:
	v_ashrrev_i32_e32 v15, 31, v1
	v_lshrrev_b32_e32 v15, 26, v15
	v_add_u32_e32 v15, v1, v15
	v_and_b32_e32 v16, 0xffffffc0, v15
	v_lshlrev_b32_e32 v15, 6, v15
	v_and_b32_e32 v15, 0xfffff000, v15
	v_or_b32_e32 v18, v16, v6
	v_sub_u32_e32 v20, v9, v15
	v_or_b32_e32 v22, 4, v18
	v_ashrrev_i32_e32 v17, 31, v16
	v_ashrrev_i32_e32 v19, 31, v18
	v_or_b32_e32 v24, 8, v18
	v_or_b32_e32 v26, 12, v18
	v_or_b32_e32 v28, 16, v18
	v_or_b32_e32 v30, 20, v18
	v_or_b32_e32 v32, 24, v18
	v_or_b32_e32 v34, 28, v18
	v_or_b32_e32 v36, 32, v18
	v_or_b32_e32 v38, 36, v18
	v_or_b32_e32 v40, 40, v18
	v_or_b32_e32 v42, 44, v18
	v_or_b32_e32 v44, 48, v18
	v_or_b32_e32 v46, 52, v18
	v_or_b32_e32 v48, 56, v18
	v_or_b32_e32 v50, 60, v18
	v_ashrrev_i32_e32 v21, 31, v20
	v_ashrrev_i32_e32 v23, 31, v22
	v_lshl_add_u64 v[80:81], v[16:17], 1, v[4:5]
	v_lshlrev_b64 v[16:17], 14, v[18:19]
	v_ashrrev_i32_e32 v25, 31, v24
	v_ashrrev_i32_e32 v27, 31, v26
	v_ashrrev_i32_e32 v29, 31, v28
	v_ashrrev_i32_e32 v31, 31, v30
	v_ashrrev_i32_e32 v33, 31, v32
	v_ashrrev_i32_e32 v35, 31, v34
	v_ashrrev_i32_e32 v37, 31, v36
	v_ashrrev_i32_e32 v39, 31, v38
	v_ashrrev_i32_e32 v41, 31, v40
	v_ashrrev_i32_e32 v43, 31, v42
	v_ashrrev_i32_e32 v45, 31, v44
	v_ashrrev_i32_e32 v47, 31, v46
	v_ashrrev_i32_e32 v49, 31, v48
	v_ashrrev_i32_e32 v51, 31, v50
	v_add_u32_e32 v18, v20, v7
	v_lshl_add_u64 v[20:21], v[20:21], 2, v[2:3]
	v_lshlrev_b64 v[22:23], 14, v[22:23]
	v_lshlrev_b64 v[24:25], 14, v[24:25]
	v_lshlrev_b64 v[26:27], 14, v[26:27]
	v_lshlrev_b64 v[28:29], 14, v[28:29]
	v_lshlrev_b64 v[30:31], 14, v[30:31]
	v_lshlrev_b64 v[32:33], 14, v[32:33]
	v_lshlrev_b64 v[34:35], 14, v[34:35]
	v_lshlrev_b64 v[36:37], 14, v[36:37]
	v_lshlrev_b64 v[38:39], 14, v[38:39]
	v_lshlrev_b64 v[40:41], 14, v[40:41]
	v_lshlrev_b64 v[42:43], 14, v[42:43]
	v_lshlrev_b64 v[44:45], 14, v[44:45]
	v_lshlrev_b64 v[46:47], 14, v[46:47]
	v_lshlrev_b64 v[48:49], 14, v[48:49]
	v_lshlrev_b64 v[50:51], 14, v[50:51]
	v_ashrrev_i32_e32 v19, 31, v18
	v_lshl_add_u64 v[76:77], v[20:21], 0, v[16:17]
	v_lshl_add_u64 v[78:79], v[20:21], 0, v[22:23]
	v_add_u32_e32 v82, 8, v18
	v_add_u32_e32 v84, 16, v18
	v_add_u32_e32 v86, 24, v18
	v_add_u32_e32 v88, 32, v18
	v_add_u32_e32 v90, 40, v18
	v_add_u32_e32 v92, 48, v18
	v_add_u32_e32 v94, 56, v18
	v_lshl_add_u64 v[96:97], v[20:21], 0, v[24:25]
	v_lshl_add_u64 v[98:99], v[20:21], 0, v[26:27]
	v_lshl_add_u64 v[100:101], v[20:21], 0, v[28:29]
	v_lshl_add_u64 v[102:103], v[20:21], 0, v[30:31]
	v_lshl_add_u64 v[104:105], v[20:21], 0, v[32:33]
	v_lshl_add_u64 v[106:107], v[20:21], 0, v[34:35]
	v_lshl_add_u64 v[108:109], v[20:21], 0, v[36:37]
	v_lshl_add_u64 v[110:111], v[20:21], 0, v[38:39]
	v_lshl_add_u64 v[112:113], v[20:21], 0, v[40:41]
	v_lshl_add_u64 v[114:115], v[20:21], 0, v[42:43]
	v_lshl_add_u64 v[116:117], v[20:21], 0, v[44:45]
	v_lshl_add_u64 v[118:119], v[20:21], 0, v[46:47]
	v_lshl_add_u64 v[120:121], v[20:21], 0, v[48:49]
	v_lshl_add_u64 v[122:123], v[20:21], 0, v[50:51]
	v_lshlrev_b64 v[124:125], 12, v[18:19]
	global_load_dwordx4 v[16:19], v[76:77], off nt
	global_load_dwordx4 v[20:23], v[78:79], off nt
	global_load_dwordx4 v[24:27], v[96:97], off nt
	global_load_dwordx4 v[28:31], v[98:99], off nt
	global_load_dwordx4 v[32:35], v[100:101], off nt
	global_load_dwordx4 v[36:39], v[102:103], off nt
	global_load_dwordx4 v[40:43], v[104:105], off nt
	global_load_dwordx4 v[44:47], v[106:107], off nt
	global_load_dwordx4 v[48:51], v[108:109], off nt
	global_load_dwordx4 v[52:55], v[110:111], off nt
	global_load_dwordx4 v[56:59], v[112:113], off nt
	global_load_dwordx4 v[60:63], v[114:115], off nt
	global_load_dwordx4 v[64:67], v[116:117], off nt
	global_load_dwordx4 v[68:71], v[118:119], off nt
	global_load_dwordx4 v[72:75], v[120:121], off nt
	global_load_dwordx4 v[76:79], v[122:123], off nt
	v_ashrrev_i32_e32 v83, 31, v82
	v_ashrrev_i32_e32 v85, 31, v84
	v_ashrrev_i32_e32 v87, 31, v86
	v_ashrrev_i32_e32 v89, 31, v88
	v_ashrrev_i32_e32 v91, 31, v90
	v_ashrrev_i32_e32 v93, 31, v92
	v_ashrrev_i32_e32 v95, 31, v94
	v_lshl_add_u64 v[96:97], v[80:81], 0, v[124:125]
	v_lshlrev_b64 v[82:83], 12, v[82:83]
	v_lshlrev_b64 v[84:85], 12, v[84:85]
	v_lshlrev_b64 v[86:87], 12, v[86:87]
	v_lshlrev_b64 v[88:89], 12, v[88:89]
	v_lshlrev_b64 v[90:91], 12, v[90:91]
	v_lshlrev_b64 v[92:93], 12, v[92:93]
	v_lshlrev_b64 v[94:95], 12, v[94:95]
	v_lshl_add_u64 v[82:83], v[80:81], 0, v[82:83]
	v_lshl_add_u64 v[84:85], v[80:81], 0, v[84:85]
	v_lshl_add_u64 v[86:87], v[80:81], 0, v[86:87]
	v_lshl_add_u64 v[88:89], v[80:81], 0, v[88:89]
	v_lshl_add_u64 v[90:91], v[80:81], 0, v[90:91]
	v_lshl_add_u64 v[92:93], v[80:81], 0, v[92:93]
	v_lshl_add_u64 v[80:81], v[80:81], 0, v[94:95]
	v_add_u32_e32 v1, s94, v1
	v_cmp_lt_i32_e32 vcc, s5, v1
	s_or_b64 s[6:7], vcc, s[6:7]
	v_add_u32_e32 v9, s4, v9
	s_waitcnt vmcnt(15)
	v_cvt_pk_bf16_f32 v15, v16, s0
	v_cvt_pk_bf16_f32 v16, v17, s0
	v_cvt_pk_bf16_f32 v17, v18, s0
	v_cvt_pk_bf16_f32 v18, v19, s0
	s_waitcnt vmcnt(14)
	v_cvt_pk_bf16_f32 v19, v20, s0
	v_cvt_pk_bf16_f32 v20, v21, s0
	v_cvt_pk_bf16_f32 v21, v22, s0
	v_cvt_pk_bf16_f32 v22, v23, s0
	s_waitcnt vmcnt(13)
	v_cvt_pk_bf16_f32 v23, v24, s0
	v_cvt_pk_bf16_f32 v24, v25, s0
	v_cvt_pk_bf16_f32 v25, v26, s0
	v_cvt_pk_bf16_f32 v26, v27, s0
	s_waitcnt vmcnt(12)
	v_cvt_pk_bf16_f32 v27, v28, s0
	v_cvt_pk_bf16_f32 v28, v29, s0
	v_cvt_pk_bf16_f32 v29, v30, s0
	v_cvt_pk_bf16_f32 v30, v31, s0
	s_waitcnt vmcnt(11)
	v_cvt_pk_bf16_f32 v31, v32, s0
	v_cvt_pk_bf16_f32 v32, v33, s0
	v_cvt_pk_bf16_f32 v33, v34, s0
	v_cvt_pk_bf16_f32 v34, v35, s0
	s_waitcnt vmcnt(10)
	v_cvt_pk_bf16_f32 v35, v36, s0
	v_cvt_pk_bf16_f32 v36, v37, s0
	v_cvt_pk_bf16_f32 v37, v38, s0
	v_cvt_pk_bf16_f32 v38, v39, s0
	s_waitcnt vmcnt(9)
	v_cvt_pk_bf16_f32 v39, v40, s0
	v_cvt_pk_bf16_f32 v40, v41, s0
	v_cvt_pk_bf16_f32 v41, v42, s0
	v_cvt_pk_bf16_f32 v42, v43, s0
	s_waitcnt vmcnt(8)
	v_cvt_pk_bf16_f32 v43, v44, s0
	v_cvt_pk_bf16_f32 v44, v45, s0
	v_cvt_pk_bf16_f32 v45, v46, s0
	v_cvt_pk_bf16_f32 v46, v47, s0
	s_waitcnt vmcnt(7)
	v_cvt_pk_bf16_f32 v47, v48, s0
	v_cvt_pk_bf16_f32 v48, v49, s0
	v_cvt_pk_bf16_f32 v49, v50, s0
	v_cvt_pk_bf16_f32 v50, v51, s0
	s_waitcnt vmcnt(6)
	v_cvt_pk_bf16_f32 v51, v52, s0
	v_cvt_pk_bf16_f32 v52, v53, s0
	v_cvt_pk_bf16_f32 v53, v54, s0
	v_cvt_pk_bf16_f32 v54, v55, s0
	s_waitcnt vmcnt(5)
	v_cvt_pk_bf16_f32 v55, v56, s0
	v_cvt_pk_bf16_f32 v56, v57, s0
	v_cvt_pk_bf16_f32 v57, v58, s0
	v_cvt_pk_bf16_f32 v58, v59, s0
	s_waitcnt vmcnt(4)
	v_cvt_pk_bf16_f32 v59, v60, s0
	v_cvt_pk_bf16_f32 v60, v61, s0
	v_cvt_pk_bf16_f32 v61, v62, s0
	v_cvt_pk_bf16_f32 v62, v63, s0
	s_waitcnt vmcnt(3)
	v_cvt_pk_bf16_f32 v63, v64, s0
	v_cvt_pk_bf16_f32 v64, v65, s0
	v_cvt_pk_bf16_f32 v65, v66, s0
	v_cvt_pk_bf16_f32 v66, v67, s0
	s_waitcnt vmcnt(2)
	v_cvt_pk_bf16_f32 v67, v68, s0
	v_cvt_pk_bf16_f32 v68, v69, s0
	v_cvt_pk_bf16_f32 v69, v70, s0
	v_cvt_pk_bf16_f32 v70, v71, s0
	s_waitcnt vmcnt(1)
	v_cvt_pk_bf16_f32 v71, v72, s0
	v_cvt_pk_bf16_f32 v72, v73, s0
	v_cvt_pk_bf16_f32 v73, v74, s0
	v_cvt_pk_bf16_f32 v74, v75, s0
	s_waitcnt vmcnt(0)
	v_cvt_pk_bf16_f32 v75, v76, s0
	v_cvt_pk_bf16_f32 v76, v77, s0
	v_cvt_pk_bf16_f32 v77, v78, s0
	v_cvt_pk_bf16_f32 v78, v79, s0
	ds_write_b16 v8, v15
	ds_write_b16 v8, v16 offset:144
	ds_write_b16 v8, v17 offset:288
	ds_write_b16 v8, v18 offset:432
	ds_write_b16 v8, v19 offset:8
	ds_write_b16 v8, v20 offset:152
	ds_write_b16 v8, v21 offset:296
	ds_write_b16 v8, v22 offset:440
	ds_write_b16 v8, v23 offset:16
	ds_write_b16 v8, v24 offset:160
	ds_write_b16 v8, v25 offset:304
	ds_write_b16 v8, v26 offset:448
	ds_write_b16 v8, v27 offset:24
	ds_write_b16 v8, v28 offset:168
	ds_write_b16 v8, v29 offset:312
	ds_write_b16 v8, v30 offset:456
	ds_write_b16 v8, v31 offset:32
	ds_write_b16 v8, v32 offset:176
	ds_write_b16 v8, v33 offset:320
	ds_write_b16 v8, v34 offset:464
	ds_write_b16 v8, v35 offset:40
	ds_write_b16 v8, v36 offset:184
	ds_write_b16 v8, v37 offset:328
	ds_write_b16 v8, v38 offset:472
	ds_write_b16 v8, v39 offset:48
	ds_write_b16 v8, v40 offset:192
	ds_write_b16 v8, v41 offset:336
	ds_write_b16 v8, v42 offset:480
	ds_write_b16 v8, v43 offset:56
	ds_write_b16 v8, v44 offset:200
	ds_write_b16 v8, v45 offset:344
	ds_write_b16 v8, v46 offset:488
	ds_write_b16 v8, v47 offset:64
	ds_write_b16 v8, v48 offset:208
	ds_write_b16 v8, v49 offset:352
	ds_write_b16 v8, v50 offset:496
	ds_write_b16 v8, v51 offset:72
	ds_write_b16 v8, v52 offset:216
	ds_write_b16 v8, v53 offset:360
	ds_write_b16 v8, v54 offset:504
	ds_write_b16 v8, v55 offset:80
	ds_write_b16 v8, v56 offset:224
	ds_write_b16 v8, v57 offset:368
	ds_write_b16 v8, v58 offset:512
	ds_write_b16 v8, v59 offset:88
	ds_write_b16 v8, v60 offset:232
	ds_write_b16 v8, v61 offset:376
	ds_write_b16 v8, v62 offset:520
	ds_write_b16 v8, v63 offset:96
	ds_write_b16 v8, v64 offset:240
	ds_write_b16 v8, v65 offset:384
	ds_write_b16 v8, v66 offset:528
	ds_write_b16 v8, v67 offset:104
	ds_write_b16 v8, v68 offset:248
	ds_write_b16 v8, v69 offset:392
	ds_write_b16 v8, v70 offset:536
	ds_write_b16 v8, v71 offset:112
	ds_write_b16 v8, v72 offset:256
	ds_write_b16 v8, v73 offset:400
	ds_write_b16 v8, v74 offset:544
	ds_write_b16 v8, v75 offset:120
	ds_write_b16 v8, v76 offset:264
	ds_write_b16 v8, v77 offset:408
	ds_write_b16 v8, v78 offset:552
	s_waitcnt lgkmcnt(0)
	ds_read_b128 v[16:19], v13
	ds_read_b128 v[20:23], v14
	ds_read_b128 v[24:27], v14 offset:1152
	ds_read_b128 v[28:31], v14 offset:2304
	ds_read_b128 v[32:35], v14 offset:3456
	ds_read_b128 v[36:39], v14 offset:4608
	ds_read_b128 v[40:43], v14 offset:5760
	ds_read_b128 v[44:47], v14 offset:6912
	s_waitcnt lgkmcnt(7)
	global_store_dwordx4 v[96:97], v[16:19], off
	s_waitcnt lgkmcnt(6)
	global_store_dwordx4 v[82:83], v[20:23], off
	s_waitcnt lgkmcnt(5)
	global_store_dwordx4 v[84:85], v[24:27], off
	s_waitcnt lgkmcnt(4)
	global_store_dwordx4 v[86:87], v[28:31], off
	s_waitcnt lgkmcnt(3)
	global_store_dwordx4 v[88:89], v[32:35], off
	s_waitcnt lgkmcnt(2)
	global_store_dwordx4 v[90:91], v[36:39], off
	s_waitcnt lgkmcnt(1)
	global_store_dwordx4 v[92:93], v[40:43], off
	s_waitcnt lgkmcnt(0)
	global_store_dwordx4 v[80:81], v[44:47], off
	s_waitcnt lgkmcnt(0)
	s_andn2_b64 exec, exec, s[6:7]
	s_cbranch_execnz .LBB0_8

.LBB0_11:
	v_mul_hi_i32 v15, v1, s5
	v_lshrrev_b32_e32 v16, 31, v15
	v_ashrrev_i32_e32 v15, 4, v15
	v_add_u32_e32 v15, v15, v16
	v_lshlrev_b32_e32 v16, 6, v15
	v_mad_u64_u32 v[18:19], s[12:13], v15, s8, v[6:7]
	v_or_b32_e32 v15, v16, v7
	v_ashrrev_i32_e32 v19, 31, v18
	v_add_u32_e32 v20, v18, v8
	v_lshl_add_u64 v[18:19], v[18:19], 2, v[2:3]
	v_or_b32_e32 v22, 4, v15
	v_ashrrev_i32_e32 v17, 31, v16
	v_or_b32_e32 v23, 8, v15
	v_or_b32_e32 v24, 12, v15
	v_or_b32_e32 v25, 16, v15
	v_or_b32_e32 v26, 20, v15
	v_or_b32_e32 v27, 24, v15
	v_or_b32_e32 v28, 28, v15
	v_or_b32_e32 v29, 32, v15
	v_or_b32_e32 v30, 36, v15
	v_or_b32_e32 v31, 40, v15
	v_or_b32_e32 v32, 44, v15
	v_or_b32_e32 v33, 48, v15
	v_or_b32_e32 v34, 52, v15
	v_or_b32_e32 v35, 56, v15
	v_or_b32_e32 v36, 60, v15
	v_ashrrev_i32_e32 v21, 31, v20
	v_mad_i64_i32 v[76:77], s[12:13], v15, s9, v[18:19]
	v_mad_i64_i32 v[78:79], s[12:13], v22, s9, v[18:19]
	v_lshl_add_u64 v[80:81], v[16:17], 1, v[4:5]
	v_add_u32_e32 v82, 8, v20
	v_add_u32_e32 v84, 16, v20
	v_add_u32_e32 v86, 24, v20
	v_add_u32_e32 v88, 32, v20
	v_add_u32_e32 v90, 40, v20
	v_add_u32_e32 v92, 48, v20
	v_add_u32_e32 v94, 56, v20
	v_mad_i64_i32 v[96:97], s[12:13], v23, s9, v[18:19]
	v_mad_i64_i32 v[98:99], s[12:13], v24, s9, v[18:19]
	v_mad_i64_i32 v[100:101], s[12:13], v25, s9, v[18:19]
	v_mad_i64_i32 v[102:103], s[12:13], v26, s9, v[18:19]
	v_mad_i64_i32 v[104:105], s[12:13], v27, s9, v[18:19]
	v_mad_i64_i32 v[106:107], s[12:13], v28, s9, v[18:19]
	v_mad_i64_i32 v[108:109], s[12:13], v29, s9, v[18:19]
	v_mad_i64_i32 v[110:111], s[12:13], v30, s9, v[18:19]
	v_mad_i64_i32 v[112:113], s[12:13], v31, s9, v[18:19]
	v_mad_i64_i32 v[114:115], s[12:13], v32, s9, v[18:19]
	v_mad_i64_i32 v[116:117], s[12:13], v33, s9, v[18:19]
	v_mad_i64_i32 v[118:119], s[12:13], v34, s9, v[18:19]
	v_mad_i64_i32 v[120:121], s[12:13], v35, s9, v[18:19]
	v_mad_i64_i32 v[122:123], s[12:13], v36, s9, v[18:19]
	v_lshlrev_b64 v[124:125], 12, v[20:21]
	global_load_dwordx4 v[16:19], v[76:77], off nt
	global_load_dwordx4 v[20:23], v[78:79], off nt
	global_load_dwordx4 v[24:27], v[96:97], off nt
	global_load_dwordx4 v[28:31], v[98:99], off nt
	global_load_dwordx4 v[32:35], v[100:101], off nt
	global_load_dwordx4 v[36:39], v[102:103], off nt
	global_load_dwordx4 v[40:43], v[104:105], off nt
	global_load_dwordx4 v[44:47], v[106:107], off nt
	global_load_dwordx4 v[48:51], v[108:109], off nt
	global_load_dwordx4 v[52:55], v[110:111], off nt
	global_load_dwordx4 v[56:59], v[112:113], off nt
	global_load_dwordx4 v[60:63], v[114:115], off nt
	global_load_dwordx4 v[64:67], v[116:117], off nt
	global_load_dwordx4 v[68:71], v[118:119], off nt
	global_load_dwordx4 v[72:75], v[120:121], off nt
	global_load_dwordx4 v[76:79], v[122:123], off nt
	v_ashrrev_i32_e32 v83, 31, v82
	v_ashrrev_i32_e32 v85, 31, v84
	v_ashrrev_i32_e32 v87, 31, v86
	v_ashrrev_i32_e32 v89, 31, v88
	v_ashrrev_i32_e32 v91, 31, v90
	v_ashrrev_i32_e32 v93, 31, v92
	v_ashrrev_i32_e32 v95, 31, v94
	v_lshl_add_u64 v[96:97], v[80:81], 0, v[124:125]
	v_lshlrev_b64 v[82:83], 12, v[82:83]
	v_lshlrev_b64 v[84:85], 12, v[84:85]
	v_lshlrev_b64 v[86:87], 12, v[86:87]
	v_lshlrev_b64 v[88:89], 12, v[88:89]
	v_lshlrev_b64 v[90:91], 12, v[90:91]
	v_lshlrev_b64 v[92:93], 12, v[92:93]
	v_lshlrev_b64 v[94:95], 12, v[94:95]
	v_lshl_add_u64 v[82:83], v[80:81], 0, v[82:83]
	v_lshl_add_u64 v[84:85], v[80:81], 0, v[84:85]
	v_lshl_add_u64 v[86:87], v[80:81], 0, v[86:87]
	v_lshl_add_u64 v[88:89], v[80:81], 0, v[88:89]
	v_lshl_add_u64 v[90:91], v[80:81], 0, v[90:91]
	v_lshl_add_u64 v[92:93], v[80:81], 0, v[92:93]
	v_lshl_add_u64 v[80:81], v[80:81], 0, v[94:95]
	v_add_u32_e32 v1, s94, v1
	v_cmp_lt_i32_e32 vcc, s10, v1
	s_or_b64 s[6:7], vcc, s[6:7]
	v_add_u32_e32 v6, s4, v6
	s_waitcnt vmcnt(15)
	v_cvt_pk_bf16_f32 v15, v16, s0
	v_cvt_pk_bf16_f32 v16, v17, s0
	v_cvt_pk_bf16_f32 v17, v18, s0
	v_cvt_pk_bf16_f32 v18, v19, s0
	s_waitcnt vmcnt(14)
	v_cvt_pk_bf16_f32 v19, v20, s0
	v_cvt_pk_bf16_f32 v20, v21, s0
	v_cvt_pk_bf16_f32 v21, v22, s0
	v_cvt_pk_bf16_f32 v22, v23, s0
	s_waitcnt vmcnt(13)
	v_cvt_pk_bf16_f32 v23, v24, s0
	v_cvt_pk_bf16_f32 v24, v25, s0
	v_cvt_pk_bf16_f32 v25, v26, s0
	v_cvt_pk_bf16_f32 v26, v27, s0
	s_waitcnt vmcnt(12)
	v_cvt_pk_bf16_f32 v27, v28, s0
	v_cvt_pk_bf16_f32 v28, v29, s0
	v_cvt_pk_bf16_f32 v29, v30, s0
	v_cvt_pk_bf16_f32 v30, v31, s0
	s_waitcnt vmcnt(11)
	v_cvt_pk_bf16_f32 v31, v32, s0
	v_cvt_pk_bf16_f32 v32, v33, s0
	v_cvt_pk_bf16_f32 v33, v34, s0
	v_cvt_pk_bf16_f32 v34, v35, s0
	s_waitcnt vmcnt(10)
	v_cvt_pk_bf16_f32 v35, v36, s0
	v_cvt_pk_bf16_f32 v36, v37, s0
	v_cvt_pk_bf16_f32 v37, v38, s0
	v_cvt_pk_bf16_f32 v38, v39, s0
	s_waitcnt vmcnt(9)
	v_cvt_pk_bf16_f32 v39, v40, s0
	v_cvt_pk_bf16_f32 v40, v41, s0
	v_cvt_pk_bf16_f32 v41, v42, s0
	v_cvt_pk_bf16_f32 v42, v43, s0
	s_waitcnt vmcnt(8)
	v_cvt_pk_bf16_f32 v43, v44, s0
	v_cvt_pk_bf16_f32 v44, v45, s0
	v_cvt_pk_bf16_f32 v45, v46, s0
	v_cvt_pk_bf16_f32 v46, v47, s0
	s_waitcnt vmcnt(7)
	v_cvt_pk_bf16_f32 v47, v48, s0
	v_cvt_pk_bf16_f32 v48, v49, s0
	v_cvt_pk_bf16_f32 v49, v50, s0
	v_cvt_pk_bf16_f32 v50, v51, s0
	s_waitcnt vmcnt(6)
	v_cvt_pk_bf16_f32 v51, v52, s0
	v_cvt_pk_bf16_f32 v52, v53, s0
	v_cvt_pk_bf16_f32 v53, v54, s0
	v_cvt_pk_bf16_f32 v54, v55, s0
	s_waitcnt vmcnt(5)
	v_cvt_pk_bf16_f32 v55, v56, s0
	v_cvt_pk_bf16_f32 v56, v57, s0
	v_cvt_pk_bf16_f32 v57, v58, s0
	v_cvt_pk_bf16_f32 v58, v59, s0
	s_waitcnt vmcnt(4)
	v_cvt_pk_bf16_f32 v59, v60, s0
	v_cvt_pk_bf16_f32 v60, v61, s0
	v_cvt_pk_bf16_f32 v61, v62, s0
	v_cvt_pk_bf16_f32 v62, v63, s0
	s_waitcnt vmcnt(3)
	v_cvt_pk_bf16_f32 v63, v64, s0
	v_cvt_pk_bf16_f32 v64, v65, s0
	v_cvt_pk_bf16_f32 v65, v66, s0
	v_cvt_pk_bf16_f32 v66, v67, s0
	s_waitcnt vmcnt(2)
	v_cvt_pk_bf16_f32 v67, v68, s0
	v_cvt_pk_bf16_f32 v68, v69, s0
	v_cvt_pk_bf16_f32 v69, v70, s0
	v_cvt_pk_bf16_f32 v70, v71, s0
	s_waitcnt vmcnt(1)
	v_cvt_pk_bf16_f32 v71, v72, s0
	v_cvt_pk_bf16_f32 v72, v73, s0
	v_cvt_pk_bf16_f32 v73, v74, s0
	v_cvt_pk_bf16_f32 v74, v75, s0
	s_waitcnt vmcnt(0)
	v_cvt_pk_bf16_f32 v75, v76, s0
	v_cvt_pk_bf16_f32 v76, v77, s0
	v_cvt_pk_bf16_f32 v77, v78, s0
	v_cvt_pk_bf16_f32 v78, v79, s0
	ds_write_b16 v9, v15
	ds_write_b16 v9, v16 offset:144
	ds_write_b16 v9, v17 offset:288
	ds_write_b16 v9, v18 offset:432
	ds_write_b16 v9, v19 offset:8
	ds_write_b16 v9, v20 offset:152
	ds_write_b16 v9, v21 offset:296
	ds_write_b16 v9, v22 offset:440
	ds_write_b16 v9, v23 offset:16
	ds_write_b16 v9, v24 offset:160
	ds_write_b16 v9, v25 offset:304
	ds_write_b16 v9, v26 offset:448
	ds_write_b16 v9, v27 offset:24
	ds_write_b16 v9, v28 offset:168
	ds_write_b16 v9, v29 offset:312
	ds_write_b16 v9, v30 offset:456
	ds_write_b16 v9, v31 offset:32
	ds_write_b16 v9, v32 offset:176
	ds_write_b16 v9, v33 offset:320
	ds_write_b16 v9, v34 offset:464
	ds_write_b16 v9, v35 offset:40
	ds_write_b16 v9, v36 offset:184
	ds_write_b16 v9, v37 offset:328
	ds_write_b16 v9, v38 offset:472
	ds_write_b16 v9, v39 offset:48
	ds_write_b16 v9, v40 offset:192
	ds_write_b16 v9, v41 offset:336
	ds_write_b16 v9, v42 offset:480
	ds_write_b16 v9, v43 offset:56
	ds_write_b16 v9, v44 offset:200
	ds_write_b16 v9, v45 offset:344
	ds_write_b16 v9, v46 offset:488
	ds_write_b16 v9, v47 offset:64
	ds_write_b16 v9, v48 offset:208
	ds_write_b16 v9, v49 offset:352
	ds_write_b16 v9, v50 offset:496
	ds_write_b16 v9, v51 offset:72
	ds_write_b16 v9, v52 offset:216
	ds_write_b16 v9, v53 offset:360
	ds_write_b16 v9, v54 offset:504
	ds_write_b16 v9, v55 offset:80
	ds_write_b16 v9, v56 offset:224
	ds_write_b16 v9, v57 offset:368
	ds_write_b16 v9, v58 offset:512
	ds_write_b16 v9, v59 offset:88
	ds_write_b16 v9, v60 offset:232
	ds_write_b16 v9, v61 offset:376
	ds_write_b16 v9, v62 offset:520
	ds_write_b16 v9, v63 offset:96
	ds_write_b16 v9, v64 offset:240
	ds_write_b16 v9, v65 offset:384
	ds_write_b16 v9, v66 offset:528
	ds_write_b16 v9, v67 offset:104
	ds_write_b16 v9, v68 offset:248
	ds_write_b16 v9, v69 offset:392
	ds_write_b16 v9, v70 offset:536
	ds_write_b16 v9, v71 offset:112
	ds_write_b16 v9, v72 offset:256
	ds_write_b16 v9, v73 offset:400
	ds_write_b16 v9, v74 offset:544
	ds_write_b16 v9, v75 offset:120
	ds_write_b16 v9, v76 offset:264
	ds_write_b16 v9, v77 offset:408
	ds_write_b16 v9, v78 offset:552
	s_waitcnt lgkmcnt(0)
	ds_read_b128 v[16:19], v13
	ds_read_b128 v[20:23], v14
	ds_read_b128 v[24:27], v14 offset:1152
	ds_read_b128 v[28:31], v14 offset:2304
	ds_read_b128 v[32:35], v14 offset:3456
	ds_read_b128 v[36:39], v14 offset:4608
	ds_read_b128 v[40:43], v14 offset:5760
	ds_read_b128 v[44:47], v14 offset:6912
	s_waitcnt lgkmcnt(7)
	global_store_dwordx4 v[96:97], v[16:19], off
	s_waitcnt lgkmcnt(6)
	global_store_dwordx4 v[82:83], v[20:23], off
	s_waitcnt lgkmcnt(5)
	global_store_dwordx4 v[84:85], v[24:27], off
	s_waitcnt lgkmcnt(4)
	global_store_dwordx4 v[86:87], v[28:31], off
	s_waitcnt lgkmcnt(3)
	global_store_dwordx4 v[88:89], v[32:35], off
	s_waitcnt lgkmcnt(2)
	global_store_dwordx4 v[90:91], v[36:39], off
	s_waitcnt lgkmcnt(1)
	global_store_dwordx4 v[92:93], v[40:43], off
	s_waitcnt lgkmcnt(0)
	global_store_dwordx4 v[80:81], v[44:47], off
	s_waitcnt lgkmcnt(0)
	s_andn2_b64 exec, exec, s[6:7]
	s_cbranch_execnz .LBB0_11

.LBB0_14:
	v_ashrrev_i32_e32 v15, 31, v1
	v_lshrrev_b32_e32 v15, 27, v15
	v_add_u32_e32 v15, v1, v15
	v_ashrrev_i32_e32 v15, 5, v15
	v_lshlrev_b32_e32 v16, 6, v15
	v_lshlrev_b32_e32 v15, 11, v15
	v_sub_u32_e32 v18, v9, v15
	v_or_b32_e32 v20, v16, v6
	v_ashrrev_i32_e32 v17, 31, v16
	v_ashrrev_i32_e32 v19, 31, v18
	v_ashrrev_i32_e32 v21, 31, v20
	v_or_b32_e32 v22, 4, v20
	v_lshl_add_u64 v[80:81], v[16:17], 1, v[4:5]
	v_add_u32_e32 v16, v18, v7
	v_lshl_add_u64 v[52:53], v[18:19], 2, v[2:3]
	v_lshlrev_b64 v[18:19], 13, v[20:21]
	v_or_b32_e32 v24, 8, v20
	v_or_b32_e32 v26, 12, v20
	v_or_b32_e32 v28, 16, v20
	v_or_b32_e32 v30, 20, v20
	v_or_b32_e32 v32, 24, v20
	v_or_b32_e32 v34, 28, v20
	v_or_b32_e32 v36, 32, v20
	v_or_b32_e32 v38, 36, v20
	v_or_b32_e32 v40, 40, v20
	v_or_b32_e32 v42, 44, v20
	v_or_b32_e32 v44, 48, v20
	v_or_b32_e32 v46, 52, v20
	v_or_b32_e32 v48, 56, v20
	v_or_b32_e32 v50, 60, v20
	v_ashrrev_i32_e32 v23, 31, v22
	v_ashrrev_i32_e32 v17, 31, v16
	v_lshl_add_u64 v[18:19], v[52:53], 0, v[18:19]
	v_ashrrev_i32_e32 v25, 31, v24
	v_ashrrev_i32_e32 v27, 31, v26
	v_ashrrev_i32_e32 v29, 31, v28
	v_ashrrev_i32_e32 v31, 31, v30
	v_ashrrev_i32_e32 v33, 31, v32
	v_ashrrev_i32_e32 v35, 31, v34
	v_ashrrev_i32_e32 v37, 31, v36
	v_ashrrev_i32_e32 v39, 31, v38
	v_ashrrev_i32_e32 v41, 31, v40
	v_ashrrev_i32_e32 v43, 31, v42
	v_ashrrev_i32_e32 v45, 31, v44
	v_ashrrev_i32_e32 v47, 31, v46
	v_ashrrev_i32_e32 v49, 31, v48
	v_ashrrev_i32_e32 v51, 31, v50
	v_add_u32_e32 v20, 8, v16
	v_add_u32_e32 v54, 16, v16
	v_add_u32_e32 v56, 24, v16
	v_add_u32_e32 v58, 32, v16
	v_add_u32_e32 v60, 40, v16
	v_add_u32_e32 v62, 48, v16
	v_add_u32_e32 v64, 56, v16
	v_lshlrev_b64 v[22:23], 13, v[22:23]
	v_lshlrev_b64 v[66:67], 12, v[16:17]
	global_load_dwordx4 v[16:19], v[18:19], off nt
	v_lshlrev_b64 v[24:25], 13, v[24:25]
	v_lshlrev_b64 v[26:27], 13, v[26:27]
	v_lshlrev_b64 v[28:29], 13, v[28:29]
	v_lshlrev_b64 v[30:31], 13, v[30:31]
	v_lshlrev_b64 v[32:33], 13, v[32:33]
	v_lshlrev_b64 v[34:35], 13, v[34:35]
	v_lshlrev_b64 v[36:37], 13, v[36:37]
	v_lshlrev_b64 v[38:39], 13, v[38:39]
	v_lshlrev_b64 v[40:41], 13, v[40:41]
	v_lshlrev_b64 v[42:43], 13, v[42:43]
	v_lshlrev_b64 v[44:45], 13, v[44:45]
	v_lshlrev_b64 v[46:47], 13, v[46:47]
	v_lshlrev_b64 v[48:49], 13, v[48:49]
	v_lshlrev_b64 v[50:51], 13, v[50:51]
	v_ashrrev_i32_e32 v21, 31, v20
	v_ashrrev_i32_e32 v55, 31, v54
	v_ashrrev_i32_e32 v57, 31, v56
	v_ashrrev_i32_e32 v59, 31, v58
	v_ashrrev_i32_e32 v61, 31, v60
	v_ashrrev_i32_e32 v63, 31, v62
	v_ashrrev_i32_e32 v65, 31, v64
	v_lshl_add_u64 v[82:83], v[52:53], 0, v[22:23]
	v_lshl_add_u64 v[84:85], v[52:53], 0, v[24:25]
	v_lshl_add_u64 v[86:87], v[52:53], 0, v[26:27]
	v_lshl_add_u64 v[88:89], v[52:53], 0, v[28:29]
	v_lshl_add_u64 v[90:91], v[52:53], 0, v[30:31]
	v_lshl_add_u64 v[92:93], v[52:53], 0, v[32:33]
	v_lshl_add_u64 v[94:95], v[52:53], 0, v[34:35]
	v_lshl_add_u64 v[96:97], v[52:53], 0, v[36:37]
	v_lshl_add_u64 v[98:99], v[52:53], 0, v[38:39]
	v_lshl_add_u64 v[100:101], v[52:53], 0, v[40:41]
	v_lshl_add_u64 v[102:103], v[52:53], 0, v[42:43]
	v_lshl_add_u64 v[104:105], v[52:53], 0, v[44:45]
	v_lshl_add_u64 v[106:107], v[52:53], 0, v[46:47]
	v_lshl_add_u64 v[108:109], v[52:53], 0, v[48:49]
	v_lshl_add_u64 v[110:111], v[52:53], 0, v[50:51]
	v_lshl_add_u64 v[112:113], v[80:81], 0, v[66:67]
	v_lshlrev_b64 v[114:115], 12, v[20:21]
	v_lshlrev_b64 v[116:117], 12, v[54:55]
	v_lshlrev_b64 v[118:119], 12, v[56:57]
	v_lshlrev_b64 v[120:121], 12, v[58:59]
	v_lshlrev_b64 v[122:123], 12, v[60:61]
	v_lshlrev_b64 v[124:125], 12, v[62:63]
	v_lshlrev_b64 v[126:127], 12, v[64:65]
	global_load_dwordx4 v[20:23], v[82:83], off nt
	global_load_dwordx4 v[24:27], v[84:85], off nt
	global_load_dwordx4 v[28:31], v[86:87], off nt
	global_load_dwordx4 v[32:35], v[88:89], off nt
	global_load_dwordx4 v[36:39], v[90:91], off nt
	global_load_dwordx4 v[40:43], v[92:93], off nt
	global_load_dwordx4 v[44:47], v[94:95], off nt
	global_load_dwordx4 v[48:51], v[96:97], off nt
	global_load_dwordx4 v[52:55], v[98:99], off nt
	global_load_dwordx4 v[56:59], v[100:101], off nt
	global_load_dwordx4 v[60:63], v[102:103], off nt
	global_load_dwordx4 v[64:67], v[104:105], off nt
	global_load_dwordx4 v[68:71], v[106:107], off nt
	global_load_dwordx4 v[72:75], v[108:109], off nt
	global_load_dwordx4 v[76:79], v[110:111], off nt
	v_lshl_add_u64 v[82:83], v[80:81], 0, v[114:115]
	v_lshl_add_u64 v[84:85], v[80:81], 0, v[116:117]
	v_lshl_add_u64 v[86:87], v[80:81], 0, v[118:119]
	v_lshl_add_u64 v[88:89], v[80:81], 0, v[120:121]
	v_lshl_add_u64 v[90:91], v[80:81], 0, v[122:123]
	v_lshl_add_u64 v[92:93], v[80:81], 0, v[124:125]
	v_lshl_add_u64 v[80:81], v[80:81], 0, v[126:127]
	v_add_u32_e32 v1, s94, v1
	v_cmp_lt_i32_e32 vcc, s5, v1
	s_or_b64 s[8:9], vcc, s[8:9]
	v_add_u32_e32 v9, s4, v9
	s_waitcnt vmcnt(15)
	v_cvt_pk_bf16_f32 v15, v16, s0
	v_cvt_pk_bf16_f32 v16, v17, s0
	v_cvt_pk_bf16_f32 v17, v18, s0
	v_cvt_pk_bf16_f32 v18, v19, s0
	ds_write_b16 v8, v15
	ds_write_b16 v8, v16 offset:144
	ds_write_b16 v8, v17 offset:288
	ds_write_b16 v8, v18 offset:432
	s_waitcnt vmcnt(14)
	v_cvt_pk_bf16_f32 v15, v20, s0
	v_cvt_pk_bf16_f32 v16, v21, s0
	v_cvt_pk_bf16_f32 v17, v22, s0
	v_cvt_pk_bf16_f32 v18, v23, s0
	s_waitcnt vmcnt(13)
	v_cvt_pk_bf16_f32 v19, v24, s0
	v_cvt_pk_bf16_f32 v20, v25, s0
	v_cvt_pk_bf16_f32 v21, v26, s0
	v_cvt_pk_bf16_f32 v22, v27, s0
	s_waitcnt vmcnt(12)
	v_cvt_pk_bf16_f32 v23, v28, s0
	v_cvt_pk_bf16_f32 v24, v29, s0
	v_cvt_pk_bf16_f32 v25, v30, s0
	v_cvt_pk_bf16_f32 v26, v31, s0
	s_waitcnt vmcnt(11)
	v_cvt_pk_bf16_f32 v27, v32, s0
	v_cvt_pk_bf16_f32 v28, v33, s0
	v_cvt_pk_bf16_f32 v29, v34, s0
	v_cvt_pk_bf16_f32 v30, v35, s0
	s_waitcnt vmcnt(10)
	v_cvt_pk_bf16_f32 v31, v36, s0
	v_cvt_pk_bf16_f32 v32, v37, s0
	v_cvt_pk_bf16_f32 v33, v38, s0
	v_cvt_pk_bf16_f32 v34, v39, s0
	s_waitcnt vmcnt(9)
	v_cvt_pk_bf16_f32 v35, v40, s0
	v_cvt_pk_bf16_f32 v36, v41, s0
	v_cvt_pk_bf16_f32 v37, v42, s0
	v_cvt_pk_bf16_f32 v38, v43, s0
	s_waitcnt vmcnt(8)
	v_cvt_pk_bf16_f32 v39, v44, s0
	v_cvt_pk_bf16_f32 v40, v45, s0
	v_cvt_pk_bf16_f32 v41, v46, s0
	v_cvt_pk_bf16_f32 v42, v47, s0
	s_waitcnt vmcnt(7)
	v_cvt_pk_bf16_f32 v43, v48, s0
	v_cvt_pk_bf16_f32 v44, v49, s0
	v_cvt_pk_bf16_f32 v45, v50, s0
	v_cvt_pk_bf16_f32 v46, v51, s0
	s_waitcnt vmcnt(6)
	v_cvt_pk_bf16_f32 v47, v52, s0
	v_cvt_pk_bf16_f32 v48, v53, s0
	v_cvt_pk_bf16_f32 v49, v54, s0
	v_cvt_pk_bf16_f32 v50, v55, s0
	s_waitcnt vmcnt(5)
	v_cvt_pk_bf16_f32 v51, v56, s0
	v_cvt_pk_bf16_f32 v52, v57, s0
	v_cvt_pk_bf16_f32 v53, v58, s0
	v_cvt_pk_bf16_f32 v54, v59, s0
	s_waitcnt vmcnt(4)
	v_cvt_pk_bf16_f32 v55, v60, s0
	v_cvt_pk_bf16_f32 v56, v61, s0
	v_cvt_pk_bf16_f32 v57, v62, s0
	v_cvt_pk_bf16_f32 v58, v63, s0
	s_waitcnt vmcnt(3)
	v_cvt_pk_bf16_f32 v59, v64, s0
	v_cvt_pk_bf16_f32 v60, v65, s0
	v_cvt_pk_bf16_f32 v61, v66, s0
	v_cvt_pk_bf16_f32 v62, v67, s0
	s_waitcnt vmcnt(2)
	v_cvt_pk_bf16_f32 v63, v68, s0
	v_cvt_pk_bf16_f32 v64, v69, s0
	v_cvt_pk_bf16_f32 v65, v70, s0
	v_cvt_pk_bf16_f32 v66, v71, s0
	s_waitcnt vmcnt(1)
	v_cvt_pk_bf16_f32 v67, v72, s0
	v_cvt_pk_bf16_f32 v68, v73, s0
	v_cvt_pk_bf16_f32 v69, v74, s0
	v_cvt_pk_bf16_f32 v70, v75, s0
	s_waitcnt vmcnt(0)
	v_cvt_pk_bf16_f32 v71, v76, s0
	v_cvt_pk_bf16_f32 v72, v77, s0
	v_cvt_pk_bf16_f32 v73, v78, s0
	v_cvt_pk_bf16_f32 v74, v79, s0
	ds_write_b16 v8, v15 offset:8
	ds_write_b16 v8, v16 offset:152
	ds_write_b16 v8, v17 offset:296
	ds_write_b16 v8, v18 offset:440
	ds_write_b16 v8, v19 offset:16
	ds_write_b16 v8, v20 offset:160
	ds_write_b16 v8, v21 offset:304
	ds_write_b16 v8, v22 offset:448
	ds_write_b16 v8, v23 offset:24
	ds_write_b16 v8, v24 offset:168
	ds_write_b16 v8, v25 offset:312
	ds_write_b16 v8, v26 offset:456
	ds_write_b16 v8, v27 offset:32
	ds_write_b16 v8, v28 offset:176
	ds_write_b16 v8, v29 offset:320
	ds_write_b16 v8, v30 offset:464
	ds_write_b16 v8, v31 offset:40
	ds_write_b16 v8, v32 offset:184
	ds_write_b16 v8, v33 offset:328
	ds_write_b16 v8, v34 offset:472
	ds_write_b16 v8, v35 offset:48
	ds_write_b16 v8, v36 offset:192
	ds_write_b16 v8, v37 offset:336
	ds_write_b16 v8, v38 offset:480
	ds_write_b16 v8, v39 offset:56
	ds_write_b16 v8, v40 offset:200
	ds_write_b16 v8, v41 offset:344
	ds_write_b16 v8, v42 offset:488
	ds_write_b16 v8, v43 offset:64
	ds_write_b16 v8, v44 offset:208
	ds_write_b16 v8, v45 offset:352
	ds_write_b16 v8, v46 offset:496
	ds_write_b16 v8, v47 offset:72
	ds_write_b16 v8, v48 offset:216
	ds_write_b16 v8, v49 offset:360
	ds_write_b16 v8, v50 offset:504
	ds_write_b16 v8, v51 offset:80
	ds_write_b16 v8, v52 offset:224
	ds_write_b16 v8, v53 offset:368
	ds_write_b16 v8, v54 offset:512
	ds_write_b16 v8, v55 offset:88
	ds_write_b16 v8, v56 offset:232
	ds_write_b16 v8, v57 offset:376
	ds_write_b16 v8, v58 offset:520
	ds_write_b16 v8, v59 offset:96
	ds_write_b16 v8, v60 offset:240
	ds_write_b16 v8, v61 offset:384
	ds_write_b16 v8, v62 offset:528
	ds_write_b16 v8, v63 offset:104
	ds_write_b16 v8, v64 offset:248
	ds_write_b16 v8, v65 offset:392
	ds_write_b16 v8, v66 offset:536
	ds_write_b16 v8, v67 offset:112
	ds_write_b16 v8, v68 offset:256
	ds_write_b16 v8, v69 offset:400
	ds_write_b16 v8, v70 offset:544
	ds_write_b16 v8, v71 offset:120
	ds_write_b16 v8, v72 offset:264
	ds_write_b16 v8, v73 offset:408
	ds_write_b16 v8, v74 offset:552
	s_waitcnt lgkmcnt(0)
	ds_read_b128 v[16:19], v13
	ds_read_b128 v[20:23], v14
	ds_read_b128 v[24:27], v14 offset:1152
	ds_read_b128 v[28:31], v14 offset:2304
	ds_read_b128 v[32:35], v14 offset:3456
	ds_read_b128 v[36:39], v14 offset:4608
	ds_read_b128 v[40:43], v14 offset:5760
	ds_read_b128 v[44:47], v14 offset:6912
	s_waitcnt lgkmcnt(7)
	global_store_dwordx4 v[112:113], v[16:19], off
	s_waitcnt lgkmcnt(6)
	global_store_dwordx4 v[82:83], v[20:23], off
	s_waitcnt lgkmcnt(5)
	global_store_dwordx4 v[84:85], v[24:27], off
	s_waitcnt lgkmcnt(4)
	global_store_dwordx4 v[86:87], v[28:31], off
	s_waitcnt lgkmcnt(3)
	global_store_dwordx4 v[88:89], v[32:35], off
	s_waitcnt lgkmcnt(2)
	global_store_dwordx4 v[90:91], v[36:39], off
	s_waitcnt lgkmcnt(1)
	global_store_dwordx4 v[92:93], v[40:43], off
	s_waitcnt lgkmcnt(0)
	global_store_dwordx4 v[80:81], v[44:47], off
	s_waitcnt lgkmcnt(0)
	s_andn2_b64 exec, exec, s[8:9]
	s_cbranch_execnz .LBB0_14

.LBB0_17:
	v_ashrrev_i32_e32 v15, 31, v1
	v_lshrrev_b32_e32 v15, 27, v15
	v_add_u32_e32 v15, v1, v15
	v_ashrrev_i32_e32 v15, 5, v15
	v_lshlrev_b32_e32 v16, 6, v15
	v_lshlrev_b32_e32 v15, 11, v15
	v_sub_u32_e32 v18, v9, v15
	v_or_b32_e32 v20, v16, v6
	v_ashrrev_i32_e32 v17, 31, v16
	v_ashrrev_i32_e32 v19, 31, v18
	v_ashrrev_i32_e32 v21, 31, v20
	v_or_b32_e32 v22, 4, v20
	v_lshl_add_u64 v[80:81], v[16:17], 1, v[4:5]
	v_add_u32_e32 v16, v18, v7
	v_lshl_add_u64 v[52:53], v[18:19], 2, v[2:3]
	v_lshlrev_b64 v[18:19], 13, v[20:21]
	v_or_b32_e32 v24, 8, v20
	v_or_b32_e32 v26, 12, v20
	v_or_b32_e32 v28, 16, v20
	v_or_b32_e32 v30, 20, v20
	v_or_b32_e32 v32, 24, v20
	v_or_b32_e32 v34, 28, v20
	v_or_b32_e32 v36, 32, v20
	v_or_b32_e32 v38, 36, v20
	v_or_b32_e32 v40, 40, v20
	v_or_b32_e32 v42, 44, v20
	v_or_b32_e32 v44, 48, v20
	v_or_b32_e32 v46, 52, v20
	v_or_b32_e32 v48, 56, v20
	v_or_b32_e32 v50, 60, v20
	v_ashrrev_i32_e32 v23, 31, v22
	v_ashrrev_i32_e32 v17, 31, v16
	v_lshl_add_u64 v[18:19], v[52:53], 0, v[18:19]
	v_ashrrev_i32_e32 v25, 31, v24
	v_ashrrev_i32_e32 v27, 31, v26
	v_ashrrev_i32_e32 v29, 31, v28
	v_ashrrev_i32_e32 v31, 31, v30
	v_ashrrev_i32_e32 v33, 31, v32
	v_ashrrev_i32_e32 v35, 31, v34
	v_ashrrev_i32_e32 v37, 31, v36
	v_ashrrev_i32_e32 v39, 31, v38
	v_ashrrev_i32_e32 v41, 31, v40
	v_ashrrev_i32_e32 v43, 31, v42
	v_ashrrev_i32_e32 v45, 31, v44
	v_ashrrev_i32_e32 v47, 31, v46
	v_ashrrev_i32_e32 v49, 31, v48
	v_ashrrev_i32_e32 v51, 31, v50
	v_add_u32_e32 v20, 8, v16
	v_add_u32_e32 v54, 16, v16
	v_add_u32_e32 v56, 24, v16
	v_add_u32_e32 v58, 32, v16
	v_add_u32_e32 v60, 40, v16
	v_add_u32_e32 v62, 48, v16
	v_add_u32_e32 v64, 56, v16
	v_lshlrev_b64 v[22:23], 13, v[22:23]
	v_lshlrev_b64 v[66:67], 12, v[16:17]
	global_load_dwordx4 v[16:19], v[18:19], off nt
	v_lshlrev_b64 v[24:25], 13, v[24:25]
	v_lshlrev_b64 v[26:27], 13, v[26:27]
	v_lshlrev_b64 v[28:29], 13, v[28:29]
	v_lshlrev_b64 v[30:31], 13, v[30:31]
	v_lshlrev_b64 v[32:33], 13, v[32:33]
	v_lshlrev_b64 v[34:35], 13, v[34:35]
	v_lshlrev_b64 v[36:37], 13, v[36:37]
	v_lshlrev_b64 v[38:39], 13, v[38:39]
	v_lshlrev_b64 v[40:41], 13, v[40:41]
	v_lshlrev_b64 v[42:43], 13, v[42:43]
	v_lshlrev_b64 v[44:45], 13, v[44:45]
	v_lshlrev_b64 v[46:47], 13, v[46:47]
	v_lshlrev_b64 v[48:49], 13, v[48:49]
	v_lshlrev_b64 v[50:51], 13, v[50:51]
	v_ashrrev_i32_e32 v21, 31, v20
	v_ashrrev_i32_e32 v55, 31, v54
	v_ashrrev_i32_e32 v57, 31, v56
	v_ashrrev_i32_e32 v59, 31, v58
	v_ashrrev_i32_e32 v61, 31, v60
	v_ashrrev_i32_e32 v63, 31, v62
	v_ashrrev_i32_e32 v65, 31, v64
	v_lshl_add_u64 v[82:83], v[52:53], 0, v[22:23]
	v_lshl_add_u64 v[84:85], v[52:53], 0, v[24:25]
	v_lshl_add_u64 v[86:87], v[52:53], 0, v[26:27]
	v_lshl_add_u64 v[88:89], v[52:53], 0, v[28:29]
	v_lshl_add_u64 v[90:91], v[52:53], 0, v[30:31]
	v_lshl_add_u64 v[92:93], v[52:53], 0, v[32:33]
	v_lshl_add_u64 v[94:95], v[52:53], 0, v[34:35]
	v_lshl_add_u64 v[96:97], v[52:53], 0, v[36:37]
	v_lshl_add_u64 v[98:99], v[52:53], 0, v[38:39]
	v_lshl_add_u64 v[100:101], v[52:53], 0, v[40:41]
	v_lshl_add_u64 v[102:103], v[52:53], 0, v[42:43]
	v_lshl_add_u64 v[104:105], v[52:53], 0, v[44:45]
	v_lshl_add_u64 v[106:107], v[52:53], 0, v[46:47]
	v_lshl_add_u64 v[108:109], v[52:53], 0, v[48:49]
	v_lshl_add_u64 v[110:111], v[52:53], 0, v[50:51]
	v_lshl_add_u64 v[112:113], v[80:81], 0, v[66:67]
	v_lshlrev_b64 v[114:115], 12, v[20:21]
	v_lshlrev_b64 v[116:117], 12, v[54:55]
	v_lshlrev_b64 v[118:119], 12, v[56:57]
	v_lshlrev_b64 v[120:121], 12, v[58:59]
	v_lshlrev_b64 v[122:123], 12, v[60:61]
	v_lshlrev_b64 v[124:125], 12, v[62:63]
	v_lshlrev_b64 v[126:127], 12, v[64:65]
	global_load_dwordx4 v[20:23], v[82:83], off nt
	global_load_dwordx4 v[24:27], v[84:85], off nt
	global_load_dwordx4 v[28:31], v[86:87], off nt
	global_load_dwordx4 v[32:35], v[88:89], off nt
	global_load_dwordx4 v[36:39], v[90:91], off nt
	global_load_dwordx4 v[40:43], v[92:93], off nt
	global_load_dwordx4 v[44:47], v[94:95], off nt
	global_load_dwordx4 v[48:51], v[96:97], off nt
	global_load_dwordx4 v[52:55], v[98:99], off nt
	global_load_dwordx4 v[56:59], v[100:101], off nt
	global_load_dwordx4 v[60:63], v[102:103], off nt
	global_load_dwordx4 v[64:67], v[104:105], off nt
	global_load_dwordx4 v[68:71], v[106:107], off nt
	global_load_dwordx4 v[72:75], v[108:109], off nt
	global_load_dwordx4 v[76:79], v[110:111], off nt
	v_lshl_add_u64 v[82:83], v[80:81], 0, v[114:115]
	v_lshl_add_u64 v[84:85], v[80:81], 0, v[116:117]
	v_lshl_add_u64 v[86:87], v[80:81], 0, v[118:119]
	v_lshl_add_u64 v[88:89], v[80:81], 0, v[120:121]
	v_lshl_add_u64 v[90:91], v[80:81], 0, v[122:123]
	v_lshl_add_u64 v[92:93], v[80:81], 0, v[124:125]
	v_lshl_add_u64 v[80:81], v[80:81], 0, v[126:127]
	v_add_u32_e32 v1, s94, v1
	v_cmp_lt_i32_e32 vcc, s5, v1
	s_or_b64 s[2:3], vcc, s[2:3]
	v_add_u32_e32 v9, s4, v9
	s_waitcnt vmcnt(15)
	v_cvt_pk_bf16_f32 v15, v16, s0
	v_cvt_pk_bf16_f32 v16, v17, s0
	v_cvt_pk_bf16_f32 v17, v18, s0
	v_cvt_pk_bf16_f32 v18, v19, s0
	ds_write_b16 v8, v15
	ds_write_b16 v8, v16 offset:144
	ds_write_b16 v8, v17 offset:288
	ds_write_b16 v8, v18 offset:432
	s_waitcnt vmcnt(14)
	v_cvt_pk_bf16_f32 v15, v20, s0
	v_cvt_pk_bf16_f32 v16, v21, s0
	v_cvt_pk_bf16_f32 v17, v22, s0
	v_cvt_pk_bf16_f32 v18, v23, s0
	s_waitcnt vmcnt(13)
	v_cvt_pk_bf16_f32 v19, v24, s0
	v_cvt_pk_bf16_f32 v20, v25, s0
	v_cvt_pk_bf16_f32 v21, v26, s0
	v_cvt_pk_bf16_f32 v22, v27, s0
	s_waitcnt vmcnt(12)
	v_cvt_pk_bf16_f32 v23, v28, s0
	v_cvt_pk_bf16_f32 v24, v29, s0
	v_cvt_pk_bf16_f32 v25, v30, s0
	v_cvt_pk_bf16_f32 v26, v31, s0
	s_waitcnt vmcnt(11)
	v_cvt_pk_bf16_f32 v27, v32, s0
	v_cvt_pk_bf16_f32 v28, v33, s0
	v_cvt_pk_bf16_f32 v29, v34, s0
	v_cvt_pk_bf16_f32 v30, v35, s0
	s_waitcnt vmcnt(10)
	v_cvt_pk_bf16_f32 v31, v36, s0
	v_cvt_pk_bf16_f32 v32, v37, s0
	v_cvt_pk_bf16_f32 v33, v38, s0
	v_cvt_pk_bf16_f32 v34, v39, s0
	s_waitcnt vmcnt(9)
	v_cvt_pk_bf16_f32 v35, v40, s0
	v_cvt_pk_bf16_f32 v36, v41, s0
	v_cvt_pk_bf16_f32 v37, v42, s0
	v_cvt_pk_bf16_f32 v38, v43, s0
	s_waitcnt vmcnt(8)
	v_cvt_pk_bf16_f32 v39, v44, s0
	v_cvt_pk_bf16_f32 v40, v45, s0
	v_cvt_pk_bf16_f32 v41, v46, s0
	v_cvt_pk_bf16_f32 v42, v47, s0
	s_waitcnt vmcnt(7)
	v_cvt_pk_bf16_f32 v43, v48, s0
	v_cvt_pk_bf16_f32 v44, v49, s0
	v_cvt_pk_bf16_f32 v45, v50, s0
	v_cvt_pk_bf16_f32 v46, v51, s0
	s_waitcnt vmcnt(6)
	v_cvt_pk_bf16_f32 v47, v52, s0
	v_cvt_pk_bf16_f32 v48, v53, s0
	v_cvt_pk_bf16_f32 v49, v54, s0
	v_cvt_pk_bf16_f32 v50, v55, s0
	s_waitcnt vmcnt(5)
	v_cvt_pk_bf16_f32 v51, v56, s0
	v_cvt_pk_bf16_f32 v52, v57, s0
	v_cvt_pk_bf16_f32 v53, v58, s0
	v_cvt_pk_bf16_f32 v54, v59, s0
	s_waitcnt vmcnt(4)
	v_cvt_pk_bf16_f32 v55, v60, s0
	v_cvt_pk_bf16_f32 v56, v61, s0
	v_cvt_pk_bf16_f32 v57, v62, s0
	v_cvt_pk_bf16_f32 v58, v63, s0
	s_waitcnt vmcnt(3)
	v_cvt_pk_bf16_f32 v59, v64, s0
	v_cvt_pk_bf16_f32 v60, v65, s0
	v_cvt_pk_bf16_f32 v61, v66, s0
	v_cvt_pk_bf16_f32 v62, v67, s0
	s_waitcnt vmcnt(2)
	v_cvt_pk_bf16_f32 v63, v68, s0
	v_cvt_pk_bf16_f32 v64, v69, s0
	v_cvt_pk_bf16_f32 v65, v70, s0
	v_cvt_pk_bf16_f32 v66, v71, s0
	s_waitcnt vmcnt(1)
	v_cvt_pk_bf16_f32 v67, v72, s0
	v_cvt_pk_bf16_f32 v68, v73, s0
	v_cvt_pk_bf16_f32 v69, v74, s0
	v_cvt_pk_bf16_f32 v70, v75, s0
	s_waitcnt vmcnt(0)
	v_cvt_pk_bf16_f32 v71, v76, s0
	v_cvt_pk_bf16_f32 v72, v77, s0
	v_cvt_pk_bf16_f32 v73, v78, s0
	v_cvt_pk_bf16_f32 v74, v79, s0
	ds_write_b16 v8, v15 offset:8
	ds_write_b16 v8, v16 offset:152
	ds_write_b16 v8, v17 offset:296
	ds_write_b16 v8, v18 offset:440
	ds_write_b16 v8, v19 offset:16
	ds_write_b16 v8, v20 offset:160
	ds_write_b16 v8, v21 offset:304
	ds_write_b16 v8, v22 offset:448
	ds_write_b16 v8, v23 offset:24
	ds_write_b16 v8, v24 offset:168
	ds_write_b16 v8, v25 offset:312
	ds_write_b16 v8, v26 offset:456
	ds_write_b16 v8, v27 offset:32
	ds_write_b16 v8, v28 offset:176
	ds_write_b16 v8, v29 offset:320
	ds_write_b16 v8, v30 offset:464
	ds_write_b16 v8, v31 offset:40
	ds_write_b16 v8, v32 offset:184
	ds_write_b16 v8, v33 offset:328
	ds_write_b16 v8, v34 offset:472
	ds_write_b16 v8, v35 offset:48
	ds_write_b16 v8, v36 offset:192
	ds_write_b16 v8, v37 offset:336
	ds_write_b16 v8, v38 offset:480
	ds_write_b16 v8, v39 offset:56
	ds_write_b16 v8, v40 offset:200
	ds_write_b16 v8, v41 offset:344
	ds_write_b16 v8, v42 offset:488
	ds_write_b16 v8, v43 offset:64
	ds_write_b16 v8, v44 offset:208
	ds_write_b16 v8, v45 offset:352
	ds_write_b16 v8, v46 offset:496
	ds_write_b16 v8, v47 offset:72
	ds_write_b16 v8, v48 offset:216
	ds_write_b16 v8, v49 offset:360
	ds_write_b16 v8, v50 offset:504
	ds_write_b16 v8, v51 offset:80
	ds_write_b16 v8, v52 offset:224
	ds_write_b16 v8, v53 offset:368
	ds_write_b16 v8, v54 offset:512
	ds_write_b16 v8, v55 offset:88
	ds_write_b16 v8, v56 offset:232
	ds_write_b16 v8, v57 offset:376
	ds_write_b16 v8, v58 offset:520
	ds_write_b16 v8, v59 offset:96
	ds_write_b16 v8, v60 offset:240
	ds_write_b16 v8, v61 offset:384
	ds_write_b16 v8, v62 offset:528
	ds_write_b16 v8, v63 offset:104
	ds_write_b16 v8, v64 offset:248
	ds_write_b16 v8, v65 offset:392
	ds_write_b16 v8, v66 offset:536
	ds_write_b16 v8, v67 offset:112
	ds_write_b16 v8, v68 offset:256
	ds_write_b16 v8, v69 offset:400
	ds_write_b16 v8, v70 offset:544
	ds_write_b16 v8, v71 offset:120
	ds_write_b16 v8, v72 offset:264
	ds_write_b16 v8, v73 offset:408
	ds_write_b16 v8, v74 offset:552
	s_waitcnt lgkmcnt(0)
	ds_read_b128 v[16:19], v13
	ds_read_b128 v[20:23], v14
	ds_read_b128 v[24:27], v14 offset:1152
	ds_read_b128 v[28:31], v14 offset:2304
	ds_read_b128 v[32:35], v14 offset:3456
	ds_read_b128 v[36:39], v14 offset:4608
	ds_read_b128 v[40:43], v14 offset:5760
	ds_read_b128 v[44:47], v14 offset:6912
	s_waitcnt lgkmcnt(7)
	global_store_dwordx4 v[112:113], v[16:19], off
	s_waitcnt lgkmcnt(6)
	global_store_dwordx4 v[82:83], v[20:23], off
	s_waitcnt lgkmcnt(5)
	global_store_dwordx4 v[84:85], v[24:27], off
	s_waitcnt lgkmcnt(4)
	global_store_dwordx4 v[86:87], v[28:31], off
	s_waitcnt lgkmcnt(3)
	global_store_dwordx4 v[88:89], v[32:35], off
	s_waitcnt lgkmcnt(2)
	global_store_dwordx4 v[90:91], v[36:39], off
	s_waitcnt lgkmcnt(1)
	global_store_dwordx4 v[92:93], v[40:43], off
	s_waitcnt lgkmcnt(0)
	global_store_dwordx4 v[80:81], v[44:47], off
	s_waitcnt lgkmcnt(0)
	s_andn2_b64 exec, exec, s[2:3]
	s_cbranch_execnz .LBB0_17

.LBB0_20:
	v_ashrrev_i32_e32 v15, 31, v1
	v_lshrrev_b32_e32 v15, 25, v15
	v_add_u32_e32 v15, v1, v15
	v_ashrrev_i32_e32 v15, 7, v15
	v_lshlrev_b32_e32 v16, 6, v15
	v_lshlrev_b32_e32 v15, 13, v15
	v_sub_u32_e32 v18, v9, v15
	v_or_b32_e32 v20, v16, v6
	v_ashrrev_i32_e32 v17, 31, v16
	v_ashrrev_i32_e32 v19, 31, v18
	v_ashrrev_i32_e32 v21, 31, v20
	v_or_b32_e32 v22, 4, v20
	v_lshl_add_u64 v[80:81], v[16:17], 1, v[4:5]
	v_add_u32_e32 v16, v18, v7
	v_lshl_add_u64 v[52:53], v[18:19], 2, v[2:3]
	v_lshlrev_b64 v[18:19], 15, v[20:21]
	v_or_b32_e32 v24, 8, v20
	v_or_b32_e32 v26, 12, v20
	v_or_b32_e32 v28, 16, v20
	v_or_b32_e32 v30, 20, v20
	v_or_b32_e32 v32, 24, v20
	v_or_b32_e32 v34, 28, v20
	v_or_b32_e32 v36, 32, v20
	v_or_b32_e32 v38, 36, v20
	v_or_b32_e32 v40, 40, v20
	v_or_b32_e32 v42, 44, v20
	v_or_b32_e32 v44, 48, v20
	v_or_b32_e32 v46, 52, v20
	v_or_b32_e32 v48, 56, v20
	v_or_b32_e32 v50, 60, v20
	v_ashrrev_i32_e32 v23, 31, v22
	v_ashrrev_i32_e32 v17, 31, v16
	v_lshl_add_u64 v[18:19], v[52:53], 0, v[18:19]
	v_ashrrev_i32_e32 v25, 31, v24
	v_ashrrev_i32_e32 v27, 31, v26
	v_ashrrev_i32_e32 v29, 31, v28
	v_ashrrev_i32_e32 v31, 31, v30
	v_ashrrev_i32_e32 v33, 31, v32
	v_ashrrev_i32_e32 v35, 31, v34
	v_ashrrev_i32_e32 v37, 31, v36
	v_ashrrev_i32_e32 v39, 31, v38
	v_ashrrev_i32_e32 v41, 31, v40
	v_ashrrev_i32_e32 v43, 31, v42
	v_ashrrev_i32_e32 v45, 31, v44
	v_ashrrev_i32_e32 v47, 31, v46
	v_ashrrev_i32_e32 v49, 31, v48
	v_ashrrev_i32_e32 v51, 31, v50
	v_add_u32_e32 v20, 8, v16
	v_add_u32_e32 v54, 16, v16
	v_add_u32_e32 v56, 24, v16
	v_add_u32_e32 v58, 32, v16
	v_add_u32_e32 v60, 40, v16
	v_add_u32_e32 v62, 48, v16
	v_add_u32_e32 v64, 56, v16
	v_lshlrev_b64 v[22:23], 15, v[22:23]
	v_lshlrev_b64 v[66:67], 12, v[16:17]
	global_load_dwordx4 v[16:19], v[18:19], off nt
	v_lshlrev_b64 v[24:25], 15, v[24:25]
	v_lshlrev_b64 v[26:27], 15, v[26:27]
	v_lshlrev_b64 v[28:29], 15, v[28:29]
	v_lshlrev_b64 v[30:31], 15, v[30:31]
	v_lshlrev_b64 v[32:33], 15, v[32:33]
	v_lshlrev_b64 v[34:35], 15, v[34:35]
	v_lshlrev_b64 v[36:37], 15, v[36:37]
	v_lshlrev_b64 v[38:39], 15, v[38:39]
	v_lshlrev_b64 v[40:41], 15, v[40:41]
	v_lshlrev_b64 v[42:43], 15, v[42:43]
	v_lshlrev_b64 v[44:45], 15, v[44:45]
	v_lshlrev_b64 v[46:47], 15, v[46:47]
	v_lshlrev_b64 v[48:49], 15, v[48:49]
	v_lshlrev_b64 v[50:51], 15, v[50:51]
	v_ashrrev_i32_e32 v21, 31, v20
	v_ashrrev_i32_e32 v55, 31, v54
	v_ashrrev_i32_e32 v57, 31, v56
	v_ashrrev_i32_e32 v59, 31, v58
	v_ashrrev_i32_e32 v61, 31, v60
	v_ashrrev_i32_e32 v63, 31, v62
	v_ashrrev_i32_e32 v65, 31, v64
	v_lshl_add_u64 v[82:83], v[52:53], 0, v[22:23]
	v_lshl_add_u64 v[84:85], v[52:53], 0, v[24:25]
	v_lshl_add_u64 v[86:87], v[52:53], 0, v[26:27]
	v_lshl_add_u64 v[88:89], v[52:53], 0, v[28:29]
	v_lshl_add_u64 v[90:91], v[52:53], 0, v[30:31]
	v_lshl_add_u64 v[92:93], v[52:53], 0, v[32:33]
	v_lshl_add_u64 v[94:95], v[52:53], 0, v[34:35]
	v_lshl_add_u64 v[96:97], v[52:53], 0, v[36:37]
	v_lshl_add_u64 v[98:99], v[52:53], 0, v[38:39]
	v_lshl_add_u64 v[100:101], v[52:53], 0, v[40:41]
	v_lshl_add_u64 v[102:103], v[52:53], 0, v[42:43]
	v_lshl_add_u64 v[104:105], v[52:53], 0, v[44:45]
	v_lshl_add_u64 v[106:107], v[52:53], 0, v[46:47]
	v_lshl_add_u64 v[108:109], v[52:53], 0, v[48:49]
	v_lshl_add_u64 v[110:111], v[52:53], 0, v[50:51]
	v_lshl_add_u64 v[112:113], v[80:81], 0, v[66:67]
	v_lshlrev_b64 v[114:115], 12, v[20:21]
	v_lshlrev_b64 v[116:117], 12, v[54:55]
	v_lshlrev_b64 v[118:119], 12, v[56:57]
	v_lshlrev_b64 v[120:121], 12, v[58:59]
	v_lshlrev_b64 v[122:123], 12, v[60:61]
	v_lshlrev_b64 v[124:125], 12, v[62:63]
	v_lshlrev_b64 v[126:127], 12, v[64:65]
	global_load_dwordx4 v[20:23], v[82:83], off nt
	global_load_dwordx4 v[24:27], v[84:85], off nt
	global_load_dwordx4 v[28:31], v[86:87], off nt
	global_load_dwordx4 v[32:35], v[88:89], off nt
	global_load_dwordx4 v[36:39], v[90:91], off nt
	global_load_dwordx4 v[40:43], v[92:93], off nt
	global_load_dwordx4 v[44:47], v[94:95], off nt
	global_load_dwordx4 v[48:51], v[96:97], off nt
	global_load_dwordx4 v[52:55], v[98:99], off nt
	global_load_dwordx4 v[56:59], v[100:101], off nt
	global_load_dwordx4 v[60:63], v[102:103], off nt
	global_load_dwordx4 v[64:67], v[104:105], off nt
	global_load_dwordx4 v[68:71], v[106:107], off nt
	global_load_dwordx4 v[72:75], v[108:109], off nt
	global_load_dwordx4 v[76:79], v[110:111], off nt
	v_lshl_add_u64 v[82:83], v[80:81], 0, v[114:115]
	v_lshl_add_u64 v[84:85], v[80:81], 0, v[116:117]
	v_lshl_add_u64 v[86:87], v[80:81], 0, v[118:119]
	v_lshl_add_u64 v[88:89], v[80:81], 0, v[120:121]
	v_lshl_add_u64 v[90:91], v[80:81], 0, v[122:123]
	v_lshl_add_u64 v[92:93], v[80:81], 0, v[124:125]
	v_lshl_add_u64 v[80:81], v[80:81], 0, v[126:127]
	v_add_u32_e32 v1, s94, v1
	v_cmp_lt_i32_e32 vcc, s5, v1
	s_or_b64 s[8:9], vcc, s[8:9]
	v_add_u32_e32 v9, s4, v9
	s_waitcnt vmcnt(15)
	v_cvt_pk_bf16_f32 v15, v16, s0
	v_cvt_pk_bf16_f32 v16, v17, s0
	v_cvt_pk_bf16_f32 v17, v18, s0
	v_cvt_pk_bf16_f32 v18, v19, s0
	ds_write_b16 v8, v15
	ds_write_b16 v8, v16 offset:144
	ds_write_b16 v8, v17 offset:288
	ds_write_b16 v8, v18 offset:432
	s_waitcnt vmcnt(14)
	v_cvt_pk_bf16_f32 v15, v20, s0
	v_cvt_pk_bf16_f32 v16, v21, s0
	v_cvt_pk_bf16_f32 v17, v22, s0
	v_cvt_pk_bf16_f32 v18, v23, s0
	s_waitcnt vmcnt(13)
	v_cvt_pk_bf16_f32 v19, v24, s0
	v_cvt_pk_bf16_f32 v20, v25, s0
	v_cvt_pk_bf16_f32 v21, v26, s0
	v_cvt_pk_bf16_f32 v22, v27, s0
	s_waitcnt vmcnt(12)
	v_cvt_pk_bf16_f32 v23, v28, s0
	v_cvt_pk_bf16_f32 v24, v29, s0
	v_cvt_pk_bf16_f32 v25, v30, s0
	v_cvt_pk_bf16_f32 v26, v31, s0
	s_waitcnt vmcnt(11)
	v_cvt_pk_bf16_f32 v27, v32, s0
	v_cvt_pk_bf16_f32 v28, v33, s0
	v_cvt_pk_bf16_f32 v29, v34, s0
	v_cvt_pk_bf16_f32 v30, v35, s0
	s_waitcnt vmcnt(10)
	v_cvt_pk_bf16_f32 v31, v36, s0
	v_cvt_pk_bf16_f32 v32, v37, s0
	v_cvt_pk_bf16_f32 v33, v38, s0
	v_cvt_pk_bf16_f32 v34, v39, s0
	s_waitcnt vmcnt(9)
	v_cvt_pk_bf16_f32 v35, v40, s0
	v_cvt_pk_bf16_f32 v36, v41, s0
	v_cvt_pk_bf16_f32 v37, v42, s0
	v_cvt_pk_bf16_f32 v38, v43, s0
	s_waitcnt vmcnt(8)
	v_cvt_pk_bf16_f32 v39, v44, s0
	v_cvt_pk_bf16_f32 v40, v45, s0
	v_cvt_pk_bf16_f32 v41, v46, s0
	v_cvt_pk_bf16_f32 v42, v47, s0
	s_waitcnt vmcnt(7)
	v_cvt_pk_bf16_f32 v43, v48, s0
	v_cvt_pk_bf16_f32 v44, v49, s0
	v_cvt_pk_bf16_f32 v45, v50, s0
	v_cvt_pk_bf16_f32 v46, v51, s0
	s_waitcnt vmcnt(6)
	v_cvt_pk_bf16_f32 v47, v52, s0
	v_cvt_pk_bf16_f32 v48, v53, s0
	v_cvt_pk_bf16_f32 v49, v54, s0
	v_cvt_pk_bf16_f32 v50, v55, s0
	s_waitcnt vmcnt(5)
	v_cvt_pk_bf16_f32 v51, v56, s0
	v_cvt_pk_bf16_f32 v52, v57, s0
	v_cvt_pk_bf16_f32 v53, v58, s0
	v_cvt_pk_bf16_f32 v54, v59, s0
	s_waitcnt vmcnt(4)
	v_cvt_pk_bf16_f32 v55, v60, s0
	v_cvt_pk_bf16_f32 v56, v61, s0
	v_cvt_pk_bf16_f32 v57, v62, s0
	v_cvt_pk_bf16_f32 v58, v63, s0
	s_waitcnt vmcnt(3)
	v_cvt_pk_bf16_f32 v59, v64, s0
	v_cvt_pk_bf16_f32 v60, v65, s0
	v_cvt_pk_bf16_f32 v61, v66, s0
	v_cvt_pk_bf16_f32 v62, v67, s0
	s_waitcnt vmcnt(2)
	v_cvt_pk_bf16_f32 v63, v68, s0
	v_cvt_pk_bf16_f32 v64, v69, s0
	v_cvt_pk_bf16_f32 v65, v70, s0
	v_cvt_pk_bf16_f32 v66, v71, s0
	s_waitcnt vmcnt(1)
	v_cvt_pk_bf16_f32 v67, v72, s0
	v_cvt_pk_bf16_f32 v68, v73, s0
	v_cvt_pk_bf16_f32 v69, v74, s0
	v_cvt_pk_bf16_f32 v70, v75, s0
	s_waitcnt vmcnt(0)
	v_cvt_pk_bf16_f32 v71, v76, s0
	v_cvt_pk_bf16_f32 v72, v77, s0
	v_cvt_pk_bf16_f32 v73, v78, s0
	v_cvt_pk_bf16_f32 v74, v79, s0
	ds_write_b16 v8, v15 offset:8
	ds_write_b16 v8, v16 offset:152
	ds_write_b16 v8, v17 offset:296
	ds_write_b16 v8, v18 offset:440
	ds_write_b16 v8, v19 offset:16
	ds_write_b16 v8, v20 offset:160
	ds_write_b16 v8, v21 offset:304
	ds_write_b16 v8, v22 offset:448
	ds_write_b16 v8, v23 offset:24
	ds_write_b16 v8, v24 offset:168
	ds_write_b16 v8, v25 offset:312
	ds_write_b16 v8, v26 offset:456
	ds_write_b16 v8, v27 offset:32
	ds_write_b16 v8, v28 offset:176
	ds_write_b16 v8, v29 offset:320
	ds_write_b16 v8, v30 offset:464
	ds_write_b16 v8, v31 offset:40
	ds_write_b16 v8, v32 offset:184
	ds_write_b16 v8, v33 offset:328
	ds_write_b16 v8, v34 offset:472
	ds_write_b16 v8, v35 offset:48
	ds_write_b16 v8, v36 offset:192
	ds_write_b16 v8, v37 offset:336
	ds_write_b16 v8, v38 offset:480
	ds_write_b16 v8, v39 offset:56
	ds_write_b16 v8, v40 offset:200
	ds_write_b16 v8, v41 offset:344
	ds_write_b16 v8, v42 offset:488
	ds_write_b16 v8, v43 offset:64
	ds_write_b16 v8, v44 offset:208
	ds_write_b16 v8, v45 offset:352
	ds_write_b16 v8, v46 offset:496
	ds_write_b16 v8, v47 offset:72
	ds_write_b16 v8, v48 offset:216
	ds_write_b16 v8, v49 offset:360
	ds_write_b16 v8, v50 offset:504
	ds_write_b16 v8, v51 offset:80
	ds_write_b16 v8, v52 offset:224
	ds_write_b16 v8, v53 offset:368
	ds_write_b16 v8, v54 offset:512
	ds_write_b16 v8, v55 offset:88
	ds_write_b16 v8, v56 offset:232
	ds_write_b16 v8, v57 offset:376
	ds_write_b16 v8, v58 offset:520
	ds_write_b16 v8, v59 offset:96
	ds_write_b16 v8, v60 offset:240
	ds_write_b16 v8, v61 offset:384
	ds_write_b16 v8, v62 offset:528
	ds_write_b16 v8, v63 offset:104
	ds_write_b16 v8, v64 offset:248
	ds_write_b16 v8, v65 offset:392
	ds_write_b16 v8, v66 offset:536
	ds_write_b16 v8, v67 offset:112
	ds_write_b16 v8, v68 offset:256
	ds_write_b16 v8, v69 offset:400
	ds_write_b16 v8, v70 offset:544
	ds_write_b16 v8, v71 offset:120
	ds_write_b16 v8, v72 offset:264
	ds_write_b16 v8, v73 offset:408
	ds_write_b16 v8, v74 offset:552
	s_waitcnt lgkmcnt(0)
	ds_read_b128 v[16:19], v13
	ds_read_b128 v[20:23], v14
	ds_read_b128 v[24:27], v14 offset:1152
	ds_read_b128 v[28:31], v14 offset:2304
	ds_read_b128 v[32:35], v14 offset:3456
	ds_read_b128 v[36:39], v14 offset:4608
	ds_read_b128 v[40:43], v14 offset:5760
	ds_read_b128 v[44:47], v14 offset:6912
	s_waitcnt lgkmcnt(7)
	global_store_dwordx4 v[112:113], v[16:19], off
	s_waitcnt lgkmcnt(6)
	global_store_dwordx4 v[82:83], v[20:23], off
	s_waitcnt lgkmcnt(5)
	global_store_dwordx4 v[84:85], v[24:27], off
	s_waitcnt lgkmcnt(4)
	global_store_dwordx4 v[86:87], v[28:31], off
	s_waitcnt lgkmcnt(3)
	global_store_dwordx4 v[88:89], v[32:35], off
	s_waitcnt lgkmcnt(2)
	global_store_dwordx4 v[90:91], v[36:39], off
	s_waitcnt lgkmcnt(1)
	global_store_dwordx4 v[92:93], v[40:43], off
	s_waitcnt lgkmcnt(0)
	global_store_dwordx4 v[80:81], v[44:47], off
	s_waitcnt lgkmcnt(0)
	s_andn2_b64 exec, exec, s[8:9]
	s_cbranch_execnz .LBB0_20

.LBB0_23:
	v_ashrrev_i32_e32 v15, 31, v1
	v_lshrrev_b32_e32 v15, 25, v15
	v_add_u32_e32 v15, v1, v15
	v_ashrrev_i32_e32 v15, 7, v15
	v_lshlrev_b32_e32 v16, 6, v15
	v_lshlrev_b32_e32 v15, 13, v15
	v_sub_u32_e32 v18, v9, v15
	v_or_b32_e32 v20, v16, v6
	v_ashrrev_i32_e32 v17, 31, v16
	v_ashrrev_i32_e32 v19, 31, v18
	v_ashrrev_i32_e32 v21, 31, v20
	v_or_b32_e32 v22, 4, v20
	v_lshl_add_u64 v[80:81], v[16:17], 1, v[4:5]
	v_add_u32_e32 v16, v18, v7
	v_lshl_add_u64 v[52:53], v[18:19], 2, v[2:3]
	v_lshlrev_b64 v[18:19], 15, v[20:21]
	v_or_b32_e32 v24, 8, v20
	v_or_b32_e32 v26, 12, v20
	v_or_b32_e32 v28, 16, v20
	v_or_b32_e32 v30, 20, v20
	v_or_b32_e32 v32, 24, v20
	v_or_b32_e32 v34, 28, v20
	v_or_b32_e32 v36, 32, v20
	v_or_b32_e32 v38, 36, v20
	v_or_b32_e32 v40, 40, v20
	v_or_b32_e32 v42, 44, v20
	v_or_b32_e32 v44, 48, v20
	v_or_b32_e32 v46, 52, v20
	v_or_b32_e32 v48, 56, v20
	v_or_b32_e32 v50, 60, v20
	v_ashrrev_i32_e32 v23, 31, v22
	v_ashrrev_i32_e32 v17, 31, v16
	v_lshl_add_u64 v[18:19], v[52:53], 0, v[18:19]
	v_ashrrev_i32_e32 v25, 31, v24
	v_ashrrev_i32_e32 v27, 31, v26
	v_ashrrev_i32_e32 v29, 31, v28
	v_ashrrev_i32_e32 v31, 31, v30
	v_ashrrev_i32_e32 v33, 31, v32
	v_ashrrev_i32_e32 v35, 31, v34
	v_ashrrev_i32_e32 v37, 31, v36
	v_ashrrev_i32_e32 v39, 31, v38
	v_ashrrev_i32_e32 v41, 31, v40
	v_ashrrev_i32_e32 v43, 31, v42
	v_ashrrev_i32_e32 v45, 31, v44
	v_ashrrev_i32_e32 v47, 31, v46
	v_ashrrev_i32_e32 v49, 31, v48
	v_ashrrev_i32_e32 v51, 31, v50
	v_add_u32_e32 v20, 8, v16
	v_add_u32_e32 v54, 16, v16
	v_add_u32_e32 v56, 24, v16
	v_add_u32_e32 v58, 32, v16
	v_add_u32_e32 v60, 40, v16
	v_add_u32_e32 v62, 48, v16
	v_add_u32_e32 v64, 56, v16
	v_lshlrev_b64 v[22:23], 15, v[22:23]
	v_lshlrev_b64 v[66:67], 12, v[16:17]
	global_load_dwordx4 v[16:19], v[18:19], off nt
	v_lshlrev_b64 v[24:25], 15, v[24:25]
	v_lshlrev_b64 v[26:27], 15, v[26:27]
	v_lshlrev_b64 v[28:29], 15, v[28:29]
	v_lshlrev_b64 v[30:31], 15, v[30:31]
	v_lshlrev_b64 v[32:33], 15, v[32:33]
	v_lshlrev_b64 v[34:35], 15, v[34:35]
	v_lshlrev_b64 v[36:37], 15, v[36:37]
	v_lshlrev_b64 v[38:39], 15, v[38:39]
	v_lshlrev_b64 v[40:41], 15, v[40:41]
	v_lshlrev_b64 v[42:43], 15, v[42:43]
	v_lshlrev_b64 v[44:45], 15, v[44:45]
	v_lshlrev_b64 v[46:47], 15, v[46:47]
	v_lshlrev_b64 v[48:49], 15, v[48:49]
	v_lshlrev_b64 v[50:51], 15, v[50:51]
	v_ashrrev_i32_e32 v21, 31, v20
	v_ashrrev_i32_e32 v55, 31, v54
	v_ashrrev_i32_e32 v57, 31, v56
	v_ashrrev_i32_e32 v59, 31, v58
	v_ashrrev_i32_e32 v61, 31, v60
	v_ashrrev_i32_e32 v63, 31, v62
	v_ashrrev_i32_e32 v65, 31, v64
	v_lshl_add_u64 v[82:83], v[52:53], 0, v[22:23]
	v_lshl_add_u64 v[84:85], v[52:53], 0, v[24:25]
	v_lshl_add_u64 v[86:87], v[52:53], 0, v[26:27]
	v_lshl_add_u64 v[88:89], v[52:53], 0, v[28:29]
	v_lshl_add_u64 v[90:91], v[52:53], 0, v[30:31]
	v_lshl_add_u64 v[92:93], v[52:53], 0, v[32:33]
	v_lshl_add_u64 v[94:95], v[52:53], 0, v[34:35]
	v_lshl_add_u64 v[96:97], v[52:53], 0, v[36:37]
	v_lshl_add_u64 v[98:99], v[52:53], 0, v[38:39]
	v_lshl_add_u64 v[100:101], v[52:53], 0, v[40:41]
	v_lshl_add_u64 v[102:103], v[52:53], 0, v[42:43]
	v_lshl_add_u64 v[104:105], v[52:53], 0, v[44:45]
	v_lshl_add_u64 v[106:107], v[52:53], 0, v[46:47]
	v_lshl_add_u64 v[108:109], v[52:53], 0, v[48:49]
	v_lshl_add_u64 v[110:111], v[52:53], 0, v[50:51]
	v_lshl_add_u64 v[112:113], v[80:81], 0, v[66:67]
	v_lshlrev_b64 v[114:115], 12, v[20:21]
	v_lshlrev_b64 v[116:117], 12, v[54:55]
	v_lshlrev_b64 v[118:119], 12, v[56:57]
	v_lshlrev_b64 v[120:121], 12, v[58:59]
	v_lshlrev_b64 v[122:123], 12, v[60:61]
	v_lshlrev_b64 v[124:125], 12, v[62:63]
	v_lshlrev_b64 v[126:127], 12, v[64:65]
	global_load_dwordx4 v[20:23], v[82:83], off nt
	global_load_dwordx4 v[24:27], v[84:85], off nt
	global_load_dwordx4 v[28:31], v[86:87], off nt
	global_load_dwordx4 v[32:35], v[88:89], off nt
	global_load_dwordx4 v[36:39], v[90:91], off nt
	global_load_dwordx4 v[40:43], v[92:93], off nt
	global_load_dwordx4 v[44:47], v[94:95], off nt
	global_load_dwordx4 v[48:51], v[96:97], off nt
	global_load_dwordx4 v[52:55], v[98:99], off nt
	global_load_dwordx4 v[56:59], v[100:101], off nt
	global_load_dwordx4 v[60:63], v[102:103], off nt
	global_load_dwordx4 v[64:67], v[104:105], off nt
	global_load_dwordx4 v[68:71], v[106:107], off nt
	global_load_dwordx4 v[72:75], v[108:109], off nt
	global_load_dwordx4 v[76:79], v[110:111], off nt
	v_lshl_add_u64 v[82:83], v[80:81], 0, v[114:115]
	v_lshl_add_u64 v[84:85], v[80:81], 0, v[116:117]
	v_lshl_add_u64 v[86:87], v[80:81], 0, v[118:119]
	v_lshl_add_u64 v[88:89], v[80:81], 0, v[120:121]
	v_lshl_add_u64 v[90:91], v[80:81], 0, v[122:123]
	v_lshl_add_u64 v[92:93], v[80:81], 0, v[124:125]
	v_lshl_add_u64 v[80:81], v[80:81], 0, v[126:127]
	v_add_u32_e32 v1, s94, v1
	v_cmp_lt_i32_e32 vcc, s5, v1
	s_or_b64 s[2:3], vcc, s[2:3]
	v_add_u32_e32 v9, s4, v9
	s_waitcnt vmcnt(15)
	v_cvt_pk_bf16_f32 v15, v16, s0
	v_cvt_pk_bf16_f32 v16, v17, s0
	v_cvt_pk_bf16_f32 v17, v18, s0
	v_cvt_pk_bf16_f32 v18, v19, s0
	ds_write_b16 v8, v15
	ds_write_b16 v8, v16 offset:144
	ds_write_b16 v8, v17 offset:288
	ds_write_b16 v8, v18 offset:432
	s_waitcnt vmcnt(14)
	v_cvt_pk_bf16_f32 v15, v20, s0
	v_cvt_pk_bf16_f32 v16, v21, s0
	v_cvt_pk_bf16_f32 v17, v22, s0
	v_cvt_pk_bf16_f32 v18, v23, s0
	s_waitcnt vmcnt(13)
	v_cvt_pk_bf16_f32 v19, v24, s0
	v_cvt_pk_bf16_f32 v20, v25, s0
	v_cvt_pk_bf16_f32 v21, v26, s0
	v_cvt_pk_bf16_f32 v22, v27, s0
	s_waitcnt vmcnt(12)
	v_cvt_pk_bf16_f32 v23, v28, s0
	v_cvt_pk_bf16_f32 v24, v29, s0
	v_cvt_pk_bf16_f32 v25, v30, s0
	v_cvt_pk_bf16_f32 v26, v31, s0
	s_waitcnt vmcnt(11)
	v_cvt_pk_bf16_f32 v27, v32, s0
	v_cvt_pk_bf16_f32 v28, v33, s0
	v_cvt_pk_bf16_f32 v29, v34, s0
	v_cvt_pk_bf16_f32 v30, v35, s0
	s_waitcnt vmcnt(10)
	v_cvt_pk_bf16_f32 v31, v36, s0
	v_cvt_pk_bf16_f32 v32, v37, s0
	v_cvt_pk_bf16_f32 v33, v38, s0
	v_cvt_pk_bf16_f32 v34, v39, s0
	s_waitcnt vmcnt(9)
	v_cvt_pk_bf16_f32 v35, v40, s0
	v_cvt_pk_bf16_f32 v36, v41, s0
	v_cvt_pk_bf16_f32 v37, v42, s0
	v_cvt_pk_bf16_f32 v38, v43, s0
	s_waitcnt vmcnt(8)
	v_cvt_pk_bf16_f32 v39, v44, s0
	v_cvt_pk_bf16_f32 v40, v45, s0
	v_cvt_pk_bf16_f32 v41, v46, s0
	v_cvt_pk_bf16_f32 v42, v47, s0
	s_waitcnt vmcnt(7)
	v_cvt_pk_bf16_f32 v43, v48, s0
	v_cvt_pk_bf16_f32 v44, v49, s0
	v_cvt_pk_bf16_f32 v45, v50, s0
	v_cvt_pk_bf16_f32 v46, v51, s0
	s_waitcnt vmcnt(6)
	v_cvt_pk_bf16_f32 v47, v52, s0
	v_cvt_pk_bf16_f32 v48, v53, s0
	v_cvt_pk_bf16_f32 v49, v54, s0
	v_cvt_pk_bf16_f32 v50, v55, s0
	s_waitcnt vmcnt(5)
	v_cvt_pk_bf16_f32 v51, v56, s0
	v_cvt_pk_bf16_f32 v52, v57, s0
	v_cvt_pk_bf16_f32 v53, v58, s0
	v_cvt_pk_bf16_f32 v54, v59, s0
	s_waitcnt vmcnt(4)
	v_cvt_pk_bf16_f32 v55, v60, s0
	v_cvt_pk_bf16_f32 v56, v61, s0
	v_cvt_pk_bf16_f32 v57, v62, s0
	v_cvt_pk_bf16_f32 v58, v63, s0
	s_waitcnt vmcnt(3)
	v_cvt_pk_bf16_f32 v59, v64, s0
	v_cvt_pk_bf16_f32 v60, v65, s0
	v_cvt_pk_bf16_f32 v61, v66, s0
	v_cvt_pk_bf16_f32 v62, v67, s0
	s_waitcnt vmcnt(2)
	v_cvt_pk_bf16_f32 v63, v68, s0
	v_cvt_pk_bf16_f32 v64, v69, s0
	v_cvt_pk_bf16_f32 v65, v70, s0
	v_cvt_pk_bf16_f32 v66, v71, s0
	s_waitcnt vmcnt(1)
	v_cvt_pk_bf16_f32 v67, v72, s0
	v_cvt_pk_bf16_f32 v68, v73, s0
	v_cvt_pk_bf16_f32 v69, v74, s0
	v_cvt_pk_bf16_f32 v70, v75, s0
	s_waitcnt vmcnt(0)
	v_cvt_pk_bf16_f32 v71, v76, s0
	v_cvt_pk_bf16_f32 v72, v77, s0
	v_cvt_pk_bf16_f32 v73, v78, s0
	v_cvt_pk_bf16_f32 v74, v79, s0
	ds_write_b16 v8, v15 offset:8
	ds_write_b16 v8, v16 offset:152
	ds_write_b16 v8, v17 offset:296
	ds_write_b16 v8, v18 offset:440
	ds_write_b16 v8, v19 offset:16
	ds_write_b16 v8, v20 offset:160
	ds_write_b16 v8, v21 offset:304
	ds_write_b16 v8, v22 offset:448
	ds_write_b16 v8, v23 offset:24
	ds_write_b16 v8, v24 offset:168
	ds_write_b16 v8, v25 offset:312
	ds_write_b16 v8, v26 offset:456
	ds_write_b16 v8, v27 offset:32
	ds_write_b16 v8, v28 offset:176
	ds_write_b16 v8, v29 offset:320
	ds_write_b16 v8, v30 offset:464
	ds_write_b16 v8, v31 offset:40
	ds_write_b16 v8, v32 offset:184
	ds_write_b16 v8, v33 offset:328
	ds_write_b16 v8, v34 offset:472
	ds_write_b16 v8, v35 offset:48
	ds_write_b16 v8, v36 offset:192
	ds_write_b16 v8, v37 offset:336
	ds_write_b16 v8, v38 offset:480
	ds_write_b16 v8, v39 offset:56
	ds_write_b16 v8, v40 offset:200
	ds_write_b16 v8, v41 offset:344
	ds_write_b16 v8, v42 offset:488
	ds_write_b16 v8, v43 offset:64
	ds_write_b16 v8, v44 offset:208
	ds_write_b16 v8, v45 offset:352
	ds_write_b16 v8, v46 offset:496
	ds_write_b16 v8, v47 offset:72
	ds_write_b16 v8, v48 offset:216
	ds_write_b16 v8, v49 offset:360
	ds_write_b16 v8, v50 offset:504
	ds_write_b16 v8, v51 offset:80
	ds_write_b16 v8, v52 offset:224
	ds_write_b16 v8, v53 offset:368
	ds_write_b16 v8, v54 offset:512
	ds_write_b16 v8, v55 offset:88
	ds_write_b16 v8, v56 offset:232
	ds_write_b16 v8, v57 offset:376
	ds_write_b16 v8, v58 offset:520
	ds_write_b16 v8, v59 offset:96
	ds_write_b16 v8, v60 offset:240
	ds_write_b16 v8, v61 offset:384
	ds_write_b16 v8, v62 offset:528
	ds_write_b16 v8, v63 offset:104
	ds_write_b16 v8, v64 offset:248
	ds_write_b16 v8, v65 offset:392
	ds_write_b16 v8, v66 offset:536
	ds_write_b16 v8, v67 offset:112
	ds_write_b16 v8, v68 offset:256
	ds_write_b16 v8, v69 offset:400
	ds_write_b16 v8, v70 offset:544
	ds_write_b16 v8, v71 offset:120
	ds_write_b16 v8, v72 offset:264
	ds_write_b16 v8, v73 offset:408
	ds_write_b16 v8, v74 offset:552
	s_waitcnt lgkmcnt(0)
	ds_read_b128 v[16:19], v13
	ds_read_b128 v[20:23], v14
	ds_read_b128 v[24:27], v14 offset:1152
	ds_read_b128 v[28:31], v14 offset:2304
	ds_read_b128 v[32:35], v14 offset:3456
	ds_read_b128 v[36:39], v14 offset:4608
	ds_read_b128 v[40:43], v14 offset:5760
	ds_read_b128 v[44:47], v14 offset:6912
	s_waitcnt lgkmcnt(7)
	global_store_dwordx4 v[112:113], v[16:19], off
	s_waitcnt lgkmcnt(6)
	global_store_dwordx4 v[82:83], v[20:23], off
	s_waitcnt lgkmcnt(5)
	global_store_dwordx4 v[84:85], v[24:27], off
	s_waitcnt lgkmcnt(4)
	global_store_dwordx4 v[86:87], v[28:31], off
	s_waitcnt lgkmcnt(3)
	global_store_dwordx4 v[88:89], v[32:35], off
	s_waitcnt lgkmcnt(2)
	global_store_dwordx4 v[90:91], v[36:39], off
	s_waitcnt lgkmcnt(1)
	global_store_dwordx4 v[92:93], v[40:43], off
	s_waitcnt lgkmcnt(0)
	global_store_dwordx4 v[80:81], v[44:47], off
	s_waitcnt lgkmcnt(0)
	s_andn2_b64 exec, exec, s[2:3]
	s_cbranch_execnz .LBB0_23

.LBB0_26:
	v_ashrrev_i32_e32 v15, 31, v1
	v_lshrrev_b32_e32 v15, 27, v15
	v_add_u32_e32 v15, v1, v15
	v_ashrrev_i32_e32 v15, 5, v15
	v_lshlrev_b32_e32 v16, 6, v15
	v_lshlrev_b32_e32 v15, 11, v15
	v_sub_u32_e32 v18, v9, v15
	v_or_b32_e32 v20, v16, v6
	v_ashrrev_i32_e32 v17, 31, v16
	v_ashrrev_i32_e32 v19, 31, v18
	v_ashrrev_i32_e32 v21, 31, v20
	v_or_b32_e32 v22, 4, v20
	v_lshl_add_u64 v[80:81], v[16:17], 1, v[4:5]
	v_add_u32_e32 v16, v18, v7
	v_lshl_add_u64 v[52:53], v[18:19], 2, v[2:3]
	v_lshlrev_b64 v[18:19], 13, v[20:21]
	v_or_b32_e32 v24, 8, v20
	v_or_b32_e32 v26, 12, v20
	v_or_b32_e32 v28, 16, v20
	v_or_b32_e32 v30, 20, v20
	v_or_b32_e32 v32, 24, v20
	v_or_b32_e32 v34, 28, v20
	v_or_b32_e32 v36, 32, v20
	v_or_b32_e32 v38, 36, v20
	v_or_b32_e32 v40, 40, v20
	v_or_b32_e32 v42, 44, v20
	v_or_b32_e32 v44, 48, v20
	v_or_b32_e32 v46, 52, v20
	v_or_b32_e32 v48, 56, v20
	v_or_b32_e32 v50, 60, v20
	v_ashrrev_i32_e32 v23, 31, v22
	v_ashrrev_i32_e32 v17, 31, v16
	v_lshl_add_u64 v[18:19], v[52:53], 0, v[18:19]
	v_ashrrev_i32_e32 v25, 31, v24
	v_ashrrev_i32_e32 v27, 31, v26
	v_ashrrev_i32_e32 v29, 31, v28
	v_ashrrev_i32_e32 v31, 31, v30
	v_ashrrev_i32_e32 v33, 31, v32
	v_ashrrev_i32_e32 v35, 31, v34
	v_ashrrev_i32_e32 v37, 31, v36
	v_ashrrev_i32_e32 v39, 31, v38
	v_ashrrev_i32_e32 v41, 31, v40
	v_ashrrev_i32_e32 v43, 31, v42
	v_ashrrev_i32_e32 v45, 31, v44
	v_ashrrev_i32_e32 v47, 31, v46
	v_ashrrev_i32_e32 v49, 31, v48
	v_ashrrev_i32_e32 v51, 31, v50
	v_add_u32_e32 v20, 8, v16
	v_add_u32_e32 v54, 16, v16
	v_add_u32_e32 v56, 24, v16
	v_add_u32_e32 v58, 32, v16
	v_add_u32_e32 v60, 40, v16
	v_add_u32_e32 v62, 48, v16
	v_add_u32_e32 v64, 56, v16
	v_lshlrev_b64 v[22:23], 13, v[22:23]
	v_lshlrev_b64 v[66:67], 14, v[16:17]
	global_load_dwordx4 v[16:19], v[18:19], off nt
	v_lshlrev_b64 v[24:25], 13, v[24:25]
	v_lshlrev_b64 v[26:27], 13, v[26:27]
	v_lshlrev_b64 v[28:29], 13, v[28:29]
	v_lshlrev_b64 v[30:31], 13, v[30:31]
	v_lshlrev_b64 v[32:33], 13, v[32:33]
	v_lshlrev_b64 v[34:35], 13, v[34:35]
	v_lshlrev_b64 v[36:37], 13, v[36:37]
	v_lshlrev_b64 v[38:39], 13, v[38:39]
	v_lshlrev_b64 v[40:41], 13, v[40:41]
	v_lshlrev_b64 v[42:43], 13, v[42:43]
	v_lshlrev_b64 v[44:45], 13, v[44:45]
	v_lshlrev_b64 v[46:47], 13, v[46:47]
	v_lshlrev_b64 v[48:49], 13, v[48:49]
	v_lshlrev_b64 v[50:51], 13, v[50:51]
	v_ashrrev_i32_e32 v21, 31, v20
	v_ashrrev_i32_e32 v55, 31, v54
	v_ashrrev_i32_e32 v57, 31, v56
	v_ashrrev_i32_e32 v59, 31, v58
	v_ashrrev_i32_e32 v61, 31, v60
	v_ashrrev_i32_e32 v63, 31, v62
	v_ashrrev_i32_e32 v65, 31, v64
	v_lshl_add_u64 v[82:83], v[52:53], 0, v[22:23]
	v_lshl_add_u64 v[84:85], v[52:53], 0, v[24:25]
	v_lshl_add_u64 v[86:87], v[52:53], 0, v[26:27]
	v_lshl_add_u64 v[88:89], v[52:53], 0, v[28:29]
	v_lshl_add_u64 v[90:91], v[52:53], 0, v[30:31]
	v_lshl_add_u64 v[92:93], v[52:53], 0, v[32:33]
	v_lshl_add_u64 v[94:95], v[52:53], 0, v[34:35]
	v_lshl_add_u64 v[96:97], v[52:53], 0, v[36:37]
	v_lshl_add_u64 v[98:99], v[52:53], 0, v[38:39]
	v_lshl_add_u64 v[100:101], v[52:53], 0, v[40:41]
	v_lshl_add_u64 v[102:103], v[52:53], 0, v[42:43]
	v_lshl_add_u64 v[104:105], v[52:53], 0, v[44:45]
	v_lshl_add_u64 v[106:107], v[52:53], 0, v[46:47]
	v_lshl_add_u64 v[108:109], v[52:53], 0, v[48:49]
	v_lshl_add_u64 v[110:111], v[52:53], 0, v[50:51]
	v_lshl_add_u64 v[112:113], v[80:81], 0, v[66:67]
	v_lshlrev_b64 v[114:115], 14, v[20:21]
	v_lshlrev_b64 v[116:117], 14, v[54:55]
	v_lshlrev_b64 v[118:119], 14, v[56:57]
	v_lshlrev_b64 v[120:121], 14, v[58:59]
	v_lshlrev_b64 v[122:123], 14, v[60:61]
	v_lshlrev_b64 v[124:125], 14, v[62:63]
	v_lshlrev_b64 v[126:127], 14, v[64:65]
	global_load_dwordx4 v[20:23], v[82:83], off nt
	global_load_dwordx4 v[24:27], v[84:85], off nt
	global_load_dwordx4 v[28:31], v[86:87], off nt
	global_load_dwordx4 v[32:35], v[88:89], off nt
	global_load_dwordx4 v[36:39], v[90:91], off nt
	global_load_dwordx4 v[40:43], v[92:93], off nt
	global_load_dwordx4 v[44:47], v[94:95], off nt
	global_load_dwordx4 v[48:51], v[96:97], off nt
	global_load_dwordx4 v[52:55], v[98:99], off nt
	global_load_dwordx4 v[56:59], v[100:101], off nt
	global_load_dwordx4 v[60:63], v[102:103], off nt
	global_load_dwordx4 v[64:67], v[104:105], off nt
	global_load_dwordx4 v[68:71], v[106:107], off nt
	global_load_dwordx4 v[72:75], v[108:109], off nt
	global_load_dwordx4 v[76:79], v[110:111], off nt
	v_lshl_add_u64 v[82:83], v[80:81], 0, v[114:115]
	v_lshl_add_u64 v[84:85], v[80:81], 0, v[116:117]
	v_lshl_add_u64 v[86:87], v[80:81], 0, v[118:119]
	v_lshl_add_u64 v[88:89], v[80:81], 0, v[120:121]
	v_lshl_add_u64 v[90:91], v[80:81], 0, v[122:123]
	v_lshl_add_u64 v[92:93], v[80:81], 0, v[124:125]
	v_lshl_add_u64 v[80:81], v[80:81], 0, v[126:127]
	v_add_u32_e32 v1, s94, v1
	v_cmp_lt_i32_e32 vcc, s5, v1
	s_or_b64 s[8:9], vcc, s[8:9]
	v_add_u32_e32 v9, s4, v9
	s_waitcnt vmcnt(15)
	v_cvt_pk_bf16_f32 v15, v16, s0
	v_cvt_pk_bf16_f32 v16, v17, s0
	v_cvt_pk_bf16_f32 v17, v18, s0
	v_cvt_pk_bf16_f32 v18, v19, s0
	ds_write_b16 v8, v15
	ds_write_b16 v8, v16 offset:144
	ds_write_b16 v8, v17 offset:288
	ds_write_b16 v8, v18 offset:432
	s_waitcnt vmcnt(14)
	v_cvt_pk_bf16_f32 v15, v20, s0
	v_cvt_pk_bf16_f32 v16, v21, s0
	v_cvt_pk_bf16_f32 v17, v22, s0
	v_cvt_pk_bf16_f32 v18, v23, s0
	s_waitcnt vmcnt(13)
	v_cvt_pk_bf16_f32 v19, v24, s0
	v_cvt_pk_bf16_f32 v20, v25, s0
	v_cvt_pk_bf16_f32 v21, v26, s0
	v_cvt_pk_bf16_f32 v22, v27, s0
	s_waitcnt vmcnt(12)
	v_cvt_pk_bf16_f32 v23, v28, s0
	v_cvt_pk_bf16_f32 v24, v29, s0
	v_cvt_pk_bf16_f32 v25, v30, s0
	v_cvt_pk_bf16_f32 v26, v31, s0
	s_waitcnt vmcnt(11)
	v_cvt_pk_bf16_f32 v27, v32, s0
	v_cvt_pk_bf16_f32 v28, v33, s0
	v_cvt_pk_bf16_f32 v29, v34, s0
	v_cvt_pk_bf16_f32 v30, v35, s0
	s_waitcnt vmcnt(10)
	v_cvt_pk_bf16_f32 v31, v36, s0
	v_cvt_pk_bf16_f32 v32, v37, s0
	v_cvt_pk_bf16_f32 v33, v38, s0
	v_cvt_pk_bf16_f32 v34, v39, s0
	s_waitcnt vmcnt(9)
	v_cvt_pk_bf16_f32 v35, v40, s0
	v_cvt_pk_bf16_f32 v36, v41, s0
	v_cvt_pk_bf16_f32 v37, v42, s0
	v_cvt_pk_bf16_f32 v38, v43, s0
	s_waitcnt vmcnt(8)
	v_cvt_pk_bf16_f32 v39, v44, s0
	v_cvt_pk_bf16_f32 v40, v45, s0
	v_cvt_pk_bf16_f32 v41, v46, s0
	v_cvt_pk_bf16_f32 v42, v47, s0
	s_waitcnt vmcnt(7)
	v_cvt_pk_bf16_f32 v43, v48, s0
	v_cvt_pk_bf16_f32 v44, v49, s0
	v_cvt_pk_bf16_f32 v45, v50, s0
	v_cvt_pk_bf16_f32 v46, v51, s0
	s_waitcnt vmcnt(6)
	v_cvt_pk_bf16_f32 v47, v52, s0
	v_cvt_pk_bf16_f32 v48, v53, s0
	v_cvt_pk_bf16_f32 v49, v54, s0
	v_cvt_pk_bf16_f32 v50, v55, s0
	s_waitcnt vmcnt(5)
	v_cvt_pk_bf16_f32 v51, v56, s0
	v_cvt_pk_bf16_f32 v52, v57, s0
	v_cvt_pk_bf16_f32 v53, v58, s0
	v_cvt_pk_bf16_f32 v54, v59, s0
	s_waitcnt vmcnt(4)
	v_cvt_pk_bf16_f32 v55, v60, s0
	v_cvt_pk_bf16_f32 v56, v61, s0
	v_cvt_pk_bf16_f32 v57, v62, s0
	v_cvt_pk_bf16_f32 v58, v63, s0
	s_waitcnt vmcnt(3)
	v_cvt_pk_bf16_f32 v59, v64, s0
	v_cvt_pk_bf16_f32 v60, v65, s0
	v_cvt_pk_bf16_f32 v61, v66, s0
	v_cvt_pk_bf16_f32 v62, v67, s0
	s_waitcnt vmcnt(2)
	v_cvt_pk_bf16_f32 v63, v68, s0
	v_cvt_pk_bf16_f32 v64, v69, s0
	v_cvt_pk_bf16_f32 v65, v70, s0
	v_cvt_pk_bf16_f32 v66, v71, s0
	s_waitcnt vmcnt(1)
	v_cvt_pk_bf16_f32 v67, v72, s0
	v_cvt_pk_bf16_f32 v68, v73, s0
	v_cvt_pk_bf16_f32 v69, v74, s0
	v_cvt_pk_bf16_f32 v70, v75, s0
	s_waitcnt vmcnt(0)
	v_cvt_pk_bf16_f32 v71, v76, s0
	v_cvt_pk_bf16_f32 v72, v77, s0
	v_cvt_pk_bf16_f32 v73, v78, s0
	v_cvt_pk_bf16_f32 v74, v79, s0
	ds_write_b16 v8, v15 offset:8
	ds_write_b16 v8, v16 offset:152
	ds_write_b16 v8, v17 offset:296
	ds_write_b16 v8, v18 offset:440
	ds_write_b16 v8, v19 offset:16
	ds_write_b16 v8, v20 offset:160
	ds_write_b16 v8, v21 offset:304
	ds_write_b16 v8, v22 offset:448
	ds_write_b16 v8, v23 offset:24
	ds_write_b16 v8, v24 offset:168
	ds_write_b16 v8, v25 offset:312
	ds_write_b16 v8, v26 offset:456
	ds_write_b16 v8, v27 offset:32
	ds_write_b16 v8, v28 offset:176
	ds_write_b16 v8, v29 offset:320
	ds_write_b16 v8, v30 offset:464
	ds_write_b16 v8, v31 offset:40
	ds_write_b16 v8, v32 offset:184
	ds_write_b16 v8, v33 offset:328
	ds_write_b16 v8, v34 offset:472
	ds_write_b16 v8, v35 offset:48
	ds_write_b16 v8, v36 offset:192
	ds_write_b16 v8, v37 offset:336
	ds_write_b16 v8, v38 offset:480
	ds_write_b16 v8, v39 offset:56
	ds_write_b16 v8, v40 offset:200
	ds_write_b16 v8, v41 offset:344
	ds_write_b16 v8, v42 offset:488
	ds_write_b16 v8, v43 offset:64
	ds_write_b16 v8, v44 offset:208
	ds_write_b16 v8, v45 offset:352
	ds_write_b16 v8, v46 offset:496
	ds_write_b16 v8, v47 offset:72
	ds_write_b16 v8, v48 offset:216
	ds_write_b16 v8, v49 offset:360
	ds_write_b16 v8, v50 offset:504
	ds_write_b16 v8, v51 offset:80
	ds_write_b16 v8, v52 offset:224
	ds_write_b16 v8, v53 offset:368
	ds_write_b16 v8, v54 offset:512
	ds_write_b16 v8, v55 offset:88
	ds_write_b16 v8, v56 offset:232
	ds_write_b16 v8, v57 offset:376
	ds_write_b16 v8, v58 offset:520
	ds_write_b16 v8, v59 offset:96
	ds_write_b16 v8, v60 offset:240
	ds_write_b16 v8, v61 offset:384
	ds_write_b16 v8, v62 offset:528
	ds_write_b16 v8, v63 offset:104
	ds_write_b16 v8, v64 offset:248
	ds_write_b16 v8, v65 offset:392
	ds_write_b16 v8, v66 offset:536
	ds_write_b16 v8, v67 offset:112
	ds_write_b16 v8, v68 offset:256
	ds_write_b16 v8, v69 offset:400
	ds_write_b16 v8, v70 offset:544
	ds_write_b16 v8, v71 offset:120
	ds_write_b16 v8, v72 offset:264
	ds_write_b16 v8, v73 offset:408
	ds_write_b16 v8, v74 offset:552
	s_waitcnt lgkmcnt(0)
	ds_read_b128 v[16:19], v13
	ds_read_b128 v[20:23], v14
	ds_read_b128 v[24:27], v14 offset:1152
	ds_read_b128 v[28:31], v14 offset:2304
	ds_read_b128 v[32:35], v14 offset:3456
	ds_read_b128 v[36:39], v14 offset:4608
	ds_read_b128 v[40:43], v14 offset:5760
	ds_read_b128 v[44:47], v14 offset:6912
	s_waitcnt lgkmcnt(7)
	global_store_dwordx4 v[112:113], v[16:19], off
	s_waitcnt lgkmcnt(6)
	global_store_dwordx4 v[82:83], v[20:23], off
	s_waitcnt lgkmcnt(5)
	global_store_dwordx4 v[84:85], v[24:27], off
	s_waitcnt lgkmcnt(4)
	global_store_dwordx4 v[86:87], v[28:31], off
	s_waitcnt lgkmcnt(3)
	global_store_dwordx4 v[88:89], v[32:35], off
	s_waitcnt lgkmcnt(2)
	global_store_dwordx4 v[90:91], v[36:39], off
	s_waitcnt lgkmcnt(1)
	global_store_dwordx4 v[92:93], v[40:43], off
	s_waitcnt lgkmcnt(0)
	global_store_dwordx4 v[80:81], v[44:47], off
	s_waitcnt lgkmcnt(0)
	s_andn2_b64 exec, exec, s[8:9]
	s_cbranch_execnz .LBB0_26

.LBB0_29:
	v_ashrrev_i32_e32 v15, 31, v1
	v_lshrrev_b32_e32 v15, 27, v15
	v_add_u32_e32 v15, v1, v15
	v_ashrrev_i32_e32 v15, 5, v15
	v_lshlrev_b32_e32 v16, 6, v15
	v_lshlrev_b32_e32 v15, 11, v15
	v_sub_u32_e32 v18, v9, v15
	v_or_b32_e32 v20, v16, v6
	v_ashrrev_i32_e32 v17, 31, v16
	v_ashrrev_i32_e32 v19, 31, v18
	v_ashrrev_i32_e32 v21, 31, v20
	v_or_b32_e32 v22, 4, v20
	v_lshl_add_u64 v[80:81], v[16:17], 1, v[4:5]
	v_add_u32_e32 v16, v18, v7
	v_lshl_add_u64 v[52:53], v[18:19], 2, v[2:3]
	v_lshlrev_b64 v[18:19], 13, v[20:21]
	v_or_b32_e32 v24, 8, v20
	v_or_b32_e32 v26, 12, v20
	v_or_b32_e32 v28, 16, v20
	v_or_b32_e32 v30, 20, v20
	v_or_b32_e32 v32, 24, v20
	v_or_b32_e32 v34, 28, v20
	v_or_b32_e32 v36, 32, v20
	v_or_b32_e32 v38, 36, v20
	v_or_b32_e32 v40, 40, v20
	v_or_b32_e32 v42, 44, v20
	v_or_b32_e32 v44, 48, v20
	v_or_b32_e32 v46, 52, v20
	v_or_b32_e32 v48, 56, v20
	v_or_b32_e32 v50, 60, v20
	v_ashrrev_i32_e32 v23, 31, v22
	v_ashrrev_i32_e32 v17, 31, v16
	v_lshl_add_u64 v[18:19], v[52:53], 0, v[18:19]
	v_ashrrev_i32_e32 v25, 31, v24
	v_ashrrev_i32_e32 v27, 31, v26
	v_ashrrev_i32_e32 v29, 31, v28
	v_ashrrev_i32_e32 v31, 31, v30
	v_ashrrev_i32_e32 v33, 31, v32
	v_ashrrev_i32_e32 v35, 31, v34
	v_ashrrev_i32_e32 v37, 31, v36
	v_ashrrev_i32_e32 v39, 31, v38
	v_ashrrev_i32_e32 v41, 31, v40
	v_ashrrev_i32_e32 v43, 31, v42
	v_ashrrev_i32_e32 v45, 31, v44
	v_ashrrev_i32_e32 v47, 31, v46
	v_ashrrev_i32_e32 v49, 31, v48
	v_ashrrev_i32_e32 v51, 31, v50
	v_add_u32_e32 v20, 8, v16
	v_add_u32_e32 v54, 16, v16
	v_add_u32_e32 v56, 24, v16
	v_add_u32_e32 v58, 32, v16
	v_add_u32_e32 v60, 40, v16
	v_add_u32_e32 v62, 48, v16
	v_add_u32_e32 v64, 56, v16
	v_lshlrev_b64 v[22:23], 13, v[22:23]
	v_lshlrev_b64 v[66:67], 14, v[16:17]
	global_load_dwordx4 v[16:19], v[18:19], off nt
	v_lshlrev_b64 v[24:25], 13, v[24:25]
	v_lshlrev_b64 v[26:27], 13, v[26:27]
	v_lshlrev_b64 v[28:29], 13, v[28:29]
	v_lshlrev_b64 v[30:31], 13, v[30:31]
	v_lshlrev_b64 v[32:33], 13, v[32:33]
	v_lshlrev_b64 v[34:35], 13, v[34:35]
	v_lshlrev_b64 v[36:37], 13, v[36:37]
	v_lshlrev_b64 v[38:39], 13, v[38:39]
	v_lshlrev_b64 v[40:41], 13, v[40:41]
	v_lshlrev_b64 v[42:43], 13, v[42:43]
	v_lshlrev_b64 v[44:45], 13, v[44:45]
	v_lshlrev_b64 v[46:47], 13, v[46:47]
	v_lshlrev_b64 v[48:49], 13, v[48:49]
	v_lshlrev_b64 v[50:51], 13, v[50:51]
	v_ashrrev_i32_e32 v21, 31, v20
	v_ashrrev_i32_e32 v55, 31, v54
	v_ashrrev_i32_e32 v57, 31, v56
	v_ashrrev_i32_e32 v59, 31, v58
	v_ashrrev_i32_e32 v61, 31, v60
	v_ashrrev_i32_e32 v63, 31, v62
	v_ashrrev_i32_e32 v65, 31, v64
	v_lshl_add_u64 v[82:83], v[52:53], 0, v[22:23]
	v_lshl_add_u64 v[84:85], v[52:53], 0, v[24:25]
	v_lshl_add_u64 v[86:87], v[52:53], 0, v[26:27]
	v_lshl_add_u64 v[88:89], v[52:53], 0, v[28:29]
	v_lshl_add_u64 v[90:91], v[52:53], 0, v[30:31]
	v_lshl_add_u64 v[92:93], v[52:53], 0, v[32:33]
	v_lshl_add_u64 v[94:95], v[52:53], 0, v[34:35]
	v_lshl_add_u64 v[96:97], v[52:53], 0, v[36:37]
	v_lshl_add_u64 v[98:99], v[52:53], 0, v[38:39]
	v_lshl_add_u64 v[100:101], v[52:53], 0, v[40:41]
	v_lshl_add_u64 v[102:103], v[52:53], 0, v[42:43]
	v_lshl_add_u64 v[104:105], v[52:53], 0, v[44:45]
	v_lshl_add_u64 v[106:107], v[52:53], 0, v[46:47]
	v_lshl_add_u64 v[108:109], v[52:53], 0, v[48:49]
	v_lshl_add_u64 v[110:111], v[52:53], 0, v[50:51]
	v_lshl_add_u64 v[112:113], v[80:81], 0, v[66:67]
	v_lshlrev_b64 v[114:115], 14, v[20:21]
	v_lshlrev_b64 v[116:117], 14, v[54:55]
	v_lshlrev_b64 v[118:119], 14, v[56:57]
	v_lshlrev_b64 v[120:121], 14, v[58:59]
	v_lshlrev_b64 v[122:123], 14, v[60:61]
	v_lshlrev_b64 v[124:125], 14, v[62:63]
	v_lshlrev_b64 v[126:127], 14, v[64:65]
	global_load_dwordx4 v[20:23], v[82:83], off nt
	global_load_dwordx4 v[24:27], v[84:85], off nt
	global_load_dwordx4 v[28:31], v[86:87], off nt
	global_load_dwordx4 v[32:35], v[88:89], off nt
	global_load_dwordx4 v[36:39], v[90:91], off nt
	global_load_dwordx4 v[40:43], v[92:93], off nt
	global_load_dwordx4 v[44:47], v[94:95], off nt
	global_load_dwordx4 v[48:51], v[96:97], off nt
	global_load_dwordx4 v[52:55], v[98:99], off nt
	global_load_dwordx4 v[56:59], v[100:101], off nt
	global_load_dwordx4 v[60:63], v[102:103], off nt
	global_load_dwordx4 v[64:67], v[104:105], off nt
	global_load_dwordx4 v[68:71], v[106:107], off nt
	global_load_dwordx4 v[72:75], v[108:109], off nt
	global_load_dwordx4 v[76:79], v[110:111], off nt
	v_lshl_add_u64 v[82:83], v[80:81], 0, v[114:115]
	v_lshl_add_u64 v[84:85], v[80:81], 0, v[116:117]
	v_lshl_add_u64 v[86:87], v[80:81], 0, v[118:119]
	v_lshl_add_u64 v[88:89], v[80:81], 0, v[120:121]
	v_lshl_add_u64 v[90:91], v[80:81], 0, v[122:123]
	v_lshl_add_u64 v[92:93], v[80:81], 0, v[124:125]
	v_lshl_add_u64 v[80:81], v[80:81], 0, v[126:127]
	v_add_u32_e32 v1, s94, v1
	v_cmp_lt_i32_e32 vcc, s5, v1
	s_or_b64 s[2:3], vcc, s[2:3]
	v_add_u32_e32 v9, s4, v9
	s_waitcnt vmcnt(15)
	v_cvt_pk_bf16_f32 v15, v16, s0
	v_cvt_pk_bf16_f32 v16, v17, s0
	v_cvt_pk_bf16_f32 v17, v18, s0
	v_cvt_pk_bf16_f32 v18, v19, s0
	ds_write_b16 v8, v15
	ds_write_b16 v8, v16 offset:144
	ds_write_b16 v8, v17 offset:288
	ds_write_b16 v8, v18 offset:432
	s_waitcnt vmcnt(14)
	v_cvt_pk_bf16_f32 v15, v20, s0
	v_cvt_pk_bf16_f32 v16, v21, s0
	v_cvt_pk_bf16_f32 v17, v22, s0
	v_cvt_pk_bf16_f32 v18, v23, s0
	s_waitcnt vmcnt(13)
	v_cvt_pk_bf16_f32 v19, v24, s0
	v_cvt_pk_bf16_f32 v20, v25, s0
	v_cvt_pk_bf16_f32 v21, v26, s0
	v_cvt_pk_bf16_f32 v22, v27, s0
	s_waitcnt vmcnt(12)
	v_cvt_pk_bf16_f32 v23, v28, s0
	v_cvt_pk_bf16_f32 v24, v29, s0
	v_cvt_pk_bf16_f32 v25, v30, s0
	v_cvt_pk_bf16_f32 v26, v31, s0
	s_waitcnt vmcnt(11)
	v_cvt_pk_bf16_f32 v27, v32, s0
	v_cvt_pk_bf16_f32 v28, v33, s0
	v_cvt_pk_bf16_f32 v29, v34, s0
	v_cvt_pk_bf16_f32 v30, v35, s0
	s_waitcnt vmcnt(10)
	v_cvt_pk_bf16_f32 v31, v36, s0
	v_cvt_pk_bf16_f32 v32, v37, s0
	v_cvt_pk_bf16_f32 v33, v38, s0
	v_cvt_pk_bf16_f32 v34, v39, s0
	s_waitcnt vmcnt(9)
	v_cvt_pk_bf16_f32 v35, v40, s0
	v_cvt_pk_bf16_f32 v36, v41, s0
	v_cvt_pk_bf16_f32 v37, v42, s0
	v_cvt_pk_bf16_f32 v38, v43, s0
	s_waitcnt vmcnt(8)
	v_cvt_pk_bf16_f32 v39, v44, s0
	v_cvt_pk_bf16_f32 v40, v45, s0
	v_cvt_pk_bf16_f32 v41, v46, s0
	v_cvt_pk_bf16_f32 v42, v47, s0
	s_waitcnt vmcnt(7)
	v_cvt_pk_bf16_f32 v43, v48, s0
	v_cvt_pk_bf16_f32 v44, v49, s0
	v_cvt_pk_bf16_f32 v45, v50, s0
	v_cvt_pk_bf16_f32 v46, v51, s0
	s_waitcnt vmcnt(6)
	v_cvt_pk_bf16_f32 v47, v52, s0
	v_cvt_pk_bf16_f32 v48, v53, s0
	v_cvt_pk_bf16_f32 v49, v54, s0
	v_cvt_pk_bf16_f32 v50, v55, s0
	s_waitcnt vmcnt(5)
	v_cvt_pk_bf16_f32 v51, v56, s0
	v_cvt_pk_bf16_f32 v52, v57, s0
	v_cvt_pk_bf16_f32 v53, v58, s0
	v_cvt_pk_bf16_f32 v54, v59, s0
	s_waitcnt vmcnt(4)
	v_cvt_pk_bf16_f32 v55, v60, s0
	v_cvt_pk_bf16_f32 v56, v61, s0
	v_cvt_pk_bf16_f32 v57, v62, s0
	v_cvt_pk_bf16_f32 v58, v63, s0
	s_waitcnt vmcnt(3)
	v_cvt_pk_bf16_f32 v59, v64, s0
	v_cvt_pk_bf16_f32 v60, v65, s0
	v_cvt_pk_bf16_f32 v61, v66, s0
	v_cvt_pk_bf16_f32 v62, v67, s0
	s_waitcnt vmcnt(2)
	v_cvt_pk_bf16_f32 v63, v68, s0
	v_cvt_pk_bf16_f32 v64, v69, s0
	v_cvt_pk_bf16_f32 v65, v70, s0
	v_cvt_pk_bf16_f32 v66, v71, s0
	s_waitcnt vmcnt(1)
	v_cvt_pk_bf16_f32 v67, v72, s0
	v_cvt_pk_bf16_f32 v68, v73, s0
	v_cvt_pk_bf16_f32 v69, v74, s0
	v_cvt_pk_bf16_f32 v70, v75, s0
	s_waitcnt vmcnt(0)
	v_cvt_pk_bf16_f32 v71, v76, s0
	v_cvt_pk_bf16_f32 v72, v77, s0
	v_cvt_pk_bf16_f32 v73, v78, s0
	v_cvt_pk_bf16_f32 v74, v79, s0
	ds_write_b16 v8, v15 offset:8
	ds_write_b16 v8, v16 offset:152
	ds_write_b16 v8, v17 offset:296
	ds_write_b16 v8, v18 offset:440
	ds_write_b16 v8, v19 offset:16
	ds_write_b16 v8, v20 offset:160
	ds_write_b16 v8, v21 offset:304
	ds_write_b16 v8, v22 offset:448
	ds_write_b16 v8, v23 offset:24
	ds_write_b16 v8, v24 offset:168
	ds_write_b16 v8, v25 offset:312
	ds_write_b16 v8, v26 offset:456
	ds_write_b16 v8, v27 offset:32
	ds_write_b16 v8, v28 offset:176
	ds_write_b16 v8, v29 offset:320
	ds_write_b16 v8, v30 offset:464
	ds_write_b16 v8, v31 offset:40
	ds_write_b16 v8, v32 offset:184
	ds_write_b16 v8, v33 offset:328
	ds_write_b16 v8, v34 offset:472
	ds_write_b16 v8, v35 offset:48
	ds_write_b16 v8, v36 offset:192
	ds_write_b16 v8, v37 offset:336
	ds_write_b16 v8, v38 offset:480
	ds_write_b16 v8, v39 offset:56
	ds_write_b16 v8, v40 offset:200
	ds_write_b16 v8, v41 offset:344
	ds_write_b16 v8, v42 offset:488
	ds_write_b16 v8, v43 offset:64
	ds_write_b16 v8, v44 offset:208
	ds_write_b16 v8, v45 offset:352
	ds_write_b16 v8, v46 offset:496
	ds_write_b16 v8, v47 offset:72
	ds_write_b16 v8, v48 offset:216
	ds_write_b16 v8, v49 offset:360
	ds_write_b16 v8, v50 offset:504
	ds_write_b16 v8, v51 offset:80
	ds_write_b16 v8, v52 offset:224
	ds_write_b16 v8, v53 offset:368
	ds_write_b16 v8, v54 offset:512
	ds_write_b16 v8, v55 offset:88
	ds_write_b16 v8, v56 offset:232
	ds_write_b16 v8, v57 offset:376
	ds_write_b16 v8, v58 offset:520
	ds_write_b16 v8, v59 offset:96
	ds_write_b16 v8, v60 offset:240
	ds_write_b16 v8, v61 offset:384
	ds_write_b16 v8, v62 offset:528
	ds_write_b16 v8, v63 offset:104
	ds_write_b16 v8, v64 offset:248
	ds_write_b16 v8, v65 offset:392
	ds_write_b16 v8, v66 offset:536
	ds_write_b16 v8, v67 offset:112
	ds_write_b16 v8, v68 offset:256
	ds_write_b16 v8, v69 offset:400
	ds_write_b16 v8, v70 offset:544
	ds_write_b16 v8, v71 offset:120
	ds_write_b16 v8, v72 offset:264
	ds_write_b16 v8, v73 offset:408
	ds_write_b16 v8, v74 offset:552
	s_waitcnt lgkmcnt(0)
	ds_read_b128 v[16:19], v13
	ds_read_b128 v[20:23], v14
	ds_read_b128 v[24:27], v14 offset:1152
	ds_read_b128 v[28:31], v14 offset:2304
	ds_read_b128 v[32:35], v14 offset:3456
	ds_read_b128 v[36:39], v14 offset:4608
	ds_read_b128 v[40:43], v14 offset:5760
	ds_read_b128 v[44:47], v14 offset:6912
	s_waitcnt lgkmcnt(7)
	global_store_dwordx4 v[112:113], v[16:19], off
	s_waitcnt lgkmcnt(6)
	global_store_dwordx4 v[82:83], v[20:23], off
	s_waitcnt lgkmcnt(5)
	global_store_dwordx4 v[84:85], v[24:27], off
	s_waitcnt lgkmcnt(4)
	global_store_dwordx4 v[86:87], v[28:31], off
	s_waitcnt lgkmcnt(3)
	global_store_dwordx4 v[88:89], v[32:35], off
	s_waitcnt lgkmcnt(2)
	global_store_dwordx4 v[90:91], v[36:39], off
	s_waitcnt lgkmcnt(1)
	global_store_dwordx4 v[92:93], v[40:43], off
	s_waitcnt lgkmcnt(0)
	global_store_dwordx4 v[80:81], v[44:47], off
	s_waitcnt lgkmcnt(0)
	s_andn2_b64 exec, exec, s[2:3]
	s_cbranch_execnz .LBB0_29

.LBB0_102:
	v_lshl_add_u64 v[24:25], v[12:13], 0, s[8:9]
	v_add_co_u32_e64 v26, s[2:3], s4, v24
	global_load_dword v64, v[24:25], off nt
	s_nop 0
	v_addc_co_u32_e64 v27, s[2:3], 0, v25, s[2:3]
	v_add_co_u32_e64 v28, s[2:3], s5, v24
	s_add_u32 s8, s8, 0x60000
	s_nop 0
	v_addc_co_u32_e64 v29, s[2:3], 0, v25, s[2:3]
	v_add_co_u32_e64 v30, s[2:3], s12, v24
	s_addc_u32 s9, s9, 0
	s_nop 0
	v_addc_co_u32_e64 v31, s[2:3], 0, v25, s[2:3]
	v_add_co_u32_e64 v32, s[2:3], s13, v24
	s_cmp_eq_u32 s8, 0xc00000
	s_nop 0
	v_addc_co_u32_e64 v33, s[2:3], 0, v25, s[2:3]
	v_add_co_u32_e64 v34, s[2:3], s17, v24
	s_nop 1
	v_addc_co_u32_e64 v35, s[2:3], 0, v25, s[2:3]
	v_add_co_u32_e64 v36, s[2:3], s18, v24
	s_nop 1
	v_addc_co_u32_e64 v37, s[2:3], 0, v25, s[2:3]
	v_add_co_u32_e64 v24, s[2:3], s19, v24
	s_nop 1
	v_addc_co_u32_e64 v25, s[2:3], 0, v25, s[2:3]
	global_load_dword v66, v[26:27], off nt
	global_load_dword v68, v[28:29], off nt
	global_load_dword v70, v[30:31], off nt
	global_load_dword v72, v[32:33], off nt
	global_load_dword v74, v[34:35], off nt
	global_load_dword v76, v[36:37], off nt
	global_load_dword v78, v[24:25], off nt
	ds_read_b128 v[24:27], v21
	ds_read_b128 v[28:31], v21 offset:16
	ds_read_b128 v[32:35], v21 offset:8192
	ds_read_b128 v[36:39], v21 offset:8208
	ds_read_b128 v[40:43], v21 offset:16384
	ds_read_b128 v[44:47], v21 offset:16400
	ds_read_b128 v[48:51], v21 offset:24576
	ds_read_b128 v[52:55], v21 offset:24592
	ds_read_b128 v[56:59], v21 offset:32768
	ds_read_b128 v[60:63], v21 offset:32784
	s_waitcnt lgkmcnt(5)
	v_mov_b32_e32 v80, v40
	v_mov_b32_e32 v81, v32
	s_waitcnt lgkmcnt(3)
	v_mov_b32_e32 v83, v48
	s_waitcnt lgkmcnt(1)
	v_mov_b32_e32 v82, v56
	v_mov_b32_e32 v32, v41
	v_mov_b32_e32 v48, v57
	v_mov_b32_e32 v40, v42
	v_mov_b32_e32 v41, v34
	v_mov_b32_e32 v56, v58
	v_mov_b32_e32 v57, v50
	v_mov_b32_e32 v34, v43
	v_mov_b32_e32 v50, v59
	v_mov_b32_e32 v42, v44
	v_mov_b32_e32 v43, v36
	s_waitcnt lgkmcnt(0)
	v_mov_b32_e32 v58, v60
	v_mov_b32_e32 v59, v52
	v_mov_b32_e32 v36, v45
	v_mov_b32_e32 v52, v61
	v_mov_b32_e32 v44, v46
	v_mov_b32_e32 v45, v38
	v_mov_b32_e32 v60, v62
	v_mov_b32_e32 v61, v54
	v_mov_b32_e32 v38, v47
	v_mov_b32_e32 v54, v63
	v_add_u32_e32 v21, 32, v21
	s_waitcnt vmcnt(7)
	v_fmac_f32_e32 v22, v64, v24
	v_pk_fma_f32 v[16:17], v[64:65], v[80:81], v[16:17] op_sel_hi:[0,1,1]
	v_pk_fma_f32 v[14:15], v[64:65], v[82:83], v[14:15] op_sel_hi:[0,1,1]
	s_waitcnt vmcnt(6)
	v_fmac_f32_e32 v22, v66, v25
	v_pk_fma_f32 v[16:17], v[66:67], v[32:33], v[16:17] op_sel_hi:[0,1,1]
	v_pk_fma_f32 v[14:15], v[66:67], v[48:49], v[14:15] op_sel_hi:[0,1,1]
	s_waitcnt vmcnt(5)
	v_fmac_f32_e32 v22, v68, v26
	v_pk_fma_f32 v[16:17], v[68:69], v[40:41], v[16:17] op_sel_hi:[0,1,1]
	v_pk_fma_f32 v[14:15], v[68:69], v[56:57], v[14:15] op_sel_hi:[0,1,1]
	s_waitcnt vmcnt(4)
	v_fmac_f32_e32 v22, v70, v27
	v_pk_fma_f32 v[16:17], v[70:71], v[34:35], v[16:17] op_sel_hi:[0,1,1]
	v_pk_fma_f32 v[14:15], v[70:71], v[50:51], v[14:15] op_sel_hi:[0,1,1]
	s_waitcnt vmcnt(3)
	v_fmac_f32_e32 v22, v72, v28
	v_pk_fma_f32 v[16:17], v[72:73], v[42:43], v[16:17] op_sel_hi:[0,1,1]
	v_pk_fma_f32 v[14:15], v[72:73], v[58:59], v[14:15] op_sel_hi:[0,1,1]
	s_waitcnt vmcnt(2)
	v_fmac_f32_e32 v22, v74, v29
	v_pk_fma_f32 v[16:17], v[74:75], v[36:37], v[16:17] op_sel_hi:[0,1,1]
	v_pk_fma_f32 v[14:15], v[74:75], v[52:53], v[14:15] op_sel_hi:[0,1,1]
	s_waitcnt vmcnt(1)
	v_fmac_f32_e32 v22, v76, v30
	v_pk_fma_f32 v[16:17], v[76:77], v[44:45], v[16:17] op_sel_hi:[0,1,1]
	v_pk_fma_f32 v[14:15], v[76:77], v[60:61], v[14:15] op_sel_hi:[0,1,1]
	s_waitcnt vmcnt(0)
	v_fmac_f32_e32 v22, v78, v31
	v_pk_fma_f32 v[16:17], v[78:79], v[38:39], v[16:17] op_sel_hi:[0,1,1]
	v_pk_fma_f32 v[14:15], v[78:79], v[54:55], v[14:15] op_sel_hi:[0,1,1]
	s_cbranch_scc0 .LBB0_102
	ds_write_b32 v18, v22 offset:40960
	ds_write2st64_b32 v19, v17, v16 offset0:161 offset1:162
	ds_write2st64_b32 v19, v15, v14 offset0:163 offset1:164
	s_waitcnt lgkmcnt(0)
	s_barrier
	s_and_saveexec_b64 s[2:3], vcc
	s_cbranch_execz .LBB0_100
	s_mul_i32 s8, s20, 0x3000
	s_add_i32 s8, s8, s6
	v_or_b32_e32 v12, s8, v4
	v_ashrrev_i32_e32 v13, 31, v12
	v_lshl_add_u64 v[12:13], v[12:13], 2, s[10:11]
	global_load_dword v21, v[12:13], off
	v_add_u32_e32 v24, v1, v5
	ds_read2st64_b32 v[14:15], v24 offset0:160 offset1:165
	ds_read2st64_b32 v[16:17], v24 offset0:170 offset1:175
	ds_read2st64_b32 v[22:23], v24 offset0:180 offset1:185
	ds_read2st64_b32 v[24:25], v24 offset0:190 offset1:195
	v_mad_i64_i32 v[12:13], s[8:9], s20, 5, v[6:7]
	v_mad_u64_u32 v[26:27], s[8:9], v12, s4, v[2:3]
	v_mad_i32_i24 v27, v13, s4, v27
	v_lshl_add_u64 v[12:13], s[6:7], 2, v[26:27]
	v_lshl_add_u64 v[12:13], v[12:13], 0, v[8:9]
	s_waitcnt vmcnt(0) lgkmcnt(3)
	v_add_f32_e32 v14, v21, v14
	v_add_f32_e32 v14, v14, v15
	s_waitcnt lgkmcnt(2)
	v_add_f32_e32 v14, v14, v16
	v_add_f32_e32 v14, v14, v17
	s_waitcnt lgkmcnt(1)
	v_add_f32_e32 v14, v14, v22
	v_add_f32_e32 v14, v14, v23
	s_waitcnt lgkmcnt(0)
	v_add_f32_e32 v14, v14, v24
	v_add_f32_e32 v14, v14, v25
	global_store_dword v[12:13], v14, off
	s_branch .LBB0_100

.Lrm0_loop:
	s_lshr_b32 s1, s5, 9
	s_lshl_b32 s1, s1, 13
	s_and_b32 s8, s5, 0x1ff
	s_add_u32 s1, s1, s8
	s_add_u32 s8, s0, 0
	s_lshl_b32 s8, s8, 9
	s_add_u32 s1, s1, s8
	s_lshl_b32 s8, s1, 13
	s_lshl_b32 s8, s1, 12
	s_add_u32 s9, s8, 0x2c800000
	s_add_u32 s10, s52, s9
	s_addc_u32 s11, s53, 0
	s_lshr_b32 s1, s5, 9
	s_lshl_b32 s1, s1, 13
	s_and_b32 s8, s5, 0x1ff
	s_add_u32 s1, s1, s8
	s_add_u32 s8, s0, 1
	s_lshl_b32 s8, s8, 9
	s_add_u32 s1, s1, s8
	s_lshl_b32 s8, s1, 13
	v_readfirstlane_b32 s6, v130
	v_readfirstlane_b32 s7, v131
	s_nop 3
	s_add_u32 s6, s6, s8
	s_addc_u32 s7, s7, 0
	s_nop 1
	global_load_dwordx4 v[136:139], v122, s[6:7] offset:0 nt
	global_load_dwordx4 v[140:143], v122, s[6:7] offset:1024 nt
	global_load_dwordx4 v[144:147], v122, s[6:7] offset:2048 nt
	global_load_dwordx4 v[148:151], v122, s[6:7] offset:3072 nt
	global_load_dwordx4 v[152:155], v123, s[6:7] offset:0 nt
	global_load_dwordx4 v[156:159], v123, s[6:7] offset:1024 nt
	global_load_dwordx4 v[160:163], v123, s[6:7] offset:2048 nt
	global_load_dwordx4 v[164:167], v123, s[6:7] offset:3072 nt
	s_waitcnt vmcnt(8)
	v_pk_mul_f32 v[108:109], v[0:1], v[0:1]
	v_pk_mul_f32 v[110:111], v[2:3], v[2:3]
	v_pk_fma_f32 v[108:109], v[4:5], v[4:5], v[108:109]
	v_pk_fma_f32 v[110:111], v[6:7], v[6:7], v[110:111]
	v_pk_fma_f32 v[108:109], v[8:9], v[8:9], v[108:109]
	v_pk_fma_f32 v[110:111], v[10:11], v[10:11], v[110:111]
	v_pk_fma_f32 v[108:109], v[12:13], v[12:13], v[108:109]
	v_pk_fma_f32 v[110:111], v[14:15], v[14:15], v[110:111]
	v_pk_fma_f32 v[108:109], v[16:17], v[16:17], v[108:109]
	v_pk_fma_f32 v[110:111], v[18:19], v[18:19], v[110:111]
	v_pk_fma_f32 v[108:109], v[20:21], v[20:21], v[108:109]
	v_pk_fma_f32 v[110:111], v[22:23], v[22:23], v[110:111]
	v_pk_fma_f32 v[108:109], v[24:25], v[24:25], v[108:109]
	v_pk_fma_f32 v[110:111], v[26:27], v[26:27], v[110:111]
	v_pk_fma_f32 v[108:109], v[28:29], v[28:29], v[108:109]
	v_pk_fma_f32 v[110:111], v[30:31], v[30:31], v[110:111]
	v_pk_add_f32 v[108:109], v[108:109], v[110:111]
	s_nop 0
	v_add_f32_e32 v128, v108, v109
	s_nop 1
	v_add_f32_dpp v128, v128, v128 quad_perm:[1,0,3,2] row_mask:0xf bank_mask:0xf
	s_nop 1
	v_add_f32_dpp v128, v128, v128 quad_perm:[2,3,0,1] row_mask:0xf bank_mask:0xf
	s_nop 1
	v_add_f32_dpp v128, v128, v128 row_half_mirror row_mask:0xf bank_mask:0xf
	s_nop 1
	v_add_f32_dpp v128, v128, v128 row_mirror row_mask:0xf bank_mask:0xf
	s_nop 1
	v_add_f32_dpp v128, v128, v128 row_bcast:15 row_mask:0xa bank_mask:0xf
	s_nop 1
	v_add_f32_dpp v128, v128, v128 row_bcast:31 row_mask:0xc bank_mask:0xf
	s_nop 1
	v_readlane_b32 s8, v128, 63
	s_nop 3
	v_mov_b32_e32 v112, s8
	v_fma_f32 v112, v112, v126, v127
	v_rsq_f32_e32 v112, v112
	s_nop 1
	v_pk_mul_f32 v[100:101], v[0:1], v[112:113] op_sel_hi:[1,0]
	v_pk_fma_f32 v[100:101], v[100:101], v[32:33], v[68:69]
	v_cvt_pk_bf16_f32 v114, v100, v101
	v_pk_mul_f32 v[102:103], v[2:3], v[112:113] op_sel_hi:[1,0]
	v_pk_fma_f32 v[102:103], v[102:103], v[34:35], v[70:71]
	v_cvt_pk_bf16_f32 v115, v102, v103
	global_store_dwordx2 v124, v[114:115], s[10:11] offset:0 nt
	v_pk_mul_f32 v[104:105], v[4:5], v[112:113] op_sel_hi:[1,0]
	v_pk_fma_f32 v[104:105], v[104:105], v[36:37], v[72:73]
	v_cvt_pk_bf16_f32 v116, v104, v105
	v_pk_mul_f32 v[106:107], v[6:7], v[112:113] op_sel_hi:[1,0]
	v_pk_fma_f32 v[106:107], v[106:107], v[38:39], v[74:75]
	v_cvt_pk_bf16_f32 v117, v106, v107
	global_store_dwordx2 v124, v[116:117], s[10:11] offset:512 nt
	v_pk_mul_f32 v[100:101], v[8:9], v[112:113] op_sel_hi:[1,0]
	v_pk_fma_f32 v[100:101], v[100:101], v[40:41], v[76:77]
	v_cvt_pk_bf16_f32 v118, v100, v101
	v_pk_mul_f32 v[102:103], v[10:11], v[112:113] op_sel_hi:[1,0]
	v_pk_fma_f32 v[102:103], v[102:103], v[42:43], v[78:79]
	v_cvt_pk_bf16_f32 v119, v102, v103
	global_store_dwordx2 v124, v[118:119], s[10:11] offset:1024 nt
	v_pk_mul_f32 v[104:105], v[12:13], v[112:113] op_sel_hi:[1,0]
	v_pk_fma_f32 v[104:105], v[104:105], v[44:45], v[80:81]
	v_cvt_pk_bf16_f32 v120, v104, v105
	v_pk_mul_f32 v[106:107], v[14:15], v[112:113] op_sel_hi:[1,0]
	v_pk_fma_f32 v[106:107], v[106:107], v[46:47], v[82:83]
	v_cvt_pk_bf16_f32 v121, v106, v107
	global_store_dwordx2 v124, v[120:121], s[10:11] offset:1536 nt
	v_pk_mul_f32 v[100:101], v[16:17], v[112:113] op_sel_hi:[1,0]
	v_pk_fma_f32 v[100:101], v[100:101], v[48:49], v[84:85]
	v_cvt_pk_bf16_f32 v114, v100, v101
	v_pk_mul_f32 v[102:103], v[18:19], v[112:113] op_sel_hi:[1,0]
	v_pk_fma_f32 v[102:103], v[102:103], v[50:51], v[86:87]
	v_cvt_pk_bf16_f32 v115, v102, v103
	global_store_dwordx2 v124, v[114:115], s[10:11] offset:2048 nt
	v_pk_mul_f32 v[104:105], v[20:21], v[112:113] op_sel_hi:[1,0]
	v_pk_fma_f32 v[104:105], v[104:105], v[56:57], v[88:89]
	v_cvt_pk_bf16_f32 v116, v104, v105
	v_pk_mul_f32 v[106:107], v[22:23], v[112:113] op_sel_hi:[1,0]
	v_pk_fma_f32 v[106:107], v[106:107], v[58:59], v[90:91]
	v_cvt_pk_bf16_f32 v117, v106, v107
	global_store_dwordx2 v124, v[116:117], s[10:11] offset:2560 nt
	v_pk_mul_f32 v[100:101], v[24:25], v[112:113] op_sel_hi:[1,0]
	v_pk_fma_f32 v[100:101], v[100:101], v[60:61], v[92:93]
	v_cvt_pk_bf16_f32 v118, v100, v101
	v_pk_mul_f32 v[102:103], v[26:27], v[112:113] op_sel_hi:[1,0]
	v_pk_fma_f32 v[102:103], v[102:103], v[62:63], v[94:95]
	v_cvt_pk_bf16_f32 v119, v102, v103
	global_store_dwordx2 v124, v[118:119], s[10:11] offset:3072 nt
	v_pk_mul_f32 v[104:105], v[28:29], v[112:113] op_sel_hi:[1,0]
	v_pk_fma_f32 v[104:105], v[104:105], v[64:65], v[96:97]
	v_cvt_pk_bf16_f32 v120, v104, v105
	v_pk_mul_f32 v[106:107], v[30:31], v[112:113] op_sel_hi:[1,0]
	v_pk_fma_f32 v[106:107], v[106:107], v[66:67], v[98:99]
	v_cvt_pk_bf16_f32 v121, v106, v107
	global_store_dwordx2 v124, v[120:121], s[10:11] offset:3584 nt
	s_lshr_b32 s1, s5, 9
	s_lshl_b32 s1, s1, 13
	s_and_b32 s8, s5, 0x1ff
	s_add_u32 s1, s1, s8
	s_add_u32 s8, s0, 1
	s_lshl_b32 s8, s8, 9
	s_add_u32 s1, s1, s8
	s_lshl_b32 s8, s1, 13
	s_lshl_b32 s8, s1, 12
	s_add_u32 s9, s8, 0x2c800000
	s_add_u32 s10, s52, s9
	s_addc_u32 s11, s53, 0
	s_cmp_lt_u32 s0, 14
	s_cbranch_scc0 .Lrm0_nopf_o
	s_lshr_b32 s1, s5, 9
	s_lshl_b32 s1, s1, 13
	s_and_b32 s8, s5, 0x1ff
	s_add_u32 s1, s1, s8
	s_add_u32 s8, s0, 2
	s_lshl_b32 s8, s8, 9
	s_add_u32 s1, s1, s8
	s_lshl_b32 s8, s1, 13
	v_readfirstlane_b32 s6, v130
	v_readfirstlane_b32 s7, v131
	s_nop 3
	s_add_u32 s6, s6, s8
	s_addc_u32 s7, s7, 0
	s_nop 1
	global_load_dwordx4 v[0:3], v122, s[6:7] offset:0 nt
	global_load_dwordx4 v[4:7], v122, s[6:7] offset:1024 nt
	global_load_dwordx4 v[8:11], v122, s[6:7] offset:2048 nt
	global_load_dwordx4 v[12:15], v122, s[6:7] offset:3072 nt
	global_load_dwordx4 v[16:19], v123, s[6:7] offset:0 nt
	global_load_dwordx4 v[20:23], v123, s[6:7] offset:1024 nt
	global_load_dwordx4 v[24:27], v123, s[6:7] offset:2048 nt
	global_load_dwordx4 v[28:31], v123, s[6:7] offset:3072 nt
	s_waitcnt vmcnt(8)
	s_branch .Lrm0_pfd_o

.Lrm0_pfd_o:
	v_pk_mul_f32 v[108:109], v[136:137], v[136:137]
	v_pk_mul_f32 v[110:111], v[138:139], v[138:139]
	v_pk_fma_f32 v[108:109], v[140:141], v[140:141], v[108:109]
	v_pk_fma_f32 v[110:111], v[142:143], v[142:143], v[110:111]
	v_pk_fma_f32 v[108:109], v[144:145], v[144:145], v[108:109]
	v_pk_fma_f32 v[110:111], v[146:147], v[146:147], v[110:111]
	v_pk_fma_f32 v[108:109], v[148:149], v[148:149], v[108:109]
	v_pk_fma_f32 v[110:111], v[150:151], v[150:151], v[110:111]
	v_pk_fma_f32 v[108:109], v[152:153], v[152:153], v[108:109]
	v_pk_fma_f32 v[110:111], v[154:155], v[154:155], v[110:111]
	v_pk_fma_f32 v[108:109], v[156:157], v[156:157], v[108:109]
	v_pk_fma_f32 v[110:111], v[158:159], v[158:159], v[110:111]
	v_pk_fma_f32 v[108:109], v[160:161], v[160:161], v[108:109]
	v_pk_fma_f32 v[110:111], v[162:163], v[162:163], v[110:111]
	v_pk_fma_f32 v[108:109], v[164:165], v[164:165], v[108:109]
	v_pk_fma_f32 v[110:111], v[166:167], v[166:167], v[110:111]
	v_pk_add_f32 v[108:109], v[108:109], v[110:111]
	s_nop 0
	v_add_f32_e32 v128, v108, v109
	s_nop 1
	v_add_f32_dpp v128, v128, v128 quad_perm:[1,0,3,2] row_mask:0xf bank_mask:0xf
	s_nop 1
	v_add_f32_dpp v128, v128, v128 quad_perm:[2,3,0,1] row_mask:0xf bank_mask:0xf
	s_nop 1
	v_add_f32_dpp v128, v128, v128 row_half_mirror row_mask:0xf bank_mask:0xf
	s_nop 1
	v_add_f32_dpp v128, v128, v128 row_mirror row_mask:0xf bank_mask:0xf
	s_nop 1
	v_add_f32_dpp v128, v128, v128 row_bcast:15 row_mask:0xa bank_mask:0xf
	s_nop 1
	v_add_f32_dpp v128, v128, v128 row_bcast:31 row_mask:0xc bank_mask:0xf
	s_nop 1
	v_readlane_b32 s8, v128, 63
	s_nop 3
	v_mov_b32_e32 v112, s8
	v_fma_f32 v112, v112, v126, v127
	v_rsq_f32_e32 v112, v112
	s_nop 1
	v_pk_mul_f32 v[100:101], v[136:137], v[112:113] op_sel_hi:[1,0]
	v_pk_fma_f32 v[100:101], v[100:101], v[32:33], v[68:69]
	v_cvt_pk_bf16_f32 v114, v100, v101
	v_pk_mul_f32 v[102:103], v[138:139], v[112:113] op_sel_hi:[1,0]
	v_pk_fma_f32 v[102:103], v[102:103], v[34:35], v[70:71]
	v_cvt_pk_bf16_f32 v115, v102, v103
	global_store_dwordx2 v124, v[114:115], s[10:11] offset:0 nt
	v_pk_mul_f32 v[104:105], v[140:141], v[112:113] op_sel_hi:[1,0]
	v_pk_fma_f32 v[104:105], v[104:105], v[36:37], v[72:73]
	v_cvt_pk_bf16_f32 v116, v104, v105
	v_pk_mul_f32 v[106:107], v[142:143], v[112:113] op_sel_hi:[1,0]
	v_pk_fma_f32 v[106:107], v[106:107], v[38:39], v[74:75]
	v_cvt_pk_bf16_f32 v117, v106, v107
	global_store_dwordx2 v124, v[116:117], s[10:11] offset:512 nt
	v_pk_mul_f32 v[100:101], v[144:145], v[112:113] op_sel_hi:[1,0]
	v_pk_fma_f32 v[100:101], v[100:101], v[40:41], v[76:77]
	v_cvt_pk_bf16_f32 v118, v100, v101
	v_pk_mul_f32 v[102:103], v[146:147], v[112:113] op_sel_hi:[1,0]
	v_pk_fma_f32 v[102:103], v[102:103], v[42:43], v[78:79]
	v_cvt_pk_bf16_f32 v119, v102, v103
	global_store_dwordx2 v124, v[118:119], s[10:11] offset:1024 nt
	v_pk_mul_f32 v[104:105], v[148:149], v[112:113] op_sel_hi:[1,0]
	v_pk_fma_f32 v[104:105], v[104:105], v[44:45], v[80:81]
	v_cvt_pk_bf16_f32 v120, v104, v105
	v_pk_mul_f32 v[106:107], v[150:151], v[112:113] op_sel_hi:[1,0]
	v_pk_fma_f32 v[106:107], v[106:107], v[46:47], v[82:83]
	v_cvt_pk_bf16_f32 v121, v106, v107
	global_store_dwordx2 v124, v[120:121], s[10:11] offset:1536 nt
	v_pk_mul_f32 v[100:101], v[152:153], v[112:113] op_sel_hi:[1,0]
	v_pk_fma_f32 v[100:101], v[100:101], v[48:49], v[84:85]
	v_cvt_pk_bf16_f32 v114, v100, v101
	v_pk_mul_f32 v[102:103], v[154:155], v[112:113] op_sel_hi:[1,0]
	v_pk_fma_f32 v[102:103], v[102:103], v[50:51], v[86:87]
	v_cvt_pk_bf16_f32 v115, v102, v103
	global_store_dwordx2 v124, v[114:115], s[10:11] offset:2048 nt
	v_pk_mul_f32 v[104:105], v[156:157], v[112:113] op_sel_hi:[1,0]
	v_pk_fma_f32 v[104:105], v[104:105], v[56:57], v[88:89]
	v_cvt_pk_bf16_f32 v116, v104, v105
	v_pk_mul_f32 v[106:107], v[158:159], v[112:113] op_sel_hi:[1,0]
	v_pk_fma_f32 v[106:107], v[106:107], v[58:59], v[90:91]
	v_cvt_pk_bf16_f32 v117, v106, v107
	global_store_dwordx2 v124, v[116:117], s[10:11] offset:2560 nt
	v_pk_mul_f32 v[100:101], v[160:161], v[112:113] op_sel_hi:[1,0]
	v_pk_fma_f32 v[100:101], v[100:101], v[60:61], v[92:93]
	v_cvt_pk_bf16_f32 v118, v100, v101
	v_pk_mul_f32 v[102:103], v[162:163], v[112:113] op_sel_hi:[1,0]
	v_pk_fma_f32 v[102:103], v[102:103], v[62:63], v[94:95]
	v_cvt_pk_bf16_f32 v119, v102, v103
	global_store_dwordx2 v124, v[118:119], s[10:11] offset:3072 nt
	v_pk_mul_f32 v[104:105], v[164:165], v[112:113] op_sel_hi:[1,0]
	v_pk_fma_f32 v[104:105], v[104:105], v[64:65], v[96:97]
	v_cvt_pk_bf16_f32 v120, v104, v105
	v_pk_mul_f32 v[106:107], v[166:167], v[112:113] op_sel_hi:[1,0]
	v_pk_fma_f32 v[106:107], v[106:107], v[66:67], v[98:99]
	v_cvt_pk_bf16_f32 v121, v106, v107
	global_store_dwordx2 v124, v[120:121], s[10:11] offset:3584 nt
	s_add_u32 s0, s0, 2
	s_cmp_lt_u32 s0, 16
	s_cbranch_scc1 .Lrm0_loop
	s_bitcmp1_b32 s5, 0
	s_cbranch_scc1 .Lrm0_done
	s_mov_b32 s4, 4
	s_branch .Lrm0_coef
.Lrm0_ctxrow:
	s_lshr_b32 s8, s5, 1
	s_lshl_b32 s8, s8, 13
	v_readfirstlane_b32 s6, v132
	v_readfirstlane_b32 s7, v133
	s_nop 3
	s_add_u32 s6, s6, s8
	s_addc_u32 s7, s7, 0
	s_nop 1
	global_load_dwordx4 v[0:3], v122, s[6:7] offset:0 nt
	global_load_dwordx4 v[4:7], v122, s[6:7] offset:1024 nt
	global_load_dwordx4 v[8:11], v122, s[6:7] offset:2048 nt
	global_load_dwordx4 v[12:15], v122, s[6:7] offset:3072 nt
	global_load_dwordx4 v[16:19], v123, s[6:7] offset:0 nt
	global_load_dwordx4 v[20:23], v123, s[6:7] offset:1024 nt
	global_load_dwordx4 v[24:27], v123, s[6:7] offset:2048 nt
	global_load_dwordx4 v[28:31], v123, s[6:7] offset:3072 nt
	s_lshr_b32 s8, s5, 1
	s_add_u32 s1, s8, 0x8000
	s_lshl_b32 s8, s8, 13
	s_lshl_b32 s8, s1, 12
	s_add_u32 s9, s8, 0x2c800000
	s_add_u32 s10, s52, s9
	s_addc_u32 s11, s53, 0
	s_waitcnt vmcnt(0)
	v_pk_mul_f32 v[108:109], v[0:1], v[0:1]
	v_pk_mul_f32 v[110:111], v[2:3], v[2:3]
	v_pk_fma_f32 v[108:109], v[4:5], v[4:5], v[108:109]
	v_pk_fma_f32 v[110:111], v[6:7], v[6:7], v[110:111]
	v_pk_fma_f32 v[108:109], v[8:9], v[8:9], v[108:109]
	v_pk_fma_f32 v[110:111], v[10:11], v[10:11], v[110:111]
	v_pk_fma_f32 v[108:109], v[12:13], v[12:13], v[108:109]
	v_pk_fma_f32 v[110:111], v[14:15], v[14:15], v[110:111]
	v_pk_fma_f32 v[108:109], v[16:17], v[16:17], v[108:109]
	v_pk_fma_f32 v[110:111], v[18:19], v[18:19], v[110:111]
	v_pk_fma_f32 v[108:109], v[20:21], v[20:21], v[108:109]
	v_pk_fma_f32 v[110:111], v[22:23], v[22:23], v[110:111]
	v_pk_fma_f32 v[108:109], v[24:25], v[24:25], v[108:109]
	v_pk_fma_f32 v[110:111], v[26:27], v[26:27], v[110:111]
	v_pk_fma_f32 v[108:109], v[28:29], v[28:29], v[108:109]
	v_pk_fma_f32 v[110:111], v[30:31], v[30:31], v[110:111]
	v_pk_add_f32 v[108:109], v[108:109], v[110:111]
	s_nop 0
	v_add_f32_e32 v128, v108, v109
	s_nop 1
	v_add_f32_dpp v128, v128, v128 quad_perm:[1,0,3,2] row_mask:0xf bank_mask:0xf
	s_nop 1
	v_add_f32_dpp v128, v128, v128 quad_perm:[2,3,0,1] row_mask:0xf bank_mask:0xf
	s_nop 1
	v_add_f32_dpp v128, v128, v128 row_half_mirror row_mask:0xf bank_mask:0xf
	s_nop 1
	v_add_f32_dpp v128, v128, v128 row_mirror row_mask:0xf bank_mask:0xf
	s_nop 1
	v_add_f32_dpp v128, v128, v128 row_bcast:15 row_mask:0xa bank_mask:0xf
	s_nop 1
	v_add_f32_dpp v128, v128, v128 row_bcast:31 row_mask:0xc bank_mask:0xf
	s_nop 1
	v_readlane_b32 s8, v128, 63
	s_nop 3
	v_mov_b32_e32 v112, s8
	v_fma_f32 v112, v112, v126, v127
	v_rsq_f32_e32 v112, v112
	s_nop 1
	v_pk_mul_f32 v[100:101], v[0:1], v[112:113] op_sel_hi:[1,0]
	v_pk_fma_f32 v[100:101], v[100:101], v[32:33], v[68:69]
	v_cvt_pk_bf16_f32 v114, v100, v101
	v_pk_mul_f32 v[102:103], v[2:3], v[112:113] op_sel_hi:[1,0]
	v_pk_fma_f32 v[102:103], v[102:103], v[34:35], v[70:71]
	v_cvt_pk_bf16_f32 v115, v102, v103
	global_store_dwordx2 v124, v[114:115], s[10:11] offset:0 nt
	v_pk_mul_f32 v[104:105], v[4:5], v[112:113] op_sel_hi:[1,0]
	v_pk_fma_f32 v[104:105], v[104:105], v[36:37], v[72:73]
	v_cvt_pk_bf16_f32 v116, v104, v105
	v_pk_mul_f32 v[106:107], v[6:7], v[112:113] op_sel_hi:[1,0]
	v_pk_fma_f32 v[106:107], v[106:107], v[38:39], v[74:75]
	v_cvt_pk_bf16_f32 v117, v106, v107
	global_store_dwordx2 v124, v[116:117], s[10:11] offset:512 nt
	v_pk_mul_f32 v[100:101], v[8:9], v[112:113] op_sel_hi:[1,0]
	v_pk_fma_f32 v[100:101], v[100:101], v[40:41], v[76:77]
	v_cvt_pk_bf16_f32 v118, v100, v101
	v_pk_mul_f32 v[102:103], v[10:11], v[112:113] op_sel_hi:[1,0]
	v_pk_fma_f32 v[102:103], v[102:103], v[42:43], v[78:79]
	v_cvt_pk_bf16_f32 v119, v102, v103
	global_store_dwordx2 v124, v[118:119], s[10:11] offset:1024 nt
	v_pk_mul_f32 v[104:105], v[12:13], v[112:113] op_sel_hi:[1,0]
	v_pk_fma_f32 v[104:105], v[104:105], v[44:45], v[80:81]
	v_cvt_pk_bf16_f32 v120, v104, v105
	v_pk_mul_f32 v[106:107], v[14:15], v[112:113] op_sel_hi:[1,0]
	v_pk_fma_f32 v[106:107], v[106:107], v[46:47], v[82:83]
	v_cvt_pk_bf16_f32 v121, v106, v107
	global_store_dwordx2 v124, v[120:121], s[10:11] offset:1536 nt
	v_pk_mul_f32 v[100:101], v[16:17], v[112:113] op_sel_hi:[1,0]
	v_pk_fma_f32 v[100:101], v[100:101], v[48:49], v[84:85]
	v_cvt_pk_bf16_f32 v114, v100, v101
	v_pk_mul_f32 v[102:103], v[18:19], v[112:113] op_sel_hi:[1,0]
	v_pk_fma_f32 v[102:103], v[102:103], v[50:51], v[86:87]
	v_cvt_pk_bf16_f32 v115, v102, v103
	global_store_dwordx2 v124, v[114:115], s[10:11] offset:2048 nt
	v_pk_mul_f32 v[104:105], v[20:21], v[112:113] op_sel_hi:[1,0]
	v_pk_fma_f32 v[104:105], v[104:105], v[56:57], v[88:89]
	v_cvt_pk_bf16_f32 v116, v104, v105
	v_pk_mul_f32 v[106:107], v[22:23], v[112:113] op_sel_hi:[1,0]
	v_pk_fma_f32 v[106:107], v[106:107], v[58:59], v[90:91]
	v_cvt_pk_bf16_f32 v117, v106, v107
	global_store_dwordx2 v124, v[116:117], s[10:11] offset:2560 nt
	v_pk_mul_f32 v[100:101], v[24:25], v[112:113] op_sel_hi:[1,0]
	v_pk_fma_f32 v[100:101], v[100:101], v[60:61], v[92:93]
	v_cvt_pk_bf16_f32 v118, v100, v101
	v_pk_mul_f32 v[102:103], v[26:27], v[112:113] op_sel_hi:[1,0]
	v_pk_fma_f32 v[102:103], v[102:103], v[62:63], v[94:95]
	v_cvt_pk_bf16_f32 v119, v102, v103
	global_store_dwordx2 v124, v[118:119], s[10:11] offset:3072 nt
	v_pk_mul_f32 v[104:105], v[28:29], v[112:113] op_sel_hi:[1,0]
	v_pk_fma_f32 v[104:105], v[104:105], v[64:65], v[96:97]
	v_cvt_pk_bf16_f32 v120, v104, v105
	v_pk_mul_f32 v[106:107], v[30:31], v[112:113] op_sel_hi:[1,0]
	v_pk_fma_f32 v[106:107], v[106:107], v[66:67], v[98:99]
	v_cvt_pk_bf16_f32 v121, v106, v107
	global_store_dwordx2 v124, v[120:121], s[10:11] offset:3584 nt

.Lrm1_loop:
	s_lshr_b32 s1, s3, 9
	s_lshl_b32 s1, s1, 13
	s_and_b32 s8, s3, 0x1ff
	s_add_u32 s1, s1, s8
	s_add_u32 s8, s0, 0
	s_lshl_b32 s8, s8, 9
	s_add_u32 s1, s1, s8
	s_lshl_b32 s8, s1, 13
	s_add_u32 s10, s58, s8
	s_addc_u32 s11, s59, 0
	s_lshl_b32 s8, s1, 12
	s_add_u32 s9, s8, 0xb800000
	s_add_u32 s12, s52, s9
	s_addc_u32 s13, s53, 0
	s_add_u32 s9, s8, 0x2c800000
	s_add_u32 s14, s52, s9
	s_addc_u32 s15, s53, 0
	global_load_dwordx2 v[32:33], v173, s[12:13] offset:0 nt
	global_load_dwordx2 v[34:35], v173, s[12:13] offset:512 nt
	global_load_dwordx2 v[36:37], v173, s[12:13] offset:1024 nt
	global_load_dwordx2 v[38:39], v173, s[12:13] offset:1536 nt
	global_load_dwordx2 v[40:41], v173, s[12:13] offset:2048 nt
	global_load_dwordx2 v[42:43], v173, s[12:13] offset:2560 nt
	global_load_dwordx2 v[44:45], v173, s[12:13] offset:3072 nt
	global_load_dwordx2 v[46:47], v173, s[12:13] offset:3584 nt
	s_lshr_b32 s1, s3, 9
	s_lshl_b32 s1, s1, 13
	s_and_b32 s8, s3, 0x1ff
	s_add_u32 s1, s1, s8
	s_add_u32 s8, s0, 1
	s_lshl_b32 s8, s8, 9
	s_add_u32 s1, s1, s8
	s_lshl_b32 s8, s1, 13
	v_readfirstlane_b32 s4, v178
	v_readfirstlane_b32 s5, v179
	s_nop 3
	s_add_u32 s4, s4, s8
	s_addc_u32 s5, s5, 0
	s_nop 1
	global_load_dwordx4 v[192:195], v76, s[4:5] offset:0 nt
	global_load_dwordx4 v[196:199], v76, s[4:5] offset:1024 nt
	global_load_dwordx4 v[200:203], v76, s[4:5] offset:2048 nt
	global_load_dwordx4 v[204:207], v76, s[4:5] offset:3072 nt
	global_load_dwordx4 v[208:211], v172, s[4:5] offset:0 nt
	global_load_dwordx4 v[216:219], v172, s[4:5] offset:1024 nt
	global_load_dwordx4 v[224:227], v172, s[4:5] offset:2048 nt
	global_load_dwordx4 v[236:239], v172, s[4:5] offset:3072 nt
	s_waitcnt vmcnt(8)
	v_lshlrev_b32_e32 v150, 16, v32
	v_and_b32_e32 v151, 0xffff0000, v32
	v_pk_mul_f32 v[158:159], v[150:151], v[150:151]
	v_lshlrev_b32_e32 v152, 16, v33
	v_and_b32_e32 v153, 0xffff0000, v33
	v_pk_mul_f32 v[160:161], v[152:153], v[152:153]
	v_lshlrev_b32_e32 v154, 16, v34
	v_and_b32_e32 v155, 0xffff0000, v34
	v_pk_fma_f32 v[158:159], v[154:155], v[154:155], v[158:159]
	v_lshlrev_b32_e32 v156, 16, v35
	v_and_b32_e32 v157, 0xffff0000, v35
	v_pk_fma_f32 v[160:161], v[156:157], v[156:157], v[160:161]
	v_lshlrev_b32_e32 v150, 16, v36
	v_and_b32_e32 v151, 0xffff0000, v36
	v_pk_fma_f32 v[158:159], v[150:151], v[150:151], v[158:159]
	v_lshlrev_b32_e32 v152, 16, v37
	v_and_b32_e32 v153, 0xffff0000, v37
	v_pk_fma_f32 v[160:161], v[152:153], v[152:153], v[160:161]
	v_lshlrev_b32_e32 v154, 16, v38
	v_and_b32_e32 v155, 0xffff0000, v38
	v_pk_fma_f32 v[158:159], v[154:155], v[154:155], v[158:159]
	v_lshlrev_b32_e32 v156, 16, v39
	v_and_b32_e32 v157, 0xffff0000, v39
	v_pk_fma_f32 v[160:161], v[156:157], v[156:157], v[160:161]
	v_lshlrev_b32_e32 v150, 16, v40
	v_and_b32_e32 v151, 0xffff0000, v40
	v_pk_fma_f32 v[158:159], v[150:151], v[150:151], v[158:159]
	v_lshlrev_b32_e32 v152, 16, v41
	v_and_b32_e32 v153, 0xffff0000, v41
	v_pk_fma_f32 v[160:161], v[152:153], v[152:153], v[160:161]
	v_lshlrev_b32_e32 v154, 16, v42
	v_and_b32_e32 v155, 0xffff0000, v42
	v_pk_fma_f32 v[158:159], v[154:155], v[154:155], v[158:159]
	v_lshlrev_b32_e32 v156, 16, v43
	v_and_b32_e32 v157, 0xffff0000, v43
	v_pk_fma_f32 v[160:161], v[156:157], v[156:157], v[160:161]
	v_lshlrev_b32_e32 v150, 16, v44
	v_and_b32_e32 v151, 0xffff0000, v44
	v_pk_fma_f32 v[158:159], v[150:151], v[150:151], v[158:159]
	v_lshlrev_b32_e32 v152, 16, v45
	v_and_b32_e32 v153, 0xffff0000, v45
	v_pk_fma_f32 v[160:161], v[152:153], v[152:153], v[160:161]
	v_lshlrev_b32_e32 v154, 16, v46
	v_and_b32_e32 v155, 0xffff0000, v46
	v_pk_fma_f32 v[158:159], v[154:155], v[154:155], v[158:159]
	v_lshlrev_b32_e32 v156, 16, v47
	v_and_b32_e32 v157, 0xffff0000, v47
	v_pk_fma_f32 v[160:161], v[156:157], v[156:157], v[160:161]
	v_pk_add_f32 v[158:159], v[158:159], v[160:161]
	s_nop 0
	v_add_f32_e32 v177, v158, v159
	s_nop 1
	v_add_f32_dpp v177, v177, v177 quad_perm:[1,0,3,2] row_mask:0xf bank_mask:0xf
	s_nop 1
	v_add_f32_dpp v177, v177, v177 quad_perm:[2,3,0,1] row_mask:0xf bank_mask:0xf
	s_nop 1
	v_add_f32_dpp v177, v177, v177 row_half_mirror row_mask:0xf bank_mask:0xf
	s_nop 1
	v_add_f32_dpp v177, v177, v177 row_mirror row_mask:0xf bank_mask:0xf
	s_nop 1
	v_add_f32_dpp v177, v177, v177 row_bcast:15 row_mask:0xa bank_mask:0xf
	s_nop 1
	v_add_f32_dpp v177, v177, v177 row_bcast:31 row_mask:0xc bank_mask:0xf
	s_nop 1
	v_readlane_b32 s8, v177, 63
	s_nop 3
	v_mov_b32_e32 v162, s8
	v_fma_f32 v162, v162, v175, v176
	v_rsq_f32_e32 v162, v162
	s_nop 1
	v_lshlrev_b32_e32 v150, 16, v32
	v_and_b32_e32 v151, 0xffff0000, v32
	v_pk_mul_f32 v[150:151], v[150:151], v[162:163] op_sel_hi:[1,0]
	v_pk_fma_f32 v[0:1], v[48:49], v[150:151], v[0:1]
	v_lshlrev_b32_e32 v152, 16, v33
	v_and_b32_e32 v153, 0xffff0000, v33
	v_pk_mul_f32 v[152:153], v[152:153], v[162:163] op_sel_hi:[1,0]
	v_pk_fma_f32 v[2:3], v[50:51], v[152:153], v[2:3]
	v_lshlrev_b32_e32 v154, 16, v34
	v_and_b32_e32 v155, 0xffff0000, v34
	v_pk_mul_f32 v[154:155], v[154:155], v[162:163] op_sel_hi:[1,0]
	v_pk_fma_f32 v[4:5], v[52:53], v[154:155], v[4:5]
	v_lshlrev_b32_e32 v156, 16, v35
	v_and_b32_e32 v157, 0xffff0000, v35
	v_pk_mul_f32 v[156:157], v[156:157], v[162:163] op_sel_hi:[1,0]
	v_pk_fma_f32 v[6:7], v[54:55], v[156:157], v[6:7]
	v_lshlrev_b32_e32 v150, 16, v36
	v_and_b32_e32 v151, 0xffff0000, v36
	v_pk_mul_f32 v[150:151], v[150:151], v[162:163] op_sel_hi:[1,0]
	v_pk_fma_f32 v[8:9], v[56:57], v[150:151], v[8:9]
	v_lshlrev_b32_e32 v152, 16, v37
	v_and_b32_e32 v153, 0xffff0000, v37
	v_pk_mul_f32 v[152:153], v[152:153], v[162:163] op_sel_hi:[1,0]
	v_pk_fma_f32 v[10:11], v[58:59], v[152:153], v[10:11]
	v_lshlrev_b32_e32 v154, 16, v38
	v_and_b32_e32 v155, 0xffff0000, v38
	v_pk_mul_f32 v[154:155], v[154:155], v[162:163] op_sel_hi:[1,0]
	v_pk_fma_f32 v[12:13], v[60:61], v[154:155], v[12:13]
	v_lshlrev_b32_e32 v156, 16, v39
	v_and_b32_e32 v157, 0xffff0000, v39
	v_pk_mul_f32 v[156:157], v[156:157], v[162:163] op_sel_hi:[1,0]
	v_pk_fma_f32 v[14:15], v[62:63], v[156:157], v[14:15]
	v_lshlrev_b32_e32 v150, 16, v40
	v_and_b32_e32 v151, 0xffff0000, v40
	v_pk_mul_f32 v[150:151], v[150:151], v[162:163] op_sel_hi:[1,0]
	v_pk_fma_f32 v[16:17], v[64:65], v[150:151], v[16:17]
	v_lshlrev_b32_e32 v152, 16, v41
	v_and_b32_e32 v153, 0xffff0000, v41
	v_pk_mul_f32 v[152:153], v[152:153], v[162:163] op_sel_hi:[1,0]
	v_pk_fma_f32 v[18:19], v[66:67], v[152:153], v[18:19]
	v_lshlrev_b32_e32 v154, 16, v42
	v_and_b32_e32 v155, 0xffff0000, v42
	v_pk_mul_f32 v[154:155], v[154:155], v[162:163] op_sel_hi:[1,0]
	v_pk_fma_f32 v[20:21], v[68:69], v[154:155], v[20:21]
	v_lshlrev_b32_e32 v156, 16, v43
	v_and_b32_e32 v157, 0xffff0000, v43
	v_pk_mul_f32 v[156:157], v[156:157], v[162:163] op_sel_hi:[1,0]
	v_pk_fma_f32 v[22:23], v[70:71], v[156:157], v[22:23]
	v_lshlrev_b32_e32 v150, 16, v44
	v_and_b32_e32 v151, 0xffff0000, v44
	v_pk_mul_f32 v[150:151], v[150:151], v[162:163] op_sel_hi:[1,0]
	v_pk_fma_f32 v[24:25], v[72:73], v[150:151], v[24:25]
	v_lshlrev_b32_e32 v152, 16, v45
	v_and_b32_e32 v153, 0xffff0000, v45
	v_pk_mul_f32 v[152:153], v[152:153], v[162:163] op_sel_hi:[1,0]
	v_pk_fma_f32 v[26:27], v[74:75], v[152:153], v[26:27]
	v_lshlrev_b32_e32 v154, 16, v46
	v_and_b32_e32 v155, 0xffff0000, v46
	v_pk_mul_f32 v[154:155], v[154:155], v[162:163] op_sel_hi:[1,0]
	v_pk_fma_f32 v[28:29], v[82:83], v[154:155], v[28:29]
	v_lshlrev_b32_e32 v156, 16, v47
	v_and_b32_e32 v157, 0xffff0000, v47
	v_pk_mul_f32 v[156:157], v[156:157], v[162:163] op_sel_hi:[1,0]
	v_pk_fma_f32 v[30:31], v[84:85], v[156:157], v[30:31]
	s_nop 0
	global_store_dwordx4 v76, v[0:3], s[10:11] offset:0 nt
	global_store_dwordx4 v76, v[4:7], s[10:11] offset:1024 nt
	global_store_dwordx4 v76, v[8:11], s[10:11] offset:2048 nt
	global_store_dwordx4 v76, v[12:15], s[10:11] offset:3072 nt
	global_store_dwordx4 v172, v[16:19], s[10:11] offset:0 nt
	global_store_dwordx4 v172, v[20:23], s[10:11] offset:1024 nt
	global_store_dwordx4 v172, v[24:27], s[10:11] offset:2048 nt
	global_store_dwordx4 v172, v[28:31], s[10:11] offset:3072 nt
	v_pk_mul_f32 v[158:159], v[0:1], v[0:1]
	v_pk_mul_f32 v[160:161], v[2:3], v[2:3]
	v_pk_fma_f32 v[158:159], v[4:5], v[4:5], v[158:159]
	v_pk_fma_f32 v[160:161], v[6:7], v[6:7], v[160:161]
	v_pk_fma_f32 v[158:159], v[8:9], v[8:9], v[158:159]
	v_pk_fma_f32 v[160:161], v[10:11], v[10:11], v[160:161]
	v_pk_fma_f32 v[158:159], v[12:13], v[12:13], v[158:159]
	v_pk_fma_f32 v[160:161], v[14:15], v[14:15], v[160:161]
	v_pk_fma_f32 v[158:159], v[16:17], v[16:17], v[158:159]
	v_pk_fma_f32 v[160:161], v[18:19], v[18:19], v[160:161]
	v_pk_fma_f32 v[158:159], v[20:21], v[20:21], v[158:159]
	v_pk_fma_f32 v[160:161], v[22:23], v[22:23], v[160:161]
	v_pk_fma_f32 v[158:159], v[24:25], v[24:25], v[158:159]
	v_pk_fma_f32 v[160:161], v[26:27], v[26:27], v[160:161]
	v_pk_fma_f32 v[158:159], v[28:29], v[28:29], v[158:159]
	v_pk_fma_f32 v[160:161], v[30:31], v[30:31], v[160:161]
	v_pk_add_f32 v[158:159], v[158:159], v[160:161]
	s_nop 0
	v_add_f32_e32 v177, v158, v159
	s_nop 1
	v_add_f32_dpp v177, v177, v177 quad_perm:[1,0,3,2] row_mask:0xf bank_mask:0xf
	s_nop 1
	v_add_f32_dpp v177, v177, v177 quad_perm:[2,3,0,1] row_mask:0xf bank_mask:0xf
	s_nop 1
	v_add_f32_dpp v177, v177, v177 row_half_mirror row_mask:0xf bank_mask:0xf
	s_nop 1
	v_add_f32_dpp v177, v177, v177 row_mirror row_mask:0xf bank_mask:0xf
	s_nop 1
	v_add_f32_dpp v177, v177, v177 row_bcast:15 row_mask:0xa bank_mask:0xf
	s_nop 1
	v_add_f32_dpp v177, v177, v177 row_bcast:31 row_mask:0xc bank_mask:0xf
	s_nop 1
	v_readlane_b32 s8, v177, 63
	s_nop 3
	v_mov_b32_e32 v162, s8
	v_fma_f32 v162, v162, v175, v176
	v_rsq_f32_e32 v162, v162
	s_nop 1
	v_pk_mul_f32 v[150:151], v[0:1], v[162:163] op_sel_hi:[1,0]
	v_pk_fma_f32 v[150:151], v[150:151], v[86:87], v[118:119]
	v_cvt_pk_bf16_f32 v164, v150, v151
	v_pk_mul_f32 v[152:153], v[2:3], v[162:163] op_sel_hi:[1,0]
	v_pk_fma_f32 v[152:153], v[152:153], v[88:89], v[120:121]
	v_cvt_pk_bf16_f32 v165, v152, v153
	global_store_dwordx2 v173, v[164:165], s[14:15] offset:0 nt
	v_pk_mul_f32 v[154:155], v[4:5], v[162:163] op_sel_hi:[1,0]
	v_pk_fma_f32 v[154:155], v[154:155], v[90:91], v[122:123]
	v_cvt_pk_bf16_f32 v166, v154, v155
	v_pk_mul_f32 v[156:157], v[6:7], v[162:163] op_sel_hi:[1,0]
	v_pk_fma_f32 v[156:157], v[156:157], v[92:93], v[124:125]
	v_cvt_pk_bf16_f32 v167, v156, v157
	global_store_dwordx2 v173, v[166:167], s[14:15] offset:512 nt
	v_pk_mul_f32 v[150:151], v[8:9], v[162:163] op_sel_hi:[1,0]
	v_pk_fma_f32 v[150:151], v[150:151], v[94:95], v[126:127]
	v_cvt_pk_bf16_f32 v168, v150, v151
	v_pk_mul_f32 v[152:153], v[10:11], v[162:163] op_sel_hi:[1,0]
	v_pk_fma_f32 v[152:153], v[152:153], v[96:97], v[128:129]
	v_cvt_pk_bf16_f32 v169, v152, v153
	global_store_dwordx2 v173, v[168:169], s[14:15] offset:1024 nt
	v_pk_mul_f32 v[154:155], v[12:13], v[162:163] op_sel_hi:[1,0]
	v_pk_fma_f32 v[154:155], v[154:155], v[98:99], v[130:131]
	v_cvt_pk_bf16_f32 v170, v154, v155
	v_pk_mul_f32 v[156:157], v[14:15], v[162:163] op_sel_hi:[1,0]
	v_pk_fma_f32 v[156:157], v[156:157], v[100:101], v[132:133]
	v_cvt_pk_bf16_f32 v171, v156, v157
	global_store_dwordx2 v173, v[170:171], s[14:15] offset:1536 nt
	v_pk_mul_f32 v[150:151], v[16:17], v[162:163] op_sel_hi:[1,0]
	v_pk_fma_f32 v[150:151], v[150:151], v[102:103], v[134:135]
	v_cvt_pk_bf16_f32 v164, v150, v151
	v_pk_mul_f32 v[152:153], v[18:19], v[162:163] op_sel_hi:[1,0]
	v_pk_fma_f32 v[152:153], v[152:153], v[104:105], v[136:137]
	v_cvt_pk_bf16_f32 v165, v152, v153
	global_store_dwordx2 v173, v[164:165], s[14:15] offset:2048 nt
	v_pk_mul_f32 v[154:155], v[20:21], v[162:163] op_sel_hi:[1,0]
	v_pk_fma_f32 v[154:155], v[154:155], v[106:107], v[138:139]
	v_cvt_pk_bf16_f32 v166, v154, v155
	v_pk_mul_f32 v[156:157], v[22:23], v[162:163] op_sel_hi:[1,0]
	v_pk_fma_f32 v[156:157], v[156:157], v[108:109], v[140:141]
	v_cvt_pk_bf16_f32 v167, v156, v157
	global_store_dwordx2 v173, v[166:167], s[14:15] offset:2560 nt
	v_pk_mul_f32 v[150:151], v[24:25], v[162:163] op_sel_hi:[1,0]
	v_pk_fma_f32 v[150:151], v[150:151], v[110:111], v[142:143]
	v_cvt_pk_bf16_f32 v168, v150, v151
	v_pk_mul_f32 v[152:153], v[26:27], v[162:163] op_sel_hi:[1,0]
	v_pk_fma_f32 v[152:153], v[152:153], v[112:113], v[144:145]
	v_cvt_pk_bf16_f32 v169, v152, v153
	global_store_dwordx2 v173, v[168:169], s[14:15] offset:3072 nt
	v_pk_mul_f32 v[154:155], v[28:29], v[162:163] op_sel_hi:[1,0]
	v_pk_fma_f32 v[154:155], v[154:155], v[114:115], v[146:147]
	v_cvt_pk_bf16_f32 v170, v154, v155
	v_pk_mul_f32 v[156:157], v[30:31], v[162:163] op_sel_hi:[1,0]
	v_pk_fma_f32 v[156:157], v[156:157], v[116:117], v[148:149]
	v_cvt_pk_bf16_f32 v171, v156, v157
	global_store_dwordx2 v173, v[170:171], s[14:15] offset:3584 nt
	s_lshr_b32 s1, s3, 9
	s_lshl_b32 s1, s1, 13
	s_and_b32 s8, s3, 0x1ff
	s_add_u32 s1, s1, s8
	s_add_u32 s8, s0, 1
	s_lshl_b32 s8, s8, 9
	s_add_u32 s1, s1, s8
	s_lshl_b32 s8, s1, 13
	s_add_u32 s10, s58, s8
	s_addc_u32 s11, s59, 0
	s_lshl_b32 s8, s1, 12
	s_add_u32 s9, s8, 0xb800000
	s_add_u32 s12, s52, s9
	s_addc_u32 s13, s53, 0
	s_add_u32 s9, s8, 0x2c800000
	s_add_u32 s14, s52, s9
	s_addc_u32 s15, s53, 0
	global_load_dwordx2 v[32:33], v173, s[12:13] offset:0 nt
	global_load_dwordx2 v[34:35], v173, s[12:13] offset:512 nt
	global_load_dwordx2 v[36:37], v173, s[12:13] offset:1024 nt
	global_load_dwordx2 v[38:39], v173, s[12:13] offset:1536 nt
	global_load_dwordx2 v[40:41], v173, s[12:13] offset:2048 nt
	global_load_dwordx2 v[42:43], v173, s[12:13] offset:2560 nt
	global_load_dwordx2 v[44:45], v173, s[12:13] offset:3072 nt
	global_load_dwordx2 v[46:47], v173, s[12:13] offset:3584 nt
	s_cmp_lt_u32 s0, 14
	s_cbranch_scc0 .Lrm1_nopf_o
	s_lshr_b32 s1, s3, 9
	s_lshl_b32 s1, s1, 13
	s_and_b32 s8, s3, 0x1ff
	s_add_u32 s1, s1, s8
	s_add_u32 s8, s0, 2
	s_lshl_b32 s8, s8, 9
	s_add_u32 s1, s1, s8
	s_lshl_b32 s8, s1, 13
	v_readfirstlane_b32 s4, v178
	v_readfirstlane_b32 s5, v179
	s_nop 3
	s_add_u32 s4, s4, s8
	s_addc_u32 s5, s5, 0
	s_nop 1
	global_load_dwordx4 v[0:3], v76, s[4:5] offset:0 nt
	global_load_dwordx4 v[4:7], v76, s[4:5] offset:1024 nt
	global_load_dwordx4 v[8:11], v76, s[4:5] offset:2048 nt
	global_load_dwordx4 v[12:15], v76, s[4:5] offset:3072 nt
	global_load_dwordx4 v[16:19], v172, s[4:5] offset:0 nt
	global_load_dwordx4 v[20:23], v172, s[4:5] offset:1024 nt
	global_load_dwordx4 v[24:27], v172, s[4:5] offset:2048 nt
	global_load_dwordx4 v[28:31], v172, s[4:5] offset:3072 nt
	s_waitcnt vmcnt(8)
	s_branch .Lrm1_pfd_o

.Lrm1_pfd_o:
	v_lshlrev_b32_e32 v150, 16, v32
	v_and_b32_e32 v151, 0xffff0000, v32
	v_pk_mul_f32 v[158:159], v[150:151], v[150:151]
	v_lshlrev_b32_e32 v152, 16, v33
	v_and_b32_e32 v153, 0xffff0000, v33
	v_pk_mul_f32 v[160:161], v[152:153], v[152:153]
	v_lshlrev_b32_e32 v154, 16, v34
	v_and_b32_e32 v155, 0xffff0000, v34
	v_pk_fma_f32 v[158:159], v[154:155], v[154:155], v[158:159]
	v_lshlrev_b32_e32 v156, 16, v35
	v_and_b32_e32 v157, 0xffff0000, v35
	v_pk_fma_f32 v[160:161], v[156:157], v[156:157], v[160:161]
	v_lshlrev_b32_e32 v150, 16, v36
	v_and_b32_e32 v151, 0xffff0000, v36
	v_pk_fma_f32 v[158:159], v[150:151], v[150:151], v[158:159]
	v_lshlrev_b32_e32 v152, 16, v37
	v_and_b32_e32 v153, 0xffff0000, v37
	v_pk_fma_f32 v[160:161], v[152:153], v[152:153], v[160:161]
	v_lshlrev_b32_e32 v154, 16, v38
	v_and_b32_e32 v155, 0xffff0000, v38
	v_pk_fma_f32 v[158:159], v[154:155], v[154:155], v[158:159]
	v_lshlrev_b32_e32 v156, 16, v39
	v_and_b32_e32 v157, 0xffff0000, v39
	v_pk_fma_f32 v[160:161], v[156:157], v[156:157], v[160:161]
	v_lshlrev_b32_e32 v150, 16, v40
	v_and_b32_e32 v151, 0xffff0000, v40
	v_pk_fma_f32 v[158:159], v[150:151], v[150:151], v[158:159]
	v_lshlrev_b32_e32 v152, 16, v41
	v_and_b32_e32 v153, 0xffff0000, v41
	v_pk_fma_f32 v[160:161], v[152:153], v[152:153], v[160:161]
	v_lshlrev_b32_e32 v154, 16, v42
	v_and_b32_e32 v155, 0xffff0000, v42
	v_pk_fma_f32 v[158:159], v[154:155], v[154:155], v[158:159]
	v_lshlrev_b32_e32 v156, 16, v43
	v_and_b32_e32 v157, 0xffff0000, v43
	v_pk_fma_f32 v[160:161], v[156:157], v[156:157], v[160:161]
	v_lshlrev_b32_e32 v150, 16, v44
	v_and_b32_e32 v151, 0xffff0000, v44
	v_pk_fma_f32 v[158:159], v[150:151], v[150:151], v[158:159]
	v_lshlrev_b32_e32 v152, 16, v45
	v_and_b32_e32 v153, 0xffff0000, v45
	v_pk_fma_f32 v[160:161], v[152:153], v[152:153], v[160:161]
	v_lshlrev_b32_e32 v154, 16, v46
	v_and_b32_e32 v155, 0xffff0000, v46
	v_pk_fma_f32 v[158:159], v[154:155], v[154:155], v[158:159]
	v_lshlrev_b32_e32 v156, 16, v47
	v_and_b32_e32 v157, 0xffff0000, v47
	v_pk_fma_f32 v[160:161], v[156:157], v[156:157], v[160:161]
	v_pk_add_f32 v[158:159], v[158:159], v[160:161]
	s_nop 0
	v_add_f32_e32 v177, v158, v159
	s_nop 1
	v_add_f32_dpp v177, v177, v177 quad_perm:[1,0,3,2] row_mask:0xf bank_mask:0xf
	s_nop 1
	v_add_f32_dpp v177, v177, v177 quad_perm:[2,3,0,1] row_mask:0xf bank_mask:0xf
	s_nop 1
	v_add_f32_dpp v177, v177, v177 row_half_mirror row_mask:0xf bank_mask:0xf
	s_nop 1
	v_add_f32_dpp v177, v177, v177 row_mirror row_mask:0xf bank_mask:0xf
	s_nop 1
	v_add_f32_dpp v177, v177, v177 row_bcast:15 row_mask:0xa bank_mask:0xf
	s_nop 1
	v_add_f32_dpp v177, v177, v177 row_bcast:31 row_mask:0xc bank_mask:0xf
	s_nop 1
	v_readlane_b32 s8, v177, 63
	s_nop 3
	v_mov_b32_e32 v162, s8
	v_fma_f32 v162, v162, v175, v176
	v_rsq_f32_e32 v162, v162
	s_nop 1
	v_lshlrev_b32_e32 v150, 16, v32
	v_and_b32_e32 v151, 0xffff0000, v32
	v_pk_mul_f32 v[150:151], v[150:151], v[162:163] op_sel_hi:[1,0]
	v_pk_fma_f32 v[192:193], v[48:49], v[150:151], v[192:193]
	v_lshlrev_b32_e32 v152, 16, v33
	v_and_b32_e32 v153, 0xffff0000, v33
	v_pk_mul_f32 v[152:153], v[152:153], v[162:163] op_sel_hi:[1,0]
	v_pk_fma_f32 v[194:195], v[50:51], v[152:153], v[194:195]
	v_lshlrev_b32_e32 v154, 16, v34
	v_and_b32_e32 v155, 0xffff0000, v34
	v_pk_mul_f32 v[154:155], v[154:155], v[162:163] op_sel_hi:[1,0]
	v_pk_fma_f32 v[196:197], v[52:53], v[154:155], v[196:197]
	v_lshlrev_b32_e32 v156, 16, v35
	v_and_b32_e32 v157, 0xffff0000, v35
	v_pk_mul_f32 v[156:157], v[156:157], v[162:163] op_sel_hi:[1,0]
	v_pk_fma_f32 v[198:199], v[54:55], v[156:157], v[198:199]
	v_lshlrev_b32_e32 v150, 16, v36
	v_and_b32_e32 v151, 0xffff0000, v36
	v_pk_mul_f32 v[150:151], v[150:151], v[162:163] op_sel_hi:[1,0]
	v_pk_fma_f32 v[200:201], v[56:57], v[150:151], v[200:201]
	v_lshlrev_b32_e32 v152, 16, v37
	v_and_b32_e32 v153, 0xffff0000, v37
	v_pk_mul_f32 v[152:153], v[152:153], v[162:163] op_sel_hi:[1,0]
	v_pk_fma_f32 v[202:203], v[58:59], v[152:153], v[202:203]
	v_lshlrev_b32_e32 v154, 16, v38
	v_and_b32_e32 v155, 0xffff0000, v38
	v_pk_mul_f32 v[154:155], v[154:155], v[162:163] op_sel_hi:[1,0]
	v_pk_fma_f32 v[204:205], v[60:61], v[154:155], v[204:205]
	v_lshlrev_b32_e32 v156, 16, v39
	v_and_b32_e32 v157, 0xffff0000, v39
	v_pk_mul_f32 v[156:157], v[156:157], v[162:163] op_sel_hi:[1,0]
	v_pk_fma_f32 v[206:207], v[62:63], v[156:157], v[206:207]
	v_lshlrev_b32_e32 v150, 16, v40
	v_and_b32_e32 v151, 0xffff0000, v40
	v_pk_mul_f32 v[150:151], v[150:151], v[162:163] op_sel_hi:[1,0]
	v_pk_fma_f32 v[208:209], v[64:65], v[150:151], v[208:209]
	v_lshlrev_b32_e32 v152, 16, v41
	v_and_b32_e32 v153, 0xffff0000, v41
	v_pk_mul_f32 v[152:153], v[152:153], v[162:163] op_sel_hi:[1,0]
	v_pk_fma_f32 v[210:211], v[66:67], v[152:153], v[210:211]
	v_lshlrev_b32_e32 v154, 16, v42
	v_and_b32_e32 v155, 0xffff0000, v42
	v_pk_mul_f32 v[154:155], v[154:155], v[162:163] op_sel_hi:[1,0]
	v_pk_fma_f32 v[216:217], v[68:69], v[154:155], v[216:217]
	v_lshlrev_b32_e32 v156, 16, v43
	v_and_b32_e32 v157, 0xffff0000, v43
	v_pk_mul_f32 v[156:157], v[156:157], v[162:163] op_sel_hi:[1,0]
	v_pk_fma_f32 v[218:219], v[70:71], v[156:157], v[218:219]
	v_lshlrev_b32_e32 v150, 16, v44
	v_and_b32_e32 v151, 0xffff0000, v44
	v_pk_mul_f32 v[150:151], v[150:151], v[162:163] op_sel_hi:[1,0]
	v_pk_fma_f32 v[224:225], v[72:73], v[150:151], v[224:225]
	v_lshlrev_b32_e32 v152, 16, v45
	v_and_b32_e32 v153, 0xffff0000, v45
	v_pk_mul_f32 v[152:153], v[152:153], v[162:163] op_sel_hi:[1,0]
	v_pk_fma_f32 v[226:227], v[74:75], v[152:153], v[226:227]
	v_lshlrev_b32_e32 v154, 16, v46
	v_and_b32_e32 v155, 0xffff0000, v46
	v_pk_mul_f32 v[154:155], v[154:155], v[162:163] op_sel_hi:[1,0]
	v_pk_fma_f32 v[236:237], v[82:83], v[154:155], v[236:237]
	v_lshlrev_b32_e32 v156, 16, v47
	v_and_b32_e32 v157, 0xffff0000, v47
	v_pk_mul_f32 v[156:157], v[156:157], v[162:163] op_sel_hi:[1,0]
	v_pk_fma_f32 v[238:239], v[84:85], v[156:157], v[238:239]
	s_nop 0
	global_store_dwordx4 v76, v[192:195], s[10:11] offset:0 nt
	global_store_dwordx4 v76, v[196:199], s[10:11] offset:1024 nt
	global_store_dwordx4 v76, v[200:203], s[10:11] offset:2048 nt
	global_store_dwordx4 v76, v[204:207], s[10:11] offset:3072 nt
	global_store_dwordx4 v172, v[208:211], s[10:11] offset:0 nt
	global_store_dwordx4 v172, v[216:219], s[10:11] offset:1024 nt
	global_store_dwordx4 v172, v[224:227], s[10:11] offset:2048 nt
	global_store_dwordx4 v172, v[236:239], s[10:11] offset:3072 nt
	v_pk_mul_f32 v[158:159], v[192:193], v[192:193]
	v_pk_mul_f32 v[160:161], v[194:195], v[194:195]
	v_pk_fma_f32 v[158:159], v[196:197], v[196:197], v[158:159]
	v_pk_fma_f32 v[160:161], v[198:199], v[198:199], v[160:161]
	v_pk_fma_f32 v[158:159], v[200:201], v[200:201], v[158:159]
	v_pk_fma_f32 v[160:161], v[202:203], v[202:203], v[160:161]
	v_pk_fma_f32 v[158:159], v[204:205], v[204:205], v[158:159]
	v_pk_fma_f32 v[160:161], v[206:207], v[206:207], v[160:161]
	v_pk_fma_f32 v[158:159], v[208:209], v[208:209], v[158:159]
	v_pk_fma_f32 v[160:161], v[210:211], v[210:211], v[160:161]
	v_pk_fma_f32 v[158:159], v[216:217], v[216:217], v[158:159]
	v_pk_fma_f32 v[160:161], v[218:219], v[218:219], v[160:161]
	v_pk_fma_f32 v[158:159], v[224:225], v[224:225], v[158:159]
	v_pk_fma_f32 v[160:161], v[226:227], v[226:227], v[160:161]
	v_pk_fma_f32 v[158:159], v[236:237], v[236:237], v[158:159]
	v_pk_fma_f32 v[160:161], v[238:239], v[238:239], v[160:161]
	v_pk_add_f32 v[158:159], v[158:159], v[160:161]
	s_nop 0
	v_add_f32_e32 v177, v158, v159
	s_nop 1
	v_add_f32_dpp v177, v177, v177 quad_perm:[1,0,3,2] row_mask:0xf bank_mask:0xf
	s_nop 1
	v_add_f32_dpp v177, v177, v177 quad_perm:[2,3,0,1] row_mask:0xf bank_mask:0xf
	s_nop 1
	v_add_f32_dpp v177, v177, v177 row_half_mirror row_mask:0xf bank_mask:0xf
	s_nop 1
	v_add_f32_dpp v177, v177, v177 row_mirror row_mask:0xf bank_mask:0xf
	s_nop 1
	v_add_f32_dpp v177, v177, v177 row_bcast:15 row_mask:0xa bank_mask:0xf
	s_nop 1
	v_add_f32_dpp v177, v177, v177 row_bcast:31 row_mask:0xc bank_mask:0xf
	s_nop 1
	v_readlane_b32 s8, v177, 63
	s_nop 3
	v_mov_b32_e32 v162, s8
	v_fma_f32 v162, v162, v175, v176
	v_rsq_f32_e32 v162, v162
	s_nop 1
	v_pk_mul_f32 v[150:151], v[192:193], v[162:163] op_sel_hi:[1,0]
	v_pk_fma_f32 v[150:151], v[150:151], v[86:87], v[118:119]
	v_cvt_pk_bf16_f32 v164, v150, v151
	v_pk_mul_f32 v[152:153], v[194:195], v[162:163] op_sel_hi:[1,0]
	v_pk_fma_f32 v[152:153], v[152:153], v[88:89], v[120:121]
	v_cvt_pk_bf16_f32 v165, v152, v153
	global_store_dwordx2 v173, v[164:165], s[14:15] offset:0 nt
	v_pk_mul_f32 v[154:155], v[196:197], v[162:163] op_sel_hi:[1,0]
	v_pk_fma_f32 v[154:155], v[154:155], v[90:91], v[122:123]
	v_cvt_pk_bf16_f32 v166, v154, v155
	v_pk_mul_f32 v[156:157], v[198:199], v[162:163] op_sel_hi:[1,0]
	v_pk_fma_f32 v[156:157], v[156:157], v[92:93], v[124:125]
	v_cvt_pk_bf16_f32 v167, v156, v157
	global_store_dwordx2 v173, v[166:167], s[14:15] offset:512 nt
	v_pk_mul_f32 v[150:151], v[200:201], v[162:163] op_sel_hi:[1,0]
	v_pk_fma_f32 v[150:151], v[150:151], v[94:95], v[126:127]
	v_cvt_pk_bf16_f32 v168, v150, v151
	v_pk_mul_f32 v[152:153], v[202:203], v[162:163] op_sel_hi:[1,0]
	v_pk_fma_f32 v[152:153], v[152:153], v[96:97], v[128:129]
	v_cvt_pk_bf16_f32 v169, v152, v153
	global_store_dwordx2 v173, v[168:169], s[14:15] offset:1024 nt
	v_pk_mul_f32 v[154:155], v[204:205], v[162:163] op_sel_hi:[1,0]
	v_pk_fma_f32 v[154:155], v[154:155], v[98:99], v[130:131]
	v_cvt_pk_bf16_f32 v170, v154, v155
	v_pk_mul_f32 v[156:157], v[206:207], v[162:163] op_sel_hi:[1,0]
	v_pk_fma_f32 v[156:157], v[156:157], v[100:101], v[132:133]
	v_cvt_pk_bf16_f32 v171, v156, v157
	global_store_dwordx2 v173, v[170:171], s[14:15] offset:1536 nt
	v_pk_mul_f32 v[150:151], v[208:209], v[162:163] op_sel_hi:[1,0]
	v_pk_fma_f32 v[150:151], v[150:151], v[102:103], v[134:135]
	v_cvt_pk_bf16_f32 v164, v150, v151
	v_pk_mul_f32 v[152:153], v[210:211], v[162:163] op_sel_hi:[1,0]
	v_pk_fma_f32 v[152:153], v[152:153], v[104:105], v[136:137]
	v_cvt_pk_bf16_f32 v165, v152, v153
	global_store_dwordx2 v173, v[164:165], s[14:15] offset:2048 nt
	v_pk_mul_f32 v[154:155], v[216:217], v[162:163] op_sel_hi:[1,0]
	v_pk_fma_f32 v[154:155], v[154:155], v[106:107], v[138:139]
	v_cvt_pk_bf16_f32 v166, v154, v155
	v_pk_mul_f32 v[156:157], v[218:219], v[162:163] op_sel_hi:[1,0]
	v_pk_fma_f32 v[156:157], v[156:157], v[108:109], v[140:141]
	v_cvt_pk_bf16_f32 v167, v156, v157
	global_store_dwordx2 v173, v[166:167], s[14:15] offset:2560 nt
	v_pk_mul_f32 v[150:151], v[224:225], v[162:163] op_sel_hi:[1,0]
	v_pk_fma_f32 v[150:151], v[150:151], v[110:111], v[142:143]
	v_cvt_pk_bf16_f32 v168, v150, v151
	v_pk_mul_f32 v[152:153], v[226:227], v[162:163] op_sel_hi:[1,0]
	v_pk_fma_f32 v[152:153], v[152:153], v[112:113], v[144:145]
	v_cvt_pk_bf16_f32 v169, v152, v153
	global_store_dwordx2 v173, v[168:169], s[14:15] offset:3072 nt
	v_pk_mul_f32 v[154:155], v[236:237], v[162:163] op_sel_hi:[1,0]
	v_pk_fma_f32 v[154:155], v[154:155], v[114:115], v[146:147]
	v_cvt_pk_bf16_f32 v170, v154, v155
	v_pk_mul_f32 v[156:157], v[238:239], v[162:163] op_sel_hi:[1,0]
	v_pk_fma_f32 v[156:157], v[156:157], v[116:117], v[148:149]
	v_cvt_pk_bf16_f32 v171, v156, v157
	global_store_dwordx2 v173, v[170:171], s[14:15] offset:3584 nt
	s_add_u32 s0, s0, 2
	s_cmp_lt_u32 s0, 16
	s_cbranch_scc1 .Lrm1_loop
	s_bitcmp1_b32 s3, 0
	s_cbranch_scc1 .Lrm1_done
	s_mov_b32 s2, 4
	s_branch .Lrm1_coef
.Lrm1_ctxrow:
	s_lshr_b32 s8, s3, 1
	s_lshl_b32 s8, s8, 13
	v_readfirstlane_b32 s4, v180
	v_readfirstlane_b32 s5, v181
	s_nop 3
	s_add_u32 s4, s4, s8
	s_addc_u32 s5, s5, 0
	s_nop 1
	global_load_dwordx4 v[0:3], v76, s[4:5] offset:0 nt
	global_load_dwordx4 v[4:7], v76, s[4:5] offset:1024 nt
	global_load_dwordx4 v[8:11], v76, s[4:5] offset:2048 nt
	global_load_dwordx4 v[12:15], v76, s[4:5] offset:3072 nt
	global_load_dwordx4 v[16:19], v172, s[4:5] offset:0 nt
	global_load_dwordx4 v[20:23], v172, s[4:5] offset:1024 nt
	global_load_dwordx4 v[24:27], v172, s[4:5] offset:2048 nt
	global_load_dwordx4 v[28:31], v172, s[4:5] offset:3072 nt
	s_lshr_b32 s8, s3, 1
	s_add_u32 s1, s8, 0x8000
	s_lshl_b32 s8, s8, 13
	s_add_u32 s9, s8, 0x3d000000
	s_add_u32 s10, s52, s9
	s_addc_u32 s11, s53, 0
	s_lshl_b32 s8, s1, 12
	s_add_u32 s9, s8, 0xb800000
	s_add_u32 s12, s52, s9
	s_addc_u32 s13, s53, 0
	s_add_u32 s9, s8, 0x2c800000
	s_add_u32 s14, s52, s9
	s_addc_u32 s15, s53, 0
	global_load_dwordx2 v[32:33], v173, s[12:13] offset:0 nt
	global_load_dwordx2 v[34:35], v173, s[12:13] offset:512 nt
	global_load_dwordx2 v[36:37], v173, s[12:13] offset:1024 nt
	global_load_dwordx2 v[38:39], v173, s[12:13] offset:1536 nt
	global_load_dwordx2 v[40:41], v173, s[12:13] offset:2048 nt
	global_load_dwordx2 v[42:43], v173, s[12:13] offset:2560 nt
	global_load_dwordx2 v[44:45], v173, s[12:13] offset:3072 nt
	global_load_dwordx2 v[46:47], v173, s[12:13] offset:3584 nt
	s_waitcnt vmcnt(0)
	v_lshlrev_b32_e32 v150, 16, v32
	v_and_b32_e32 v151, 0xffff0000, v32
	v_pk_mul_f32 v[158:159], v[150:151], v[150:151]
	v_lshlrev_b32_e32 v152, 16, v33
	v_and_b32_e32 v153, 0xffff0000, v33
	v_pk_mul_f32 v[160:161], v[152:153], v[152:153]
	v_lshlrev_b32_e32 v154, 16, v34
	v_and_b32_e32 v155, 0xffff0000, v34
	v_pk_fma_f32 v[158:159], v[154:155], v[154:155], v[158:159]
	v_lshlrev_b32_e32 v156, 16, v35
	v_and_b32_e32 v157, 0xffff0000, v35
	v_pk_fma_f32 v[160:161], v[156:157], v[156:157], v[160:161]
	v_lshlrev_b32_e32 v150, 16, v36
	v_and_b32_e32 v151, 0xffff0000, v36
	v_pk_fma_f32 v[158:159], v[150:151], v[150:151], v[158:159]
	v_lshlrev_b32_e32 v152, 16, v37
	v_and_b32_e32 v153, 0xffff0000, v37
	v_pk_fma_f32 v[160:161], v[152:153], v[152:153], v[160:161]
	v_lshlrev_b32_e32 v154, 16, v38
	v_and_b32_e32 v155, 0xffff0000, v38
	v_pk_fma_f32 v[158:159], v[154:155], v[154:155], v[158:159]
	v_lshlrev_b32_e32 v156, 16, v39
	v_and_b32_e32 v157, 0xffff0000, v39
	v_pk_fma_f32 v[160:161], v[156:157], v[156:157], v[160:161]
	v_lshlrev_b32_e32 v150, 16, v40
	v_and_b32_e32 v151, 0xffff0000, v40
	v_pk_fma_f32 v[158:159], v[150:151], v[150:151], v[158:159]
	v_lshlrev_b32_e32 v152, 16, v41
	v_and_b32_e32 v153, 0xffff0000, v41
	v_pk_fma_f32 v[160:161], v[152:153], v[152:153], v[160:161]
	v_lshlrev_b32_e32 v154, 16, v42
	v_and_b32_e32 v155, 0xffff0000, v42
	v_pk_fma_f32 v[158:159], v[154:155], v[154:155], v[158:159]
	v_lshlrev_b32_e32 v156, 16, v43
	v_and_b32_e32 v157, 0xffff0000, v43
	v_pk_fma_f32 v[160:161], v[156:157], v[156:157], v[160:161]
	v_lshlrev_b32_e32 v150, 16, v44
	v_and_b32_e32 v151, 0xffff0000, v44
	v_pk_fma_f32 v[158:159], v[150:151], v[150:151], v[158:159]
	v_lshlrev_b32_e32 v152, 16, v45
	v_and_b32_e32 v153, 0xffff0000, v45
	v_pk_fma_f32 v[160:161], v[152:153], v[152:153], v[160:161]
	v_lshlrev_b32_e32 v154, 16, v46
	v_and_b32_e32 v155, 0xffff0000, v46
	v_pk_fma_f32 v[158:159], v[154:155], v[154:155], v[158:159]
	v_lshlrev_b32_e32 v156, 16, v47
	v_and_b32_e32 v157, 0xffff0000, v47
	v_pk_fma_f32 v[160:161], v[156:157], v[156:157], v[160:161]
	v_pk_add_f32 v[158:159], v[158:159], v[160:161]
	s_nop 0
	v_add_f32_e32 v177, v158, v159
	s_nop 1
	v_add_f32_dpp v177, v177, v177 quad_perm:[1,0,3,2] row_mask:0xf bank_mask:0xf
	s_nop 1
	v_add_f32_dpp v177, v177, v177 quad_perm:[2,3,0,1] row_mask:0xf bank_mask:0xf
	s_nop 1
	v_add_f32_dpp v177, v177, v177 row_half_mirror row_mask:0xf bank_mask:0xf
	s_nop 1
	v_add_f32_dpp v177, v177, v177 row_mirror row_mask:0xf bank_mask:0xf
	s_nop 1
	v_add_f32_dpp v177, v177, v177 row_bcast:15 row_mask:0xa bank_mask:0xf
	s_nop 1
	v_add_f32_dpp v177, v177, v177 row_bcast:31 row_mask:0xc bank_mask:0xf
	s_nop 1
	v_readlane_b32 s8, v177, 63
	s_nop 3
	v_mov_b32_e32 v162, s8
	v_fma_f32 v162, v162, v175, v176
	v_rsq_f32_e32 v162, v162
	s_nop 1
	v_lshlrev_b32_e32 v150, 16, v32
	v_and_b32_e32 v151, 0xffff0000, v32
	v_pk_mul_f32 v[150:151], v[150:151], v[162:163] op_sel_hi:[1,0]
	v_pk_fma_f32 v[0:1], v[48:49], v[150:151], v[0:1]
	v_lshlrev_b32_e32 v152, 16, v33
	v_and_b32_e32 v153, 0xffff0000, v33
	v_pk_mul_f32 v[152:153], v[152:153], v[162:163] op_sel_hi:[1,0]
	v_pk_fma_f32 v[2:3], v[50:51], v[152:153], v[2:3]
	v_lshlrev_b32_e32 v154, 16, v34
	v_and_b32_e32 v155, 0xffff0000, v34
	v_pk_mul_f32 v[154:155], v[154:155], v[162:163] op_sel_hi:[1,0]
	v_pk_fma_f32 v[4:5], v[52:53], v[154:155], v[4:5]
	v_lshlrev_b32_e32 v156, 16, v35
	v_and_b32_e32 v157, 0xffff0000, v35
	v_pk_mul_f32 v[156:157], v[156:157], v[162:163] op_sel_hi:[1,0]
	v_pk_fma_f32 v[6:7], v[54:55], v[156:157], v[6:7]
	v_lshlrev_b32_e32 v150, 16, v36
	v_and_b32_e32 v151, 0xffff0000, v36
	v_pk_mul_f32 v[150:151], v[150:151], v[162:163] op_sel_hi:[1,0]
	v_pk_fma_f32 v[8:9], v[56:57], v[150:151], v[8:9]
	v_lshlrev_b32_e32 v152, 16, v37
	v_and_b32_e32 v153, 0xffff0000, v37
	v_pk_mul_f32 v[152:153], v[152:153], v[162:163] op_sel_hi:[1,0]
	v_pk_fma_f32 v[10:11], v[58:59], v[152:153], v[10:11]
	v_lshlrev_b32_e32 v154, 16, v38
	v_and_b32_e32 v155, 0xffff0000, v38
	v_pk_mul_f32 v[154:155], v[154:155], v[162:163] op_sel_hi:[1,0]
	v_pk_fma_f32 v[12:13], v[60:61], v[154:155], v[12:13]
	v_lshlrev_b32_e32 v156, 16, v39
	v_and_b32_e32 v157, 0xffff0000, v39
	v_pk_mul_f32 v[156:157], v[156:157], v[162:163] op_sel_hi:[1,0]
	v_pk_fma_f32 v[14:15], v[62:63], v[156:157], v[14:15]
	v_lshlrev_b32_e32 v150, 16, v40
	v_and_b32_e32 v151, 0xffff0000, v40
	v_pk_mul_f32 v[150:151], v[150:151], v[162:163] op_sel_hi:[1,0]
	v_pk_fma_f32 v[16:17], v[64:65], v[150:151], v[16:17]
	v_lshlrev_b32_e32 v152, 16, v41
	v_and_b32_e32 v153, 0xffff0000, v41
	v_pk_mul_f32 v[152:153], v[152:153], v[162:163] op_sel_hi:[1,0]
	v_pk_fma_f32 v[18:19], v[66:67], v[152:153], v[18:19]
	v_lshlrev_b32_e32 v154, 16, v42
	v_and_b32_e32 v155, 0xffff0000, v42
	v_pk_mul_f32 v[154:155], v[154:155], v[162:163] op_sel_hi:[1,0]
	v_pk_fma_f32 v[20:21], v[68:69], v[154:155], v[20:21]
	v_lshlrev_b32_e32 v156, 16, v43
	v_and_b32_e32 v157, 0xffff0000, v43
	v_pk_mul_f32 v[156:157], v[156:157], v[162:163] op_sel_hi:[1,0]
	v_pk_fma_f32 v[22:23], v[70:71], v[156:157], v[22:23]
	v_lshlrev_b32_e32 v150, 16, v44
	v_and_b32_e32 v151, 0xffff0000, v44
	v_pk_mul_f32 v[150:151], v[150:151], v[162:163] op_sel_hi:[1,0]
	v_pk_fma_f32 v[24:25], v[72:73], v[150:151], v[24:25]
	v_lshlrev_b32_e32 v152, 16, v45
	v_and_b32_e32 v153, 0xffff0000, v45
	v_pk_mul_f32 v[152:153], v[152:153], v[162:163] op_sel_hi:[1,0]
	v_pk_fma_f32 v[26:27], v[74:75], v[152:153], v[26:27]
	v_lshlrev_b32_e32 v154, 16, v46
	v_and_b32_e32 v155, 0xffff0000, v46
	v_pk_mul_f32 v[154:155], v[154:155], v[162:163] op_sel_hi:[1,0]
	v_pk_fma_f32 v[28:29], v[82:83], v[154:155], v[28:29]
	v_lshlrev_b32_e32 v156, 16, v47
	v_and_b32_e32 v157, 0xffff0000, v47
	v_pk_mul_f32 v[156:157], v[156:157], v[162:163] op_sel_hi:[1,0]
	v_pk_fma_f32 v[30:31], v[84:85], v[156:157], v[30:31]
	s_nop 0
	global_store_dwordx4 v76, v[0:3], s[10:11] offset:0 nt
	global_store_dwordx4 v76, v[4:7], s[10:11] offset:1024 nt
	global_store_dwordx4 v76, v[8:11], s[10:11] offset:2048 nt
	global_store_dwordx4 v76, v[12:15], s[10:11] offset:3072 nt
	global_store_dwordx4 v172, v[16:19], s[10:11] offset:0 nt
	global_store_dwordx4 v172, v[20:23], s[10:11] offset:1024 nt
	global_store_dwordx4 v172, v[24:27], s[10:11] offset:2048 nt
	global_store_dwordx4 v172, v[28:31], s[10:11] offset:3072 nt
	v_pk_mul_f32 v[158:159], v[0:1], v[0:1]
	v_pk_mul_f32 v[160:161], v[2:3], v[2:3]
	v_pk_fma_f32 v[158:159], v[4:5], v[4:5], v[158:159]
	v_pk_fma_f32 v[160:161], v[6:7], v[6:7], v[160:161]
	v_pk_fma_f32 v[158:159], v[8:9], v[8:9], v[158:159]
	v_pk_fma_f32 v[160:161], v[10:11], v[10:11], v[160:161]
	v_pk_fma_f32 v[158:159], v[12:13], v[12:13], v[158:159]
	v_pk_fma_f32 v[160:161], v[14:15], v[14:15], v[160:161]
	v_pk_fma_f32 v[158:159], v[16:17], v[16:17], v[158:159]
	v_pk_fma_f32 v[160:161], v[18:19], v[18:19], v[160:161]
	v_pk_fma_f32 v[158:159], v[20:21], v[20:21], v[158:159]
	v_pk_fma_f32 v[160:161], v[22:23], v[22:23], v[160:161]
	v_pk_fma_f32 v[158:159], v[24:25], v[24:25], v[158:159]
	v_pk_fma_f32 v[160:161], v[26:27], v[26:27], v[160:161]
	v_pk_fma_f32 v[158:159], v[28:29], v[28:29], v[158:159]
	v_pk_fma_f32 v[160:161], v[30:31], v[30:31], v[160:161]
	v_pk_add_f32 v[158:159], v[158:159], v[160:161]
	s_nop 0
	v_add_f32_e32 v177, v158, v159
	s_nop 1
	v_add_f32_dpp v177, v177, v177 quad_perm:[1,0,3,2] row_mask:0xf bank_mask:0xf
	s_nop 1
	v_add_f32_dpp v177, v177, v177 quad_perm:[2,3,0,1] row_mask:0xf bank_mask:0xf
	s_nop 1
	v_add_f32_dpp v177, v177, v177 row_half_mirror row_mask:0xf bank_mask:0xf
	s_nop 1
	v_add_f32_dpp v177, v177, v177 row_mirror row_mask:0xf bank_mask:0xf
	s_nop 1
	v_add_f32_dpp v177, v177, v177 row_bcast:15 row_mask:0xa bank_mask:0xf
	s_nop 1
	v_add_f32_dpp v177, v177, v177 row_bcast:31 row_mask:0xc bank_mask:0xf
	s_nop 1
	v_readlane_b32 s8, v177, 63
	s_nop 3
	v_mov_b32_e32 v162, s8
	v_fma_f32 v162, v162, v175, v176
	v_rsq_f32_e32 v162, v162
	s_nop 1
	v_pk_mul_f32 v[150:151], v[0:1], v[162:163] op_sel_hi:[1,0]
	v_pk_fma_f32 v[150:151], v[150:151], v[86:87], v[118:119]
	v_cvt_pk_bf16_f32 v164, v150, v151
	v_pk_mul_f32 v[152:153], v[2:3], v[162:163] op_sel_hi:[1,0]
	v_pk_fma_f32 v[152:153], v[152:153], v[88:89], v[120:121]
	v_cvt_pk_bf16_f32 v165, v152, v153
	global_store_dwordx2 v173, v[164:165], s[14:15] offset:0 nt
	v_pk_mul_f32 v[154:155], v[4:5], v[162:163] op_sel_hi:[1,0]
	v_pk_fma_f32 v[154:155], v[154:155], v[90:91], v[122:123]
	v_cvt_pk_bf16_f32 v166, v154, v155
	v_pk_mul_f32 v[156:157], v[6:7], v[162:163] op_sel_hi:[1,0]
	v_pk_fma_f32 v[156:157], v[156:157], v[92:93], v[124:125]
	v_cvt_pk_bf16_f32 v167, v156, v157
	global_store_dwordx2 v173, v[166:167], s[14:15] offset:512 nt
	v_pk_mul_f32 v[150:151], v[8:9], v[162:163] op_sel_hi:[1,0]
	v_pk_fma_f32 v[150:151], v[150:151], v[94:95], v[126:127]
	v_cvt_pk_bf16_f32 v168, v150, v151
	v_pk_mul_f32 v[152:153], v[10:11], v[162:163] op_sel_hi:[1,0]
	v_pk_fma_f32 v[152:153], v[152:153], v[96:97], v[128:129]
	v_cvt_pk_bf16_f32 v169, v152, v153
	global_store_dwordx2 v173, v[168:169], s[14:15] offset:1024 nt
	v_pk_mul_f32 v[154:155], v[12:13], v[162:163] op_sel_hi:[1,0]
	v_pk_fma_f32 v[154:155], v[154:155], v[98:99], v[130:131]
	v_cvt_pk_bf16_f32 v170, v154, v155
	v_pk_mul_f32 v[156:157], v[14:15], v[162:163] op_sel_hi:[1,0]
	v_pk_fma_f32 v[156:157], v[156:157], v[100:101], v[132:133]
	v_cvt_pk_bf16_f32 v171, v156, v157
	global_store_dwordx2 v173, v[170:171], s[14:15] offset:1536 nt
	v_pk_mul_f32 v[150:151], v[16:17], v[162:163] op_sel_hi:[1,0]
	v_pk_fma_f32 v[150:151], v[150:151], v[102:103], v[134:135]
	v_cvt_pk_bf16_f32 v164, v150, v151
	v_pk_mul_f32 v[152:153], v[18:19], v[162:163] op_sel_hi:[1,0]
	v_pk_fma_f32 v[152:153], v[152:153], v[104:105], v[136:137]
	v_cvt_pk_bf16_f32 v165, v152, v153
	global_store_dwordx2 v173, v[164:165], s[14:15] offset:2048 nt
	v_pk_mul_f32 v[154:155], v[20:21], v[162:163] op_sel_hi:[1,0]
	v_pk_fma_f32 v[154:155], v[154:155], v[106:107], v[138:139]
	v_cvt_pk_bf16_f32 v166, v154, v155
	v_pk_mul_f32 v[156:157], v[22:23], v[162:163] op_sel_hi:[1,0]
	v_pk_fma_f32 v[156:157], v[156:157], v[108:109], v[140:141]
	v_cvt_pk_bf16_f32 v167, v156, v157
	global_store_dwordx2 v173, v[166:167], s[14:15] offset:2560 nt
	v_pk_mul_f32 v[150:151], v[24:25], v[162:163] op_sel_hi:[1,0]
	v_pk_fma_f32 v[150:151], v[150:151], v[110:111], v[142:143]
	v_cvt_pk_bf16_f32 v168, v150, v151
	v_pk_mul_f32 v[152:153], v[26:27], v[162:163] op_sel_hi:[1,0]
	v_pk_fma_f32 v[152:153], v[152:153], v[112:113], v[144:145]
	v_cvt_pk_bf16_f32 v169, v152, v153
	global_store_dwordx2 v173, v[168:169], s[14:15] offset:3072 nt
	v_pk_mul_f32 v[154:155], v[28:29], v[162:163] op_sel_hi:[1,0]
	v_pk_fma_f32 v[154:155], v[154:155], v[114:115], v[146:147]
	v_cvt_pk_bf16_f32 v170, v154, v155
	v_pk_mul_f32 v[156:157], v[30:31], v[162:163] op_sel_hi:[1,0]
	v_pk_fma_f32 v[156:157], v[156:157], v[116:117], v[148:149]
	v_cvt_pk_bf16_f32 v171, v156, v157
	global_store_dwordx2 v173, v[170:171], s[14:15] offset:3584 nt

.Lrm2_loop:
	s_lshr_b32 s1, s5, 9
	s_lshl_b32 s1, s1, 13
	s_and_b32 s8, s5, 0x1ff
	s_add_u32 s1, s1, s8
	s_add_u32 s8, s0, 0
	s_lshl_b32 s8, s8, 9
	s_add_u32 s1, s1, s8
	s_lshl_b32 s8, s1, 13
	s_add_u32 s10, s58, s8
	s_addc_u32 s11, s59, 0
	s_lshl_b32 s8, s1, 12
	s_add_u32 s9, s8, 0x34c00000
	s_add_u32 s12, s52, s9
	s_addc_u32 s13, s53, 0
	s_add_u32 s9, s8, 0x2c800000
	s_add_u32 s14, s52, s9
	s_addc_u32 s15, s53, 0
	global_load_dwordx2 v[32:33], v169, s[12:13] offset:0 nt
	global_load_dwordx2 v[34:35], v169, s[12:13] offset:512 nt
	global_load_dwordx2 v[36:37], v169, s[12:13] offset:1024 nt
	global_load_dwordx2 v[38:39], v169, s[12:13] offset:1536 nt
	global_load_dwordx2 v[40:41], v169, s[12:13] offset:2048 nt
	global_load_dwordx2 v[42:43], v169, s[12:13] offset:2560 nt
	global_load_dwordx2 v[44:45], v169, s[12:13] offset:3072 nt
	global_load_dwordx2 v[46:47], v169, s[12:13] offset:3584 nt
	s_lshr_b32 s1, s5, 9
	s_lshl_b32 s1, s1, 13
	s_and_b32 s8, s5, 0x1ff
	s_add_u32 s1, s1, s8
	s_add_u32 s8, s0, 1
	s_lshl_b32 s8, s8, 9
	s_add_u32 s1, s1, s8
	s_lshl_b32 s8, s1, 13
	s_add_u32 s6, s58, s8
	s_addc_u32 s7, s59, 0
	global_load_dwordx4 v[178:181], v80, s[6:7] offset:0 nt
	global_load_dwordx4 v[182:185], v80, s[6:7] offset:1024 nt
	global_load_dwordx4 v[194:197], v80, s[6:7] offset:2048 nt
	global_load_dwordx4 v[198:201], v80, s[6:7] offset:3072 nt
	global_load_dwordx4 v[202:205], v168, s[6:7] offset:0 nt
	global_load_dwordx4 v[206:209], v168, s[6:7] offset:1024 nt
	global_load_dwordx4 v[210:213], v168, s[6:7] offset:2048 nt
	global_load_dwordx4 v[218:221], v168, s[6:7] offset:3072 nt
	s_waitcnt vmcnt(8)
	v_lshlrev_b32_e32 v146, 16, v32
	v_and_b32_e32 v147, 0xffff0000, v32
	v_pk_mul_f32 v[154:155], v[146:147], v[146:147]
	v_lshlrev_b32_e32 v148, 16, v33
	v_and_b32_e32 v149, 0xffff0000, v33
	v_pk_mul_f32 v[156:157], v[148:149], v[148:149]
	v_lshlrev_b32_e32 v150, 16, v34
	v_and_b32_e32 v151, 0xffff0000, v34
	v_pk_fma_f32 v[154:155], v[150:151], v[150:151], v[154:155]
	v_lshlrev_b32_e32 v152, 16, v35
	v_and_b32_e32 v153, 0xffff0000, v35
	v_pk_fma_f32 v[156:157], v[152:153], v[152:153], v[156:157]
	v_lshlrev_b32_e32 v146, 16, v36
	v_and_b32_e32 v147, 0xffff0000, v36
	v_pk_fma_f32 v[154:155], v[146:147], v[146:147], v[154:155]
	v_lshlrev_b32_e32 v148, 16, v37
	v_and_b32_e32 v149, 0xffff0000, v37
	v_pk_fma_f32 v[156:157], v[148:149], v[148:149], v[156:157]
	v_lshlrev_b32_e32 v150, 16, v38
	v_and_b32_e32 v151, 0xffff0000, v38
	v_pk_fma_f32 v[154:155], v[150:151], v[150:151], v[154:155]
	v_lshlrev_b32_e32 v152, 16, v39
	v_and_b32_e32 v153, 0xffff0000, v39
	v_pk_fma_f32 v[156:157], v[152:153], v[152:153], v[156:157]
	v_lshlrev_b32_e32 v146, 16, v40
	v_and_b32_e32 v147, 0xffff0000, v40
	v_pk_fma_f32 v[154:155], v[146:147], v[146:147], v[154:155]
	v_lshlrev_b32_e32 v148, 16, v41
	v_and_b32_e32 v149, 0xffff0000, v41
	v_pk_fma_f32 v[156:157], v[148:149], v[148:149], v[156:157]
	v_lshlrev_b32_e32 v150, 16, v42
	v_and_b32_e32 v151, 0xffff0000, v42
	v_pk_fma_f32 v[154:155], v[150:151], v[150:151], v[154:155]
	v_lshlrev_b32_e32 v152, 16, v43
	v_and_b32_e32 v153, 0xffff0000, v43
	v_pk_fma_f32 v[156:157], v[152:153], v[152:153], v[156:157]
	v_lshlrev_b32_e32 v146, 16, v44
	v_and_b32_e32 v147, 0xffff0000, v44
	v_pk_fma_f32 v[154:155], v[146:147], v[146:147], v[154:155]
	v_lshlrev_b32_e32 v148, 16, v45
	v_and_b32_e32 v149, 0xffff0000, v45
	v_pk_fma_f32 v[156:157], v[148:149], v[148:149], v[156:157]
	v_lshlrev_b32_e32 v150, 16, v46
	v_and_b32_e32 v151, 0xffff0000, v46
	v_pk_fma_f32 v[154:155], v[150:151], v[150:151], v[154:155]
	v_lshlrev_b32_e32 v152, 16, v47
	v_and_b32_e32 v153, 0xffff0000, v47
	v_pk_fma_f32 v[156:157], v[152:153], v[152:153], v[156:157]
	v_pk_add_f32 v[154:155], v[154:155], v[156:157]
	s_nop 0
	v_add_f32_e32 v173, v154, v155
	s_nop 1
	v_add_f32_dpp v173, v173, v173 quad_perm:[1,0,3,2] row_mask:0xf bank_mask:0xf
	s_nop 1
	v_add_f32_dpp v173, v173, v173 quad_perm:[2,3,0,1] row_mask:0xf bank_mask:0xf
	s_nop 1
	v_add_f32_dpp v173, v173, v173 row_half_mirror row_mask:0xf bank_mask:0xf
	s_nop 1
	v_add_f32_dpp v173, v173, v173 row_mirror row_mask:0xf bank_mask:0xf
	s_nop 1
	v_add_f32_dpp v173, v173, v173 row_bcast:15 row_mask:0xa bank_mask:0xf
	s_nop 1
	v_add_f32_dpp v173, v173, v173 row_bcast:31 row_mask:0xc bank_mask:0xf
	s_nop 1
	v_readlane_b32 s8, v173, 63
	s_nop 3
	v_mov_b32_e32 v158, s8
	v_fma_f32 v158, v158, v171, v172
	v_rsq_f32_e32 v158, v158
	s_nop 1
	v_lshlrev_b32_e32 v146, 16, v32
	v_and_b32_e32 v147, 0xffff0000, v32
	v_pk_mul_f32 v[146:147], v[146:147], v[158:159] op_sel_hi:[1,0]
	v_pk_fma_f32 v[0:1], v[48:49], v[146:147], v[0:1]
	v_lshlrev_b32_e32 v148, 16, v33
	v_and_b32_e32 v149, 0xffff0000, v33
	v_pk_mul_f32 v[148:149], v[148:149], v[158:159] op_sel_hi:[1,0]
	v_pk_fma_f32 v[2:3], v[50:51], v[148:149], v[2:3]
	v_lshlrev_b32_e32 v150, 16, v34
	v_and_b32_e32 v151, 0xffff0000, v34
	v_pk_mul_f32 v[150:151], v[150:151], v[158:159] op_sel_hi:[1,0]
	v_pk_fma_f32 v[4:5], v[52:53], v[150:151], v[4:5]
	v_lshlrev_b32_e32 v152, 16, v35
	v_and_b32_e32 v153, 0xffff0000, v35
	v_pk_mul_f32 v[152:153], v[152:153], v[158:159] op_sel_hi:[1,0]
	v_pk_fma_f32 v[6:7], v[54:55], v[152:153], v[6:7]
	v_lshlrev_b32_e32 v146, 16, v36
	v_and_b32_e32 v147, 0xffff0000, v36
	v_pk_mul_f32 v[146:147], v[146:147], v[158:159] op_sel_hi:[1,0]
	v_pk_fma_f32 v[8:9], v[56:57], v[146:147], v[8:9]
	v_lshlrev_b32_e32 v148, 16, v37
	v_and_b32_e32 v149, 0xffff0000, v37
	v_pk_mul_f32 v[148:149], v[148:149], v[158:159] op_sel_hi:[1,0]
	v_pk_fma_f32 v[10:11], v[58:59], v[148:149], v[10:11]
	v_lshlrev_b32_e32 v150, 16, v38
	v_and_b32_e32 v151, 0xffff0000, v38
	v_pk_mul_f32 v[150:151], v[150:151], v[158:159] op_sel_hi:[1,0]
	v_pk_fma_f32 v[12:13], v[60:61], v[150:151], v[12:13]
	v_lshlrev_b32_e32 v152, 16, v39
	v_and_b32_e32 v153, 0xffff0000, v39
	v_pk_mul_f32 v[152:153], v[152:153], v[158:159] op_sel_hi:[1,0]
	v_pk_fma_f32 v[14:15], v[62:63], v[152:153], v[14:15]
	v_lshlrev_b32_e32 v146, 16, v40
	v_and_b32_e32 v147, 0xffff0000, v40
	v_pk_mul_f32 v[146:147], v[146:147], v[158:159] op_sel_hi:[1,0]
	v_pk_fma_f32 v[16:17], v[64:65], v[146:147], v[16:17]
	v_lshlrev_b32_e32 v148, 16, v41
	v_and_b32_e32 v149, 0xffff0000, v41
	v_pk_mul_f32 v[148:149], v[148:149], v[158:159] op_sel_hi:[1,0]
	v_pk_fma_f32 v[18:19], v[66:67], v[148:149], v[18:19]
	v_lshlrev_b32_e32 v150, 16, v42
	v_and_b32_e32 v151, 0xffff0000, v42
	v_pk_mul_f32 v[150:151], v[150:151], v[158:159] op_sel_hi:[1,0]
	v_pk_fma_f32 v[20:21], v[68:69], v[150:151], v[20:21]
	v_lshlrev_b32_e32 v152, 16, v43
	v_and_b32_e32 v153, 0xffff0000, v43
	v_pk_mul_f32 v[152:153], v[152:153], v[158:159] op_sel_hi:[1,0]
	v_pk_fma_f32 v[22:23], v[70:71], v[152:153], v[22:23]
	v_lshlrev_b32_e32 v146, 16, v44
	v_and_b32_e32 v147, 0xffff0000, v44
	v_pk_mul_f32 v[146:147], v[146:147], v[158:159] op_sel_hi:[1,0]
	v_pk_fma_f32 v[24:25], v[72:73], v[146:147], v[24:25]
	v_lshlrev_b32_e32 v148, 16, v45
	v_and_b32_e32 v149, 0xffff0000, v45
	v_pk_mul_f32 v[148:149], v[148:149], v[158:159] op_sel_hi:[1,0]
	v_pk_fma_f32 v[26:27], v[74:75], v[148:149], v[26:27]
	v_lshlrev_b32_e32 v150, 16, v46
	v_and_b32_e32 v151, 0xffff0000, v46
	v_pk_mul_f32 v[150:151], v[150:151], v[158:159] op_sel_hi:[1,0]
	v_pk_fma_f32 v[28:29], v[76:77], v[150:151], v[28:29]
	v_lshlrev_b32_e32 v152, 16, v47
	v_and_b32_e32 v153, 0xffff0000, v47
	v_pk_mul_f32 v[152:153], v[152:153], v[158:159] op_sel_hi:[1,0]
	v_pk_fma_f32 v[30:31], v[78:79], v[152:153], v[30:31]
	s_nop 0
	global_store_dwordx4 v80, v[0:3], s[10:11] offset:0 nt
	global_store_dwordx4 v80, v[4:7], s[10:11] offset:1024 nt
	global_store_dwordx4 v80, v[8:11], s[10:11] offset:2048 nt
	global_store_dwordx4 v80, v[12:15], s[10:11] offset:3072 nt
	global_store_dwordx4 v168, v[16:19], s[10:11] offset:0 nt
	global_store_dwordx4 v168, v[20:23], s[10:11] offset:1024 nt
	global_store_dwordx4 v168, v[24:27], s[10:11] offset:2048 nt
	global_store_dwordx4 v168, v[28:31], s[10:11] offset:3072 nt
	v_pk_mul_f32 v[154:155], v[0:1], v[0:1]
	v_pk_mul_f32 v[156:157], v[2:3], v[2:3]
	v_pk_fma_f32 v[154:155], v[4:5], v[4:5], v[154:155]
	v_pk_fma_f32 v[156:157], v[6:7], v[6:7], v[156:157]
	v_pk_fma_f32 v[154:155], v[8:9], v[8:9], v[154:155]
	v_pk_fma_f32 v[156:157], v[10:11], v[10:11], v[156:157]
	v_pk_fma_f32 v[154:155], v[12:13], v[12:13], v[154:155]
	v_pk_fma_f32 v[156:157], v[14:15], v[14:15], v[156:157]
	v_pk_fma_f32 v[154:155], v[16:17], v[16:17], v[154:155]
	v_pk_fma_f32 v[156:157], v[18:19], v[18:19], v[156:157]
	v_pk_fma_f32 v[154:155], v[20:21], v[20:21], v[154:155]
	v_pk_fma_f32 v[156:157], v[22:23], v[22:23], v[156:157]
	v_pk_fma_f32 v[154:155], v[24:25], v[24:25], v[154:155]
	v_pk_fma_f32 v[156:157], v[26:27], v[26:27], v[156:157]
	v_pk_fma_f32 v[154:155], v[28:29], v[28:29], v[154:155]
	v_pk_fma_f32 v[156:157], v[30:31], v[30:31], v[156:157]
	v_pk_add_f32 v[154:155], v[154:155], v[156:157]
	s_nop 0
	v_add_f32_e32 v173, v154, v155
	s_nop 1
	v_add_f32_dpp v173, v173, v173 quad_perm:[1,0,3,2] row_mask:0xf bank_mask:0xf
	s_nop 1
	v_add_f32_dpp v173, v173, v173 quad_perm:[2,3,0,1] row_mask:0xf bank_mask:0xf
	s_nop 1
	v_add_f32_dpp v173, v173, v173 row_half_mirror row_mask:0xf bank_mask:0xf
	s_nop 1
	v_add_f32_dpp v173, v173, v173 row_mirror row_mask:0xf bank_mask:0xf
	s_nop 1
	v_add_f32_dpp v173, v173, v173 row_bcast:15 row_mask:0xa bank_mask:0xf
	s_nop 1
	v_add_f32_dpp v173, v173, v173 row_bcast:31 row_mask:0xc bank_mask:0xf
	s_nop 1
	v_readlane_b32 s8, v173, 63
	s_nop 3
	v_mov_b32_e32 v158, s8
	v_fma_f32 v158, v158, v171, v172
	v_rsq_f32_e32 v158, v158
	s_nop 1
	v_pk_mul_f32 v[146:147], v[0:1], v[158:159] op_sel_hi:[1,0]
	v_pk_fma_f32 v[146:147], v[146:147], v[82:83], v[114:115]
	v_cvt_pk_bf16_f32 v160, v146, v147
	v_pk_mul_f32 v[148:149], v[2:3], v[158:159] op_sel_hi:[1,0]
	v_pk_fma_f32 v[148:149], v[148:149], v[84:85], v[116:117]
	v_cvt_pk_bf16_f32 v161, v148, v149
	global_store_dwordx2 v169, v[160:161], s[14:15] offset:0 nt
	v_pk_mul_f32 v[150:151], v[4:5], v[158:159] op_sel_hi:[1,0]
	v_pk_fma_f32 v[150:151], v[150:151], v[86:87], v[118:119]
	v_cvt_pk_bf16_f32 v162, v150, v151
	v_pk_mul_f32 v[152:153], v[6:7], v[158:159] op_sel_hi:[1,0]
	v_pk_fma_f32 v[152:153], v[152:153], v[88:89], v[120:121]
	v_cvt_pk_bf16_f32 v163, v152, v153
	global_store_dwordx2 v169, v[162:163], s[14:15] offset:512 nt
	v_pk_mul_f32 v[146:147], v[8:9], v[158:159] op_sel_hi:[1,0]
	v_pk_fma_f32 v[146:147], v[146:147], v[90:91], v[122:123]
	v_cvt_pk_bf16_f32 v164, v146, v147
	v_pk_mul_f32 v[148:149], v[10:11], v[158:159] op_sel_hi:[1,0]
	v_pk_fma_f32 v[148:149], v[148:149], v[92:93], v[124:125]
	v_cvt_pk_bf16_f32 v165, v148, v149
	global_store_dwordx2 v169, v[164:165], s[14:15] offset:1024 nt
	v_pk_mul_f32 v[150:151], v[12:13], v[158:159] op_sel_hi:[1,0]
	v_pk_fma_f32 v[150:151], v[150:151], v[94:95], v[126:127]
	v_cvt_pk_bf16_f32 v166, v150, v151
	v_pk_mul_f32 v[152:153], v[14:15], v[158:159] op_sel_hi:[1,0]
	v_pk_fma_f32 v[152:153], v[152:153], v[96:97], v[128:129]
	v_cvt_pk_bf16_f32 v167, v152, v153
	global_store_dwordx2 v169, v[166:167], s[14:15] offset:1536 nt
	v_pk_mul_f32 v[146:147], v[16:17], v[158:159] op_sel_hi:[1,0]
	v_pk_fma_f32 v[146:147], v[146:147], v[98:99], v[130:131]
	v_cvt_pk_bf16_f32 v160, v146, v147
	v_pk_mul_f32 v[148:149], v[18:19], v[158:159] op_sel_hi:[1,0]
	v_pk_fma_f32 v[148:149], v[148:149], v[100:101], v[132:133]
	v_cvt_pk_bf16_f32 v161, v148, v149
	global_store_dwordx2 v169, v[160:161], s[14:15] offset:2048 nt
	v_pk_mul_f32 v[150:151], v[20:21], v[158:159] op_sel_hi:[1,0]
	v_pk_fma_f32 v[150:151], v[150:151], v[102:103], v[134:135]
	v_cvt_pk_bf16_f32 v162, v150, v151
	v_pk_mul_f32 v[152:153], v[22:23], v[158:159] op_sel_hi:[1,0]
	v_pk_fma_f32 v[152:153], v[152:153], v[104:105], v[136:137]
	v_cvt_pk_bf16_f32 v163, v152, v153
	global_store_dwordx2 v169, v[162:163], s[14:15] offset:2560 nt
	v_pk_mul_f32 v[146:147], v[24:25], v[158:159] op_sel_hi:[1,0]
	v_pk_fma_f32 v[146:147], v[146:147], v[106:107], v[138:139]
	v_cvt_pk_bf16_f32 v164, v146, v147
	v_pk_mul_f32 v[148:149], v[26:27], v[158:159] op_sel_hi:[1,0]
	v_pk_fma_f32 v[148:149], v[148:149], v[108:109], v[140:141]
	v_cvt_pk_bf16_f32 v165, v148, v149
	global_store_dwordx2 v169, v[164:165], s[14:15] offset:3072 nt
	v_pk_mul_f32 v[150:151], v[28:29], v[158:159] op_sel_hi:[1,0]
	v_pk_fma_f32 v[150:151], v[150:151], v[110:111], v[142:143]
	v_cvt_pk_bf16_f32 v166, v150, v151
	v_pk_mul_f32 v[152:153], v[30:31], v[158:159] op_sel_hi:[1,0]
	v_pk_fma_f32 v[152:153], v[152:153], v[112:113], v[144:145]
	v_cvt_pk_bf16_f32 v167, v152, v153
	global_store_dwordx2 v169, v[166:167], s[14:15] offset:3584 nt
	s_lshr_b32 s1, s5, 9
	s_lshl_b32 s1, s1, 13
	s_and_b32 s8, s5, 0x1ff
	s_add_u32 s1, s1, s8
	s_add_u32 s8, s0, 1
	s_lshl_b32 s8, s8, 9
	s_add_u32 s1, s1, s8
	s_lshl_b32 s8, s1, 13
	s_add_u32 s10, s58, s8
	s_addc_u32 s11, s59, 0
	s_lshl_b32 s8, s1, 12
	s_add_u32 s9, s8, 0x34c00000
	s_add_u32 s12, s52, s9
	s_addc_u32 s13, s53, 0
	s_add_u32 s9, s8, 0x2c800000
	s_add_u32 s14, s52, s9
	s_addc_u32 s15, s53, 0
	global_load_dwordx2 v[32:33], v169, s[12:13] offset:0 nt
	global_load_dwordx2 v[34:35], v169, s[12:13] offset:512 nt
	global_load_dwordx2 v[36:37], v169, s[12:13] offset:1024 nt
	global_load_dwordx2 v[38:39], v169, s[12:13] offset:1536 nt
	global_load_dwordx2 v[40:41], v169, s[12:13] offset:2048 nt
	global_load_dwordx2 v[42:43], v169, s[12:13] offset:2560 nt
	global_load_dwordx2 v[44:45], v169, s[12:13] offset:3072 nt
	global_load_dwordx2 v[46:47], v169, s[12:13] offset:3584 nt
	s_cmp_lt_u32 s0, 14
	s_cbranch_scc0 .Lrm2_nopf_o
	s_lshr_b32 s1, s5, 9
	s_lshl_b32 s1, s1, 13
	s_and_b32 s8, s5, 0x1ff
	s_add_u32 s1, s1, s8
	s_add_u32 s8, s0, 2
	s_lshl_b32 s8, s8, 9
	s_add_u32 s1, s1, s8
	s_lshl_b32 s8, s1, 13
	s_add_u32 s6, s58, s8
	s_addc_u32 s7, s59, 0
	global_load_dwordx4 v[0:3], v80, s[6:7] offset:0 nt
	global_load_dwordx4 v[4:7], v80, s[6:7] offset:1024 nt
	global_load_dwordx4 v[8:11], v80, s[6:7] offset:2048 nt
	global_load_dwordx4 v[12:15], v80, s[6:7] offset:3072 nt
	global_load_dwordx4 v[16:19], v168, s[6:7] offset:0 nt
	global_load_dwordx4 v[20:23], v168, s[6:7] offset:1024 nt
	global_load_dwordx4 v[24:27], v168, s[6:7] offset:2048 nt
	global_load_dwordx4 v[28:31], v168, s[6:7] offset:3072 nt
	s_waitcnt vmcnt(8)
	s_branch .Lrm2_pfd_o

.Lrm2_pfd_o:
	v_lshlrev_b32_e32 v146, 16, v32
	v_and_b32_e32 v147, 0xffff0000, v32
	v_pk_mul_f32 v[154:155], v[146:147], v[146:147]
	v_lshlrev_b32_e32 v148, 16, v33
	v_and_b32_e32 v149, 0xffff0000, v33
	v_pk_mul_f32 v[156:157], v[148:149], v[148:149]
	v_lshlrev_b32_e32 v150, 16, v34
	v_and_b32_e32 v151, 0xffff0000, v34
	v_pk_fma_f32 v[154:155], v[150:151], v[150:151], v[154:155]
	v_lshlrev_b32_e32 v152, 16, v35
	v_and_b32_e32 v153, 0xffff0000, v35
	v_pk_fma_f32 v[156:157], v[152:153], v[152:153], v[156:157]
	v_lshlrev_b32_e32 v146, 16, v36
	v_and_b32_e32 v147, 0xffff0000, v36
	v_pk_fma_f32 v[154:155], v[146:147], v[146:147], v[154:155]
	v_lshlrev_b32_e32 v148, 16, v37
	v_and_b32_e32 v149, 0xffff0000, v37
	v_pk_fma_f32 v[156:157], v[148:149], v[148:149], v[156:157]
	v_lshlrev_b32_e32 v150, 16, v38
	v_and_b32_e32 v151, 0xffff0000, v38
	v_pk_fma_f32 v[154:155], v[150:151], v[150:151], v[154:155]
	v_lshlrev_b32_e32 v152, 16, v39
	v_and_b32_e32 v153, 0xffff0000, v39
	v_pk_fma_f32 v[156:157], v[152:153], v[152:153], v[156:157]
	v_lshlrev_b32_e32 v146, 16, v40
	v_and_b32_e32 v147, 0xffff0000, v40
	v_pk_fma_f32 v[154:155], v[146:147], v[146:147], v[154:155]
	v_lshlrev_b32_e32 v148, 16, v41
	v_and_b32_e32 v149, 0xffff0000, v41
	v_pk_fma_f32 v[156:157], v[148:149], v[148:149], v[156:157]
	v_lshlrev_b32_e32 v150, 16, v42
	v_and_b32_e32 v151, 0xffff0000, v42
	v_pk_fma_f32 v[154:155], v[150:151], v[150:151], v[154:155]
	v_lshlrev_b32_e32 v152, 16, v43
	v_and_b32_e32 v153, 0xffff0000, v43
	v_pk_fma_f32 v[156:157], v[152:153], v[152:153], v[156:157]
	v_lshlrev_b32_e32 v146, 16, v44
	v_and_b32_e32 v147, 0xffff0000, v44
	v_pk_fma_f32 v[154:155], v[146:147], v[146:147], v[154:155]
	v_lshlrev_b32_e32 v148, 16, v45
	v_and_b32_e32 v149, 0xffff0000, v45
	v_pk_fma_f32 v[156:157], v[148:149], v[148:149], v[156:157]
	v_lshlrev_b32_e32 v150, 16, v46
	v_and_b32_e32 v151, 0xffff0000, v46
	v_pk_fma_f32 v[154:155], v[150:151], v[150:151], v[154:155]
	v_lshlrev_b32_e32 v152, 16, v47
	v_and_b32_e32 v153, 0xffff0000, v47
	v_pk_fma_f32 v[156:157], v[152:153], v[152:153], v[156:157]
	v_pk_add_f32 v[154:155], v[154:155], v[156:157]
	s_nop 0
	v_add_f32_e32 v173, v154, v155
	s_nop 1
	v_add_f32_dpp v173, v173, v173 quad_perm:[1,0,3,2] row_mask:0xf bank_mask:0xf
	s_nop 1
	v_add_f32_dpp v173, v173, v173 quad_perm:[2,3,0,1] row_mask:0xf bank_mask:0xf
	s_nop 1
	v_add_f32_dpp v173, v173, v173 row_half_mirror row_mask:0xf bank_mask:0xf
	s_nop 1
	v_add_f32_dpp v173, v173, v173 row_mirror row_mask:0xf bank_mask:0xf
	s_nop 1
	v_add_f32_dpp v173, v173, v173 row_bcast:15 row_mask:0xa bank_mask:0xf
	s_nop 1
	v_add_f32_dpp v173, v173, v173 row_bcast:31 row_mask:0xc bank_mask:0xf
	s_nop 1
	v_readlane_b32 s8, v173, 63
	s_nop 3
	v_mov_b32_e32 v158, s8
	v_fma_f32 v158, v158, v171, v172
	v_rsq_f32_e32 v158, v158
	s_nop 1
	v_lshlrev_b32_e32 v146, 16, v32
	v_and_b32_e32 v147, 0xffff0000, v32
	v_pk_mul_f32 v[146:147], v[146:147], v[158:159] op_sel_hi:[1,0]
	v_pk_fma_f32 v[178:179], v[48:49], v[146:147], v[178:179]
	v_lshlrev_b32_e32 v148, 16, v33
	v_and_b32_e32 v149, 0xffff0000, v33
	v_pk_mul_f32 v[148:149], v[148:149], v[158:159] op_sel_hi:[1,0]
	v_pk_fma_f32 v[180:181], v[50:51], v[148:149], v[180:181]
	v_lshlrev_b32_e32 v150, 16, v34
	v_and_b32_e32 v151, 0xffff0000, v34
	v_pk_mul_f32 v[150:151], v[150:151], v[158:159] op_sel_hi:[1,0]
	v_pk_fma_f32 v[182:183], v[52:53], v[150:151], v[182:183]
	v_lshlrev_b32_e32 v152, 16, v35
	v_and_b32_e32 v153, 0xffff0000, v35
	v_pk_mul_f32 v[152:153], v[152:153], v[158:159] op_sel_hi:[1,0]
	v_pk_fma_f32 v[184:185], v[54:55], v[152:153], v[184:185]
	v_lshlrev_b32_e32 v146, 16, v36
	v_and_b32_e32 v147, 0xffff0000, v36
	v_pk_mul_f32 v[146:147], v[146:147], v[158:159] op_sel_hi:[1,0]
	v_pk_fma_f32 v[194:195], v[56:57], v[146:147], v[194:195]
	v_lshlrev_b32_e32 v148, 16, v37
	v_and_b32_e32 v149, 0xffff0000, v37
	v_pk_mul_f32 v[148:149], v[148:149], v[158:159] op_sel_hi:[1,0]
	v_pk_fma_f32 v[196:197], v[58:59], v[148:149], v[196:197]
	v_lshlrev_b32_e32 v150, 16, v38
	v_and_b32_e32 v151, 0xffff0000, v38
	v_pk_mul_f32 v[150:151], v[150:151], v[158:159] op_sel_hi:[1,0]
	v_pk_fma_f32 v[198:199], v[60:61], v[150:151], v[198:199]
	v_lshlrev_b32_e32 v152, 16, v39
	v_and_b32_e32 v153, 0xffff0000, v39
	v_pk_mul_f32 v[152:153], v[152:153], v[158:159] op_sel_hi:[1,0]
	v_pk_fma_f32 v[200:201], v[62:63], v[152:153], v[200:201]
	v_lshlrev_b32_e32 v146, 16, v40
	v_and_b32_e32 v147, 0xffff0000, v40
	v_pk_mul_f32 v[146:147], v[146:147], v[158:159] op_sel_hi:[1,0]
	v_pk_fma_f32 v[202:203], v[64:65], v[146:147], v[202:203]
	v_lshlrev_b32_e32 v148, 16, v41
	v_and_b32_e32 v149, 0xffff0000, v41
	v_pk_mul_f32 v[148:149], v[148:149], v[158:159] op_sel_hi:[1,0]
	v_pk_fma_f32 v[204:205], v[66:67], v[148:149], v[204:205]
	v_lshlrev_b32_e32 v150, 16, v42
	v_and_b32_e32 v151, 0xffff0000, v42
	v_pk_mul_f32 v[150:151], v[150:151], v[158:159] op_sel_hi:[1,0]
	v_pk_fma_f32 v[206:207], v[68:69], v[150:151], v[206:207]
	v_lshlrev_b32_e32 v152, 16, v43
	v_and_b32_e32 v153, 0xffff0000, v43
	v_pk_mul_f32 v[152:153], v[152:153], v[158:159] op_sel_hi:[1,0]
	v_pk_fma_f32 v[208:209], v[70:71], v[152:153], v[208:209]
	v_lshlrev_b32_e32 v146, 16, v44
	v_and_b32_e32 v147, 0xffff0000, v44
	v_pk_mul_f32 v[146:147], v[146:147], v[158:159] op_sel_hi:[1,0]
	v_pk_fma_f32 v[210:211], v[72:73], v[146:147], v[210:211]
	v_lshlrev_b32_e32 v148, 16, v45
	v_and_b32_e32 v149, 0xffff0000, v45
	v_pk_mul_f32 v[148:149], v[148:149], v[158:159] op_sel_hi:[1,0]
	v_pk_fma_f32 v[212:213], v[74:75], v[148:149], v[212:213]
	v_lshlrev_b32_e32 v150, 16, v46
	v_and_b32_e32 v151, 0xffff0000, v46
	v_pk_mul_f32 v[150:151], v[150:151], v[158:159] op_sel_hi:[1,0]
	v_pk_fma_f32 v[218:219], v[76:77], v[150:151], v[218:219]
	v_lshlrev_b32_e32 v152, 16, v47
	v_and_b32_e32 v153, 0xffff0000, v47
	v_pk_mul_f32 v[152:153], v[152:153], v[158:159] op_sel_hi:[1,0]
	v_pk_fma_f32 v[220:221], v[78:79], v[152:153], v[220:221]
	s_nop 0
	global_store_dwordx4 v80, v[178:181], s[10:11] offset:0 nt
	global_store_dwordx4 v80, v[182:185], s[10:11] offset:1024 nt
	global_store_dwordx4 v80, v[194:197], s[10:11] offset:2048 nt
	global_store_dwordx4 v80, v[198:201], s[10:11] offset:3072 nt
	global_store_dwordx4 v168, v[202:205], s[10:11] offset:0 nt
	global_store_dwordx4 v168, v[206:209], s[10:11] offset:1024 nt
	global_store_dwordx4 v168, v[210:213], s[10:11] offset:2048 nt
	global_store_dwordx4 v168, v[218:221], s[10:11] offset:3072 nt
	v_pk_mul_f32 v[154:155], v[178:179], v[178:179]
	v_pk_mul_f32 v[156:157], v[180:181], v[180:181]
	v_pk_fma_f32 v[154:155], v[182:183], v[182:183], v[154:155]
	v_pk_fma_f32 v[156:157], v[184:185], v[184:185], v[156:157]
	v_pk_fma_f32 v[154:155], v[194:195], v[194:195], v[154:155]
	v_pk_fma_f32 v[156:157], v[196:197], v[196:197], v[156:157]
	v_pk_fma_f32 v[154:155], v[198:199], v[198:199], v[154:155]
	v_pk_fma_f32 v[156:157], v[200:201], v[200:201], v[156:157]
	v_pk_fma_f32 v[154:155], v[202:203], v[202:203], v[154:155]
	v_pk_fma_f32 v[156:157], v[204:205], v[204:205], v[156:157]
	v_pk_fma_f32 v[154:155], v[206:207], v[206:207], v[154:155]
	v_pk_fma_f32 v[156:157], v[208:209], v[208:209], v[156:157]
	v_pk_fma_f32 v[154:155], v[210:211], v[210:211], v[154:155]
	v_pk_fma_f32 v[156:157], v[212:213], v[212:213], v[156:157]
	v_pk_fma_f32 v[154:155], v[218:219], v[218:219], v[154:155]
	v_pk_fma_f32 v[156:157], v[220:221], v[220:221], v[156:157]
	v_pk_add_f32 v[154:155], v[154:155], v[156:157]
	s_nop 0
	v_add_f32_e32 v173, v154, v155
	s_nop 1
	v_add_f32_dpp v173, v173, v173 quad_perm:[1,0,3,2] row_mask:0xf bank_mask:0xf
	s_nop 1
	v_add_f32_dpp v173, v173, v173 quad_perm:[2,3,0,1] row_mask:0xf bank_mask:0xf
	s_nop 1
	v_add_f32_dpp v173, v173, v173 row_half_mirror row_mask:0xf bank_mask:0xf
	s_nop 1
	v_add_f32_dpp v173, v173, v173 row_mirror row_mask:0xf bank_mask:0xf
	s_nop 1
	v_add_f32_dpp v173, v173, v173 row_bcast:15 row_mask:0xa bank_mask:0xf
	s_nop 1
	v_add_f32_dpp v173, v173, v173 row_bcast:31 row_mask:0xc bank_mask:0xf
	s_nop 1
	v_readlane_b32 s8, v173, 63
	s_nop 3
	v_mov_b32_e32 v158, s8
	v_fma_f32 v158, v158, v171, v172
	v_rsq_f32_e32 v158, v158
	s_nop 1
	v_pk_mul_f32 v[146:147], v[178:179], v[158:159] op_sel_hi:[1,0]
	v_pk_fma_f32 v[146:147], v[146:147], v[82:83], v[114:115]
	v_cvt_pk_bf16_f32 v160, v146, v147
	v_pk_mul_f32 v[148:149], v[180:181], v[158:159] op_sel_hi:[1,0]
	v_pk_fma_f32 v[148:149], v[148:149], v[84:85], v[116:117]
	v_cvt_pk_bf16_f32 v161, v148, v149
	global_store_dwordx2 v169, v[160:161], s[14:15] offset:0 nt
	v_pk_mul_f32 v[150:151], v[182:183], v[158:159] op_sel_hi:[1,0]
	v_pk_fma_f32 v[150:151], v[150:151], v[86:87], v[118:119]
	v_cvt_pk_bf16_f32 v162, v150, v151
	v_pk_mul_f32 v[152:153], v[184:185], v[158:159] op_sel_hi:[1,0]
	v_pk_fma_f32 v[152:153], v[152:153], v[88:89], v[120:121]
	v_cvt_pk_bf16_f32 v163, v152, v153
	global_store_dwordx2 v169, v[162:163], s[14:15] offset:512 nt
	v_pk_mul_f32 v[146:147], v[194:195], v[158:159] op_sel_hi:[1,0]
	v_pk_fma_f32 v[146:147], v[146:147], v[90:91], v[122:123]
	v_cvt_pk_bf16_f32 v164, v146, v147
	v_pk_mul_f32 v[148:149], v[196:197], v[158:159] op_sel_hi:[1,0]
	v_pk_fma_f32 v[148:149], v[148:149], v[92:93], v[124:125]
	v_cvt_pk_bf16_f32 v165, v148, v149
	global_store_dwordx2 v169, v[164:165], s[14:15] offset:1024 nt
	v_pk_mul_f32 v[150:151], v[198:199], v[158:159] op_sel_hi:[1,0]
	v_pk_fma_f32 v[150:151], v[150:151], v[94:95], v[126:127]
	v_cvt_pk_bf16_f32 v166, v150, v151
	v_pk_mul_f32 v[152:153], v[200:201], v[158:159] op_sel_hi:[1,0]
	v_pk_fma_f32 v[152:153], v[152:153], v[96:97], v[128:129]
	v_cvt_pk_bf16_f32 v167, v152, v153
	global_store_dwordx2 v169, v[166:167], s[14:15] offset:1536 nt
	v_pk_mul_f32 v[146:147], v[202:203], v[158:159] op_sel_hi:[1,0]
	v_pk_fma_f32 v[146:147], v[146:147], v[98:99], v[130:131]
	v_cvt_pk_bf16_f32 v160, v146, v147
	v_pk_mul_f32 v[148:149], v[204:205], v[158:159] op_sel_hi:[1,0]
	v_pk_fma_f32 v[148:149], v[148:149], v[100:101], v[132:133]
	v_cvt_pk_bf16_f32 v161, v148, v149
	global_store_dwordx2 v169, v[160:161], s[14:15] offset:2048 nt
	v_pk_mul_f32 v[150:151], v[206:207], v[158:159] op_sel_hi:[1,0]
	v_pk_fma_f32 v[150:151], v[150:151], v[102:103], v[134:135]
	v_cvt_pk_bf16_f32 v162, v150, v151
	v_pk_mul_f32 v[152:153], v[208:209], v[158:159] op_sel_hi:[1,0]
	v_pk_fma_f32 v[152:153], v[152:153], v[104:105], v[136:137]
	v_cvt_pk_bf16_f32 v163, v152, v153
	global_store_dwordx2 v169, v[162:163], s[14:15] offset:2560 nt
	v_pk_mul_f32 v[146:147], v[210:211], v[158:159] op_sel_hi:[1,0]
	v_pk_fma_f32 v[146:147], v[146:147], v[106:107], v[138:139]
	v_cvt_pk_bf16_f32 v164, v146, v147
	v_pk_mul_f32 v[148:149], v[212:213], v[158:159] op_sel_hi:[1,0]
	v_pk_fma_f32 v[148:149], v[148:149], v[108:109], v[140:141]
	v_cvt_pk_bf16_f32 v165, v148, v149
	global_store_dwordx2 v169, v[164:165], s[14:15] offset:3072 nt
	v_pk_mul_f32 v[150:151], v[218:219], v[158:159] op_sel_hi:[1,0]
	v_pk_fma_f32 v[150:151], v[150:151], v[110:111], v[142:143]
	v_cvt_pk_bf16_f32 v166, v150, v151
	v_pk_mul_f32 v[152:153], v[220:221], v[158:159] op_sel_hi:[1,0]
	v_pk_fma_f32 v[152:153], v[152:153], v[112:113], v[144:145]
	v_cvt_pk_bf16_f32 v167, v152, v153
	global_store_dwordx2 v169, v[166:167], s[14:15] offset:3584 nt
	s_add_u32 s0, s0, 2
	s_cmp_lt_u32 s0, 16
	s_cbranch_scc1 .Lrm2_loop
	s_bitcmp1_b32 s5, 0
	s_cbranch_scc1 .Lrm2_done
	s_mov_b32 s4, 4
	s_branch .Lrm2_coef
.Lrm2_ctxrow:
	s_lshr_b32 s8, s5, 1
	s_lshl_b32 s8, s8, 13
	s_add_u32 s8, s8, 0x3d000000
	s_add_u32 s6, s52, s8
	s_addc_u32 s7, s53, 0
	s_sub_u32 s8, s8, 0x3d000000
	global_load_dwordx4 v[0:3], v80, s[6:7] offset:0 nt
	global_load_dwordx4 v[4:7], v80, s[6:7] offset:1024 nt
	global_load_dwordx4 v[8:11], v80, s[6:7] offset:2048 nt
	global_load_dwordx4 v[12:15], v80, s[6:7] offset:3072 nt
	global_load_dwordx4 v[16:19], v168, s[6:7] offset:0 nt
	global_load_dwordx4 v[20:23], v168, s[6:7] offset:1024 nt
	global_load_dwordx4 v[24:27], v168, s[6:7] offset:2048 nt
	global_load_dwordx4 v[28:31], v168, s[6:7] offset:3072 nt
	s_lshr_b32 s8, s5, 1
	s_add_u32 s1, s8, 0x8000
	s_lshl_b32 s8, s8, 13
	s_add_u32 s9, s8, 0x3d000000
	s_add_u32 s10, s52, s9
	s_addc_u32 s11, s53, 0
	s_lshl_b32 s8, s1, 12
	s_add_u32 s9, s8, 0x34c00000
	s_add_u32 s12, s52, s9
	s_addc_u32 s13, s53, 0
	s_add_u32 s9, s8, 0x2c800000
	s_add_u32 s14, s52, s9
	s_addc_u32 s15, s53, 0
	global_load_dwordx2 v[32:33], v169, s[12:13] offset:0 nt
	global_load_dwordx2 v[34:35], v169, s[12:13] offset:512 nt
	global_load_dwordx2 v[36:37], v169, s[12:13] offset:1024 nt
	global_load_dwordx2 v[38:39], v169, s[12:13] offset:1536 nt
	global_load_dwordx2 v[40:41], v169, s[12:13] offset:2048 nt
	global_load_dwordx2 v[42:43], v169, s[12:13] offset:2560 nt
	global_load_dwordx2 v[44:45], v169, s[12:13] offset:3072 nt
	global_load_dwordx2 v[46:47], v169, s[12:13] offset:3584 nt
	s_waitcnt vmcnt(0)
	v_lshlrev_b32_e32 v146, 16, v32
	v_and_b32_e32 v147, 0xffff0000, v32
	v_pk_mul_f32 v[154:155], v[146:147], v[146:147]
	v_lshlrev_b32_e32 v148, 16, v33
	v_and_b32_e32 v149, 0xffff0000, v33
	v_pk_mul_f32 v[156:157], v[148:149], v[148:149]
	v_lshlrev_b32_e32 v150, 16, v34
	v_and_b32_e32 v151, 0xffff0000, v34
	v_pk_fma_f32 v[154:155], v[150:151], v[150:151], v[154:155]
	v_lshlrev_b32_e32 v152, 16, v35
	v_and_b32_e32 v153, 0xffff0000, v35
	v_pk_fma_f32 v[156:157], v[152:153], v[152:153], v[156:157]
	v_lshlrev_b32_e32 v146, 16, v36
	v_and_b32_e32 v147, 0xffff0000, v36
	v_pk_fma_f32 v[154:155], v[146:147], v[146:147], v[154:155]
	v_lshlrev_b32_e32 v148, 16, v37
	v_and_b32_e32 v149, 0xffff0000, v37
	v_pk_fma_f32 v[156:157], v[148:149], v[148:149], v[156:157]
	v_lshlrev_b32_e32 v150, 16, v38
	v_and_b32_e32 v151, 0xffff0000, v38
	v_pk_fma_f32 v[154:155], v[150:151], v[150:151], v[154:155]
	v_lshlrev_b32_e32 v152, 16, v39
	v_and_b32_e32 v153, 0xffff0000, v39
	v_pk_fma_f32 v[156:157], v[152:153], v[152:153], v[156:157]
	v_lshlrev_b32_e32 v146, 16, v40
	v_and_b32_e32 v147, 0xffff0000, v40
	v_pk_fma_f32 v[154:155], v[146:147], v[146:147], v[154:155]
	v_lshlrev_b32_e32 v148, 16, v41
	v_and_b32_e32 v149, 0xffff0000, v41
	v_pk_fma_f32 v[156:157], v[148:149], v[148:149], v[156:157]
	v_lshlrev_b32_e32 v150, 16, v42
	v_and_b32_e32 v151, 0xffff0000, v42
	v_pk_fma_f32 v[154:155], v[150:151], v[150:151], v[154:155]
	v_lshlrev_b32_e32 v152, 16, v43
	v_and_b32_e32 v153, 0xffff0000, v43
	v_pk_fma_f32 v[156:157], v[152:153], v[152:153], v[156:157]
	v_lshlrev_b32_e32 v146, 16, v44
	v_and_b32_e32 v147, 0xffff0000, v44
	v_pk_fma_f32 v[154:155], v[146:147], v[146:147], v[154:155]
	v_lshlrev_b32_e32 v148, 16, v45
	v_and_b32_e32 v149, 0xffff0000, v45
	v_pk_fma_f32 v[156:157], v[148:149], v[148:149], v[156:157]
	v_lshlrev_b32_e32 v150, 16, v46
	v_and_b32_e32 v151, 0xffff0000, v46
	v_pk_fma_f32 v[154:155], v[150:151], v[150:151], v[154:155]
	v_lshlrev_b32_e32 v152, 16, v47
	v_and_b32_e32 v153, 0xffff0000, v47
	v_pk_fma_f32 v[156:157], v[152:153], v[152:153], v[156:157]
	v_pk_add_f32 v[154:155], v[154:155], v[156:157]
	s_nop 0
	v_add_f32_e32 v173, v154, v155
	s_nop 1
	v_add_f32_dpp v173, v173, v173 quad_perm:[1,0,3,2] row_mask:0xf bank_mask:0xf
	s_nop 1
	v_add_f32_dpp v173, v173, v173 quad_perm:[2,3,0,1] row_mask:0xf bank_mask:0xf
	s_nop 1
	v_add_f32_dpp v173, v173, v173 row_half_mirror row_mask:0xf bank_mask:0xf
	s_nop 1
	v_add_f32_dpp v173, v173, v173 row_mirror row_mask:0xf bank_mask:0xf
	s_nop 1
	v_add_f32_dpp v173, v173, v173 row_bcast:15 row_mask:0xa bank_mask:0xf
	s_nop 1
	v_add_f32_dpp v173, v173, v173 row_bcast:31 row_mask:0xc bank_mask:0xf
	s_nop 1
	v_readlane_b32 s8, v173, 63
	s_nop 3
	v_mov_b32_e32 v158, s8
	v_fma_f32 v158, v158, v171, v172
	v_rsq_f32_e32 v158, v158
	s_nop 1
	v_lshlrev_b32_e32 v146, 16, v32
	v_and_b32_e32 v147, 0xffff0000, v32
	v_pk_mul_f32 v[146:147], v[146:147], v[158:159] op_sel_hi:[1,0]
	v_pk_fma_f32 v[0:1], v[48:49], v[146:147], v[0:1]
	v_lshlrev_b32_e32 v148, 16, v33
	v_and_b32_e32 v149, 0xffff0000, v33
	v_pk_mul_f32 v[148:149], v[148:149], v[158:159] op_sel_hi:[1,0]
	v_pk_fma_f32 v[2:3], v[50:51], v[148:149], v[2:3]
	v_lshlrev_b32_e32 v150, 16, v34
	v_and_b32_e32 v151, 0xffff0000, v34
	v_pk_mul_f32 v[150:151], v[150:151], v[158:159] op_sel_hi:[1,0]
	v_pk_fma_f32 v[4:5], v[52:53], v[150:151], v[4:5]
	v_lshlrev_b32_e32 v152, 16, v35
	v_and_b32_e32 v153, 0xffff0000, v35
	v_pk_mul_f32 v[152:153], v[152:153], v[158:159] op_sel_hi:[1,0]
	v_pk_fma_f32 v[6:7], v[54:55], v[152:153], v[6:7]
	v_lshlrev_b32_e32 v146, 16, v36
	v_and_b32_e32 v147, 0xffff0000, v36
	v_pk_mul_f32 v[146:147], v[146:147], v[158:159] op_sel_hi:[1,0]
	v_pk_fma_f32 v[8:9], v[56:57], v[146:147], v[8:9]
	v_lshlrev_b32_e32 v148, 16, v37
	v_and_b32_e32 v149, 0xffff0000, v37
	v_pk_mul_f32 v[148:149], v[148:149], v[158:159] op_sel_hi:[1,0]
	v_pk_fma_f32 v[10:11], v[58:59], v[148:149], v[10:11]
	v_lshlrev_b32_e32 v150, 16, v38
	v_and_b32_e32 v151, 0xffff0000, v38
	v_pk_mul_f32 v[150:151], v[150:151], v[158:159] op_sel_hi:[1,0]
	v_pk_fma_f32 v[12:13], v[60:61], v[150:151], v[12:13]
	v_lshlrev_b32_e32 v152, 16, v39
	v_and_b32_e32 v153, 0xffff0000, v39
	v_pk_mul_f32 v[152:153], v[152:153], v[158:159] op_sel_hi:[1,0]
	v_pk_fma_f32 v[14:15], v[62:63], v[152:153], v[14:15]
	v_lshlrev_b32_e32 v146, 16, v40
	v_and_b32_e32 v147, 0xffff0000, v40
	v_pk_mul_f32 v[146:147], v[146:147], v[158:159] op_sel_hi:[1,0]
	v_pk_fma_f32 v[16:17], v[64:65], v[146:147], v[16:17]
	v_lshlrev_b32_e32 v148, 16, v41
	v_and_b32_e32 v149, 0xffff0000, v41
	v_pk_mul_f32 v[148:149], v[148:149], v[158:159] op_sel_hi:[1,0]
	v_pk_fma_f32 v[18:19], v[66:67], v[148:149], v[18:19]
	v_lshlrev_b32_e32 v150, 16, v42
	v_and_b32_e32 v151, 0xffff0000, v42
	v_pk_mul_f32 v[150:151], v[150:151], v[158:159] op_sel_hi:[1,0]
	v_pk_fma_f32 v[20:21], v[68:69], v[150:151], v[20:21]
	v_lshlrev_b32_e32 v152, 16, v43
	v_and_b32_e32 v153, 0xffff0000, v43
	v_pk_mul_f32 v[152:153], v[152:153], v[158:159] op_sel_hi:[1,0]
	v_pk_fma_f32 v[22:23], v[70:71], v[152:153], v[22:23]
	v_lshlrev_b32_e32 v146, 16, v44
	v_and_b32_e32 v147, 0xffff0000, v44
	v_pk_mul_f32 v[146:147], v[146:147], v[158:159] op_sel_hi:[1,0]
	v_pk_fma_f32 v[24:25], v[72:73], v[146:147], v[24:25]
	v_lshlrev_b32_e32 v148, 16, v45
	v_and_b32_e32 v149, 0xffff0000, v45
	v_pk_mul_f32 v[148:149], v[148:149], v[158:159] op_sel_hi:[1,0]
	v_pk_fma_f32 v[26:27], v[74:75], v[148:149], v[26:27]
	v_lshlrev_b32_e32 v150, 16, v46
	v_and_b32_e32 v151, 0xffff0000, v46
	v_pk_mul_f32 v[150:151], v[150:151], v[158:159] op_sel_hi:[1,0]
	v_pk_fma_f32 v[28:29], v[76:77], v[150:151], v[28:29]
	v_lshlrev_b32_e32 v152, 16, v47
	v_and_b32_e32 v153, 0xffff0000, v47
	v_pk_mul_f32 v[152:153], v[152:153], v[158:159] op_sel_hi:[1,0]
	v_pk_fma_f32 v[30:31], v[78:79], v[152:153], v[30:31]
	s_nop 0
	global_store_dwordx4 v80, v[0:3], s[10:11] offset:0 nt
	global_store_dwordx4 v80, v[4:7], s[10:11] offset:1024 nt
	global_store_dwordx4 v80, v[8:11], s[10:11] offset:2048 nt
	global_store_dwordx4 v80, v[12:15], s[10:11] offset:3072 nt
	global_store_dwordx4 v168, v[16:19], s[10:11] offset:0 nt
	global_store_dwordx4 v168, v[20:23], s[10:11] offset:1024 nt
	global_store_dwordx4 v168, v[24:27], s[10:11] offset:2048 nt
	global_store_dwordx4 v168, v[28:31], s[10:11] offset:3072 nt
	v_pk_mul_f32 v[154:155], v[0:1], v[0:1]
	v_pk_mul_f32 v[156:157], v[2:3], v[2:3]
	v_pk_fma_f32 v[154:155], v[4:5], v[4:5], v[154:155]
	v_pk_fma_f32 v[156:157], v[6:7], v[6:7], v[156:157]
	v_pk_fma_f32 v[154:155], v[8:9], v[8:9], v[154:155]
	v_pk_fma_f32 v[156:157], v[10:11], v[10:11], v[156:157]
	v_pk_fma_f32 v[154:155], v[12:13], v[12:13], v[154:155]
	v_pk_fma_f32 v[156:157], v[14:15], v[14:15], v[156:157]
	v_pk_fma_f32 v[154:155], v[16:17], v[16:17], v[154:155]
	v_pk_fma_f32 v[156:157], v[18:19], v[18:19], v[156:157]
	v_pk_fma_f32 v[154:155], v[20:21], v[20:21], v[154:155]
	v_pk_fma_f32 v[156:157], v[22:23], v[22:23], v[156:157]
	v_pk_fma_f32 v[154:155], v[24:25], v[24:25], v[154:155]
	v_pk_fma_f32 v[156:157], v[26:27], v[26:27], v[156:157]
	v_pk_fma_f32 v[154:155], v[28:29], v[28:29], v[154:155]
	v_pk_fma_f32 v[156:157], v[30:31], v[30:31], v[156:157]
	v_pk_add_f32 v[154:155], v[154:155], v[156:157]
	s_nop 0
	v_add_f32_e32 v173, v154, v155
	s_nop 1
	v_add_f32_dpp v173, v173, v173 quad_perm:[1,0,3,2] row_mask:0xf bank_mask:0xf
	s_nop 1
	v_add_f32_dpp v173, v173, v173 quad_perm:[2,3,0,1] row_mask:0xf bank_mask:0xf
	s_nop 1
	v_add_f32_dpp v173, v173, v173 row_half_mirror row_mask:0xf bank_mask:0xf
	s_nop 1
	v_add_f32_dpp v173, v173, v173 row_mirror row_mask:0xf bank_mask:0xf
	s_nop 1
	v_add_f32_dpp v173, v173, v173 row_bcast:15 row_mask:0xa bank_mask:0xf
	s_nop 1
	v_add_f32_dpp v173, v173, v173 row_bcast:31 row_mask:0xc bank_mask:0xf
	s_nop 1
	v_readlane_b32 s8, v173, 63
	s_nop 3
	v_mov_b32_e32 v158, s8
	v_fma_f32 v158, v158, v171, v172
	v_rsq_f32_e32 v158, v158
	s_nop 1
	v_pk_mul_f32 v[146:147], v[0:1], v[158:159] op_sel_hi:[1,0]
	v_pk_fma_f32 v[146:147], v[146:147], v[82:83], v[114:115]
	v_cvt_pk_bf16_f32 v160, v146, v147
	v_pk_mul_f32 v[148:149], v[2:3], v[158:159] op_sel_hi:[1,0]
	v_pk_fma_f32 v[148:149], v[148:149], v[84:85], v[116:117]
	v_cvt_pk_bf16_f32 v161, v148, v149
	global_store_dwordx2 v169, v[160:161], s[14:15] offset:0 nt
	v_pk_mul_f32 v[150:151], v[4:5], v[158:159] op_sel_hi:[1,0]
	v_pk_fma_f32 v[150:151], v[150:151], v[86:87], v[118:119]
	v_cvt_pk_bf16_f32 v162, v150, v151
	v_pk_mul_f32 v[152:153], v[6:7], v[158:159] op_sel_hi:[1,0]
	v_pk_fma_f32 v[152:153], v[152:153], v[88:89], v[120:121]
	v_cvt_pk_bf16_f32 v163, v152, v153
	global_store_dwordx2 v169, v[162:163], s[14:15] offset:512 nt
	v_pk_mul_f32 v[146:147], v[8:9], v[158:159] op_sel_hi:[1,0]
	v_pk_fma_f32 v[146:147], v[146:147], v[90:91], v[122:123]
	v_cvt_pk_bf16_f32 v164, v146, v147
	v_pk_mul_f32 v[148:149], v[10:11], v[158:159] op_sel_hi:[1,0]
	v_pk_fma_f32 v[148:149], v[148:149], v[92:93], v[124:125]
	v_cvt_pk_bf16_f32 v165, v148, v149
	global_store_dwordx2 v169, v[164:165], s[14:15] offset:1024 nt
	v_pk_mul_f32 v[150:151], v[12:13], v[158:159] op_sel_hi:[1,0]
	v_pk_fma_f32 v[150:151], v[150:151], v[94:95], v[126:127]
	v_cvt_pk_bf16_f32 v166, v150, v151
	v_pk_mul_f32 v[152:153], v[14:15], v[158:159] op_sel_hi:[1,0]
	v_pk_fma_f32 v[152:153], v[152:153], v[96:97], v[128:129]
	v_cvt_pk_bf16_f32 v167, v152, v153
	global_store_dwordx2 v169, v[166:167], s[14:15] offset:1536 nt
	v_pk_mul_f32 v[146:147], v[16:17], v[158:159] op_sel_hi:[1,0]
	v_pk_fma_f32 v[146:147], v[146:147], v[98:99], v[130:131]
	v_cvt_pk_bf16_f32 v160, v146, v147
	v_pk_mul_f32 v[148:149], v[18:19], v[158:159] op_sel_hi:[1,0]
	v_pk_fma_f32 v[148:149], v[148:149], v[100:101], v[132:133]
	v_cvt_pk_bf16_f32 v161, v148, v149
	global_store_dwordx2 v169, v[160:161], s[14:15] offset:2048 nt
	v_pk_mul_f32 v[150:151], v[20:21], v[158:159] op_sel_hi:[1,0]
	v_pk_fma_f32 v[150:151], v[150:151], v[102:103], v[134:135]
	v_cvt_pk_bf16_f32 v162, v150, v151
	v_pk_mul_f32 v[152:153], v[22:23], v[158:159] op_sel_hi:[1,0]
	v_pk_fma_f32 v[152:153], v[152:153], v[104:105], v[136:137]
	v_cvt_pk_bf16_f32 v163, v152, v153
	global_store_dwordx2 v169, v[162:163], s[14:15] offset:2560 nt
	v_pk_mul_f32 v[146:147], v[24:25], v[158:159] op_sel_hi:[1,0]
	v_pk_fma_f32 v[146:147], v[146:147], v[106:107], v[138:139]
	v_cvt_pk_bf16_f32 v164, v146, v147
	v_pk_mul_f32 v[148:149], v[26:27], v[158:159] op_sel_hi:[1,0]
	v_pk_fma_f32 v[148:149], v[148:149], v[108:109], v[140:141]
	v_cvt_pk_bf16_f32 v165, v148, v149
	global_store_dwordx2 v169, v[164:165], s[14:15] offset:3072 nt
	v_pk_mul_f32 v[150:151], v[28:29], v[158:159] op_sel_hi:[1,0]
	v_pk_fma_f32 v[150:151], v[150:151], v[110:111], v[142:143]
	v_cvt_pk_bf16_f32 v166, v150, v151
	v_pk_mul_f32 v[152:153], v[30:31], v[158:159] op_sel_hi:[1,0]
	v_pk_fma_f32 v[152:153], v[152:153], v[112:113], v[144:145]
	v_cvt_pk_bf16_f32 v167, v152, v153
	global_store_dwordx2 v169, v[166:167], s[14:15] offset:3584 nt

.Lrm3_loop:
	s_lshr_b32 s1, s5, 9
	s_lshl_b32 s1, s1, 13
	s_and_b32 s8, s5, 0x1ff
	s_add_u32 s1, s1, s8
	s_add_u32 s8, s0, 0
	s_lshl_b32 s8, s8, 9
	s_add_u32 s1, s1, s8
	s_lshl_b32 s8, s1, 13
	s_add_u32 s10, s58, s8
	s_addc_u32 s11, s59, 0
	s_lshl_b32 s8, s1, 12
	s_add_u32 s9, s8, 0xb800000
	s_add_u32 s12, s52, s9
	s_addc_u32 s13, s53, 0
	s_add_u32 s9, s8, 0x2c800000
	s_add_u32 s14, s52, s9
	s_addc_u32 s15, s53, 0
	global_load_dwordx2 v[32:33], v169, s[12:13] offset:0 nt
	global_load_dwordx2 v[34:35], v169, s[12:13] offset:512 nt
	global_load_dwordx2 v[36:37], v169, s[12:13] offset:1024 nt
	global_load_dwordx2 v[38:39], v169, s[12:13] offset:1536 nt
	global_load_dwordx2 v[40:41], v169, s[12:13] offset:2048 nt
	global_load_dwordx2 v[42:43], v169, s[12:13] offset:2560 nt
	global_load_dwordx2 v[44:45], v169, s[12:13] offset:3072 nt
	global_load_dwordx2 v[46:47], v169, s[12:13] offset:3584 nt
	s_lshr_b32 s1, s5, 9
	s_lshl_b32 s1, s1, 13
	s_and_b32 s8, s5, 0x1ff
	s_add_u32 s1, s1, s8
	s_add_u32 s8, s0, 1
	s_lshl_b32 s8, s8, 9
	s_add_u32 s1, s1, s8
	s_lshl_b32 s8, s1, 13
	s_add_u32 s6, s58, s8
	s_addc_u32 s7, s59, 0
	global_load_dwordx4 v[178:181], v80, s[6:7] offset:0 nt
	global_load_dwordx4 v[182:185], v80, s[6:7] offset:1024 nt
	global_load_dwordx4 v[192:195], v80, s[6:7] offset:2048 nt
	global_load_dwordx4 v[198:201], v80, s[6:7] offset:3072 nt
	global_load_dwordx4 v[202:205], v168, s[6:7] offset:0 nt
	global_load_dwordx4 v[206:209], v168, s[6:7] offset:1024 nt
	global_load_dwordx4 v[210:213], v168, s[6:7] offset:2048 nt
	global_load_dwordx4 v[214:217], v168, s[6:7] offset:3072 nt
	s_waitcnt vmcnt(8)
	v_lshlrev_b32_e32 v146, 16, v32
	v_and_b32_e32 v147, 0xffff0000, v32
	v_pk_mul_f32 v[154:155], v[146:147], v[146:147]
	v_lshlrev_b32_e32 v148, 16, v33
	v_and_b32_e32 v149, 0xffff0000, v33
	v_pk_mul_f32 v[156:157], v[148:149], v[148:149]
	v_lshlrev_b32_e32 v150, 16, v34
	v_and_b32_e32 v151, 0xffff0000, v34
	v_pk_fma_f32 v[154:155], v[150:151], v[150:151], v[154:155]
	v_lshlrev_b32_e32 v152, 16, v35
	v_and_b32_e32 v153, 0xffff0000, v35
	v_pk_fma_f32 v[156:157], v[152:153], v[152:153], v[156:157]
	v_lshlrev_b32_e32 v146, 16, v36
	v_and_b32_e32 v147, 0xffff0000, v36
	v_pk_fma_f32 v[154:155], v[146:147], v[146:147], v[154:155]
	v_lshlrev_b32_e32 v148, 16, v37
	v_and_b32_e32 v149, 0xffff0000, v37
	v_pk_fma_f32 v[156:157], v[148:149], v[148:149], v[156:157]
	v_lshlrev_b32_e32 v150, 16, v38
	v_and_b32_e32 v151, 0xffff0000, v38
	v_pk_fma_f32 v[154:155], v[150:151], v[150:151], v[154:155]
	v_lshlrev_b32_e32 v152, 16, v39
	v_and_b32_e32 v153, 0xffff0000, v39
	v_pk_fma_f32 v[156:157], v[152:153], v[152:153], v[156:157]
	v_lshlrev_b32_e32 v146, 16, v40
	v_and_b32_e32 v147, 0xffff0000, v40
	v_pk_fma_f32 v[154:155], v[146:147], v[146:147], v[154:155]
	v_lshlrev_b32_e32 v148, 16, v41
	v_and_b32_e32 v149, 0xffff0000, v41
	v_pk_fma_f32 v[156:157], v[148:149], v[148:149], v[156:157]
	v_lshlrev_b32_e32 v150, 16, v42
	v_and_b32_e32 v151, 0xffff0000, v42
	v_pk_fma_f32 v[154:155], v[150:151], v[150:151], v[154:155]
	v_lshlrev_b32_e32 v152, 16, v43
	v_and_b32_e32 v153, 0xffff0000, v43
	v_pk_fma_f32 v[156:157], v[152:153], v[152:153], v[156:157]
	v_lshlrev_b32_e32 v146, 16, v44
	v_and_b32_e32 v147, 0xffff0000, v44
	v_pk_fma_f32 v[154:155], v[146:147], v[146:147], v[154:155]
	v_lshlrev_b32_e32 v148, 16, v45
	v_and_b32_e32 v149, 0xffff0000, v45
	v_pk_fma_f32 v[156:157], v[148:149], v[148:149], v[156:157]
	v_lshlrev_b32_e32 v150, 16, v46
	v_and_b32_e32 v151, 0xffff0000, v46
	v_pk_fma_f32 v[154:155], v[150:151], v[150:151], v[154:155]
	v_lshlrev_b32_e32 v152, 16, v47
	v_and_b32_e32 v153, 0xffff0000, v47
	v_pk_fma_f32 v[156:157], v[152:153], v[152:153], v[156:157]
	v_pk_add_f32 v[154:155], v[154:155], v[156:157]
	s_nop 0
	v_add_f32_e32 v173, v154, v155
	s_nop 1
	v_add_f32_dpp v173, v173, v173 quad_perm:[1,0,3,2] row_mask:0xf bank_mask:0xf
	s_nop 1
	v_add_f32_dpp v173, v173, v173 quad_perm:[2,3,0,1] row_mask:0xf bank_mask:0xf
	s_nop 1
	v_add_f32_dpp v173, v173, v173 row_half_mirror row_mask:0xf bank_mask:0xf
	s_nop 1
	v_add_f32_dpp v173, v173, v173 row_mirror row_mask:0xf bank_mask:0xf
	s_nop 1
	v_add_f32_dpp v173, v173, v173 row_bcast:15 row_mask:0xa bank_mask:0xf
	s_nop 1
	v_add_f32_dpp v173, v173, v173 row_bcast:31 row_mask:0xc bank_mask:0xf
	s_nop 1
	v_readlane_b32 s8, v173, 63
	s_nop 3
	v_mov_b32_e32 v158, s8
	v_fma_f32 v158, v158, v171, v172
	v_rsq_f32_e32 v158, v158
	s_nop 1
	v_lshlrev_b32_e32 v146, 16, v32
	v_and_b32_e32 v147, 0xffff0000, v32
	v_pk_mul_f32 v[146:147], v[146:147], v[158:159] op_sel_hi:[1,0]
	v_pk_fma_f32 v[0:1], v[48:49], v[146:147], v[0:1]
	v_lshlrev_b32_e32 v148, 16, v33
	v_and_b32_e32 v149, 0xffff0000, v33
	v_pk_mul_f32 v[148:149], v[148:149], v[158:159] op_sel_hi:[1,0]
	v_pk_fma_f32 v[2:3], v[50:51], v[148:149], v[2:3]
	v_lshlrev_b32_e32 v150, 16, v34
	v_and_b32_e32 v151, 0xffff0000, v34
	v_pk_mul_f32 v[150:151], v[150:151], v[158:159] op_sel_hi:[1,0]
	v_pk_fma_f32 v[4:5], v[52:53], v[150:151], v[4:5]
	v_lshlrev_b32_e32 v152, 16, v35
	v_and_b32_e32 v153, 0xffff0000, v35
	v_pk_mul_f32 v[152:153], v[152:153], v[158:159] op_sel_hi:[1,0]
	v_pk_fma_f32 v[6:7], v[54:55], v[152:153], v[6:7]
	v_lshlrev_b32_e32 v146, 16, v36
	v_and_b32_e32 v147, 0xffff0000, v36
	v_pk_mul_f32 v[146:147], v[146:147], v[158:159] op_sel_hi:[1,0]
	v_pk_fma_f32 v[8:9], v[56:57], v[146:147], v[8:9]
	v_lshlrev_b32_e32 v148, 16, v37
	v_and_b32_e32 v149, 0xffff0000, v37
	v_pk_mul_f32 v[148:149], v[148:149], v[158:159] op_sel_hi:[1,0]
	v_pk_fma_f32 v[10:11], v[58:59], v[148:149], v[10:11]
	v_lshlrev_b32_e32 v150, 16, v38
	v_and_b32_e32 v151, 0xffff0000, v38
	v_pk_mul_f32 v[150:151], v[150:151], v[158:159] op_sel_hi:[1,0]
	v_pk_fma_f32 v[12:13], v[60:61], v[150:151], v[12:13]
	v_lshlrev_b32_e32 v152, 16, v39
	v_and_b32_e32 v153, 0xffff0000, v39
	v_pk_mul_f32 v[152:153], v[152:153], v[158:159] op_sel_hi:[1,0]
	v_pk_fma_f32 v[14:15], v[62:63], v[152:153], v[14:15]
	v_lshlrev_b32_e32 v146, 16, v40
	v_and_b32_e32 v147, 0xffff0000, v40
	v_pk_mul_f32 v[146:147], v[146:147], v[158:159] op_sel_hi:[1,0]
	v_pk_fma_f32 v[16:17], v[64:65], v[146:147], v[16:17]
	v_lshlrev_b32_e32 v148, 16, v41
	v_and_b32_e32 v149, 0xffff0000, v41
	v_pk_mul_f32 v[148:149], v[148:149], v[158:159] op_sel_hi:[1,0]
	v_pk_fma_f32 v[18:19], v[66:67], v[148:149], v[18:19]
	v_lshlrev_b32_e32 v150, 16, v42
	v_and_b32_e32 v151, 0xffff0000, v42
	v_pk_mul_f32 v[150:151], v[150:151], v[158:159] op_sel_hi:[1,0]
	v_pk_fma_f32 v[20:21], v[68:69], v[150:151], v[20:21]
	v_lshlrev_b32_e32 v152, 16, v43
	v_and_b32_e32 v153, 0xffff0000, v43
	v_pk_mul_f32 v[152:153], v[152:153], v[158:159] op_sel_hi:[1,0]
	v_pk_fma_f32 v[22:23], v[70:71], v[152:153], v[22:23]
	v_lshlrev_b32_e32 v146, 16, v44
	v_and_b32_e32 v147, 0xffff0000, v44
	v_pk_mul_f32 v[146:147], v[146:147], v[158:159] op_sel_hi:[1,0]
	v_pk_fma_f32 v[24:25], v[72:73], v[146:147], v[24:25]
	v_lshlrev_b32_e32 v148, 16, v45
	v_and_b32_e32 v149, 0xffff0000, v45
	v_pk_mul_f32 v[148:149], v[148:149], v[158:159] op_sel_hi:[1,0]
	v_pk_fma_f32 v[26:27], v[74:75], v[148:149], v[26:27]
	v_lshlrev_b32_e32 v150, 16, v46
	v_and_b32_e32 v151, 0xffff0000, v46
	v_pk_mul_f32 v[150:151], v[150:151], v[158:159] op_sel_hi:[1,0]
	v_pk_fma_f32 v[28:29], v[76:77], v[150:151], v[28:29]
	v_lshlrev_b32_e32 v152, 16, v47
	v_and_b32_e32 v153, 0xffff0000, v47
	v_pk_mul_f32 v[152:153], v[152:153], v[158:159] op_sel_hi:[1,0]
	v_pk_fma_f32 v[30:31], v[78:79], v[152:153], v[30:31]
	s_nop 0
	global_store_dwordx4 v80, v[0:3], s[10:11] offset:0 nt
	global_store_dwordx4 v80, v[4:7], s[10:11] offset:1024 nt
	global_store_dwordx4 v80, v[8:11], s[10:11] offset:2048 nt
	global_store_dwordx4 v80, v[12:15], s[10:11] offset:3072 nt
	global_store_dwordx4 v168, v[16:19], s[10:11] offset:0 nt
	global_store_dwordx4 v168, v[20:23], s[10:11] offset:1024 nt
	global_store_dwordx4 v168, v[24:27], s[10:11] offset:2048 nt
	global_store_dwordx4 v168, v[28:31], s[10:11] offset:3072 nt
	v_pk_mul_f32 v[154:155], v[0:1], v[0:1]
	v_pk_mul_f32 v[156:157], v[2:3], v[2:3]
	v_pk_fma_f32 v[154:155], v[4:5], v[4:5], v[154:155]
	v_pk_fma_f32 v[156:157], v[6:7], v[6:7], v[156:157]
	v_pk_fma_f32 v[154:155], v[8:9], v[8:9], v[154:155]
	v_pk_fma_f32 v[156:157], v[10:11], v[10:11], v[156:157]
	v_pk_fma_f32 v[154:155], v[12:13], v[12:13], v[154:155]
	v_pk_fma_f32 v[156:157], v[14:15], v[14:15], v[156:157]
	v_pk_fma_f32 v[154:155], v[16:17], v[16:17], v[154:155]
	v_pk_fma_f32 v[156:157], v[18:19], v[18:19], v[156:157]
	v_pk_fma_f32 v[154:155], v[20:21], v[20:21], v[154:155]
	v_pk_fma_f32 v[156:157], v[22:23], v[22:23], v[156:157]
	v_pk_fma_f32 v[154:155], v[24:25], v[24:25], v[154:155]
	v_pk_fma_f32 v[156:157], v[26:27], v[26:27], v[156:157]
	v_pk_fma_f32 v[154:155], v[28:29], v[28:29], v[154:155]
	v_pk_fma_f32 v[156:157], v[30:31], v[30:31], v[156:157]
	v_pk_add_f32 v[154:155], v[154:155], v[156:157]
	s_nop 0
	v_add_f32_e32 v173, v154, v155
	s_nop 1
	v_add_f32_dpp v173, v173, v173 quad_perm:[1,0,3,2] row_mask:0xf bank_mask:0xf
	s_nop 1
	v_add_f32_dpp v173, v173, v173 quad_perm:[2,3,0,1] row_mask:0xf bank_mask:0xf
	s_nop 1
	v_add_f32_dpp v173, v173, v173 row_half_mirror row_mask:0xf bank_mask:0xf
	s_nop 1
	v_add_f32_dpp v173, v173, v173 row_mirror row_mask:0xf bank_mask:0xf
	s_nop 1
	v_add_f32_dpp v173, v173, v173 row_bcast:15 row_mask:0xa bank_mask:0xf
	s_nop 1
	v_add_f32_dpp v173, v173, v173 row_bcast:31 row_mask:0xc bank_mask:0xf
	s_nop 1
	v_readlane_b32 s8, v173, 63
	s_nop 3
	v_mov_b32_e32 v158, s8
	v_fma_f32 v158, v158, v171, v172
	v_rsq_f32_e32 v158, v158
	s_nop 1
	v_pk_mul_f32 v[146:147], v[0:1], v[158:159] op_sel_hi:[1,0]
	v_pk_fma_f32 v[146:147], v[146:147], v[82:83], v[114:115]
	v_cvt_pk_bf16_f32 v160, v146, v147
	v_pk_mul_f32 v[148:149], v[2:3], v[158:159] op_sel_hi:[1,0]
	v_pk_fma_f32 v[148:149], v[148:149], v[84:85], v[116:117]
	v_cvt_pk_bf16_f32 v161, v148, v149
	global_store_dwordx2 v169, v[160:161], s[14:15] offset:0 nt
	v_pk_mul_f32 v[150:151], v[4:5], v[158:159] op_sel_hi:[1,0]
	v_pk_fma_f32 v[150:151], v[150:151], v[86:87], v[118:119]
	v_cvt_pk_bf16_f32 v162, v150, v151
	v_pk_mul_f32 v[152:153], v[6:7], v[158:159] op_sel_hi:[1,0]
	v_pk_fma_f32 v[152:153], v[152:153], v[88:89], v[120:121]
	v_cvt_pk_bf16_f32 v163, v152, v153
	global_store_dwordx2 v169, v[162:163], s[14:15] offset:512 nt
	v_pk_mul_f32 v[146:147], v[8:9], v[158:159] op_sel_hi:[1,0]
	v_pk_fma_f32 v[146:147], v[146:147], v[90:91], v[122:123]
	v_cvt_pk_bf16_f32 v164, v146, v147
	v_pk_mul_f32 v[148:149], v[10:11], v[158:159] op_sel_hi:[1,0]
	v_pk_fma_f32 v[148:149], v[148:149], v[92:93], v[124:125]
	v_cvt_pk_bf16_f32 v165, v148, v149
	global_store_dwordx2 v169, v[164:165], s[14:15] offset:1024 nt
	v_pk_mul_f32 v[150:151], v[12:13], v[158:159] op_sel_hi:[1,0]
	v_pk_fma_f32 v[150:151], v[150:151], v[94:95], v[126:127]
	v_cvt_pk_bf16_f32 v166, v150, v151
	v_pk_mul_f32 v[152:153], v[14:15], v[158:159] op_sel_hi:[1,0]
	v_pk_fma_f32 v[152:153], v[152:153], v[96:97], v[128:129]
	v_cvt_pk_bf16_f32 v167, v152, v153
	global_store_dwordx2 v169, v[166:167], s[14:15] offset:1536 nt
	v_pk_mul_f32 v[146:147], v[16:17], v[158:159] op_sel_hi:[1,0]
	v_pk_fma_f32 v[146:147], v[146:147], v[98:99], v[130:131]
	v_cvt_pk_bf16_f32 v160, v146, v147
	v_pk_mul_f32 v[148:149], v[18:19], v[158:159] op_sel_hi:[1,0]
	v_pk_fma_f32 v[148:149], v[148:149], v[100:101], v[132:133]
	v_cvt_pk_bf16_f32 v161, v148, v149
	global_store_dwordx2 v169, v[160:161], s[14:15] offset:2048 nt
	v_pk_mul_f32 v[150:151], v[20:21], v[158:159] op_sel_hi:[1,0]
	v_pk_fma_f32 v[150:151], v[150:151], v[102:103], v[134:135]
	v_cvt_pk_bf16_f32 v162, v150, v151
	v_pk_mul_f32 v[152:153], v[22:23], v[158:159] op_sel_hi:[1,0]
	v_pk_fma_f32 v[152:153], v[152:153], v[104:105], v[136:137]
	v_cvt_pk_bf16_f32 v163, v152, v153
	global_store_dwordx2 v169, v[162:163], s[14:15] offset:2560 nt
	v_pk_mul_f32 v[146:147], v[24:25], v[158:159] op_sel_hi:[1,0]
	v_pk_fma_f32 v[146:147], v[146:147], v[106:107], v[138:139]
	v_cvt_pk_bf16_f32 v164, v146, v147
	v_pk_mul_f32 v[148:149], v[26:27], v[158:159] op_sel_hi:[1,0]
	v_pk_fma_f32 v[148:149], v[148:149], v[108:109], v[140:141]
	v_cvt_pk_bf16_f32 v165, v148, v149
	global_store_dwordx2 v169, v[164:165], s[14:15] offset:3072 nt
	v_pk_mul_f32 v[150:151], v[28:29], v[158:159] op_sel_hi:[1,0]
	v_pk_fma_f32 v[150:151], v[150:151], v[110:111], v[142:143]
	v_cvt_pk_bf16_f32 v166, v150, v151
	v_pk_mul_f32 v[152:153], v[30:31], v[158:159] op_sel_hi:[1,0]
	v_pk_fma_f32 v[152:153], v[152:153], v[112:113], v[144:145]
	v_cvt_pk_bf16_f32 v167, v152, v153
	global_store_dwordx2 v169, v[166:167], s[14:15] offset:3584 nt
	s_lshr_b32 s1, s5, 9
	s_lshl_b32 s1, s1, 13
	s_and_b32 s8, s5, 0x1ff
	s_add_u32 s1, s1, s8
	s_add_u32 s8, s0, 1
	s_lshl_b32 s8, s8, 9
	s_add_u32 s1, s1, s8
	s_lshl_b32 s8, s1, 13
	s_add_u32 s10, s58, s8
	s_addc_u32 s11, s59, 0
	s_lshl_b32 s8, s1, 12
	s_add_u32 s9, s8, 0xb800000
	s_add_u32 s12, s52, s9
	s_addc_u32 s13, s53, 0
	s_add_u32 s9, s8, 0x2c800000
	s_add_u32 s14, s52, s9
	s_addc_u32 s15, s53, 0
	global_load_dwordx2 v[32:33], v169, s[12:13] offset:0 nt
	global_load_dwordx2 v[34:35], v169, s[12:13] offset:512 nt
	global_load_dwordx2 v[36:37], v169, s[12:13] offset:1024 nt
	global_load_dwordx2 v[38:39], v169, s[12:13] offset:1536 nt
	global_load_dwordx2 v[40:41], v169, s[12:13] offset:2048 nt
	global_load_dwordx2 v[42:43], v169, s[12:13] offset:2560 nt
	global_load_dwordx2 v[44:45], v169, s[12:13] offset:3072 nt
	global_load_dwordx2 v[46:47], v169, s[12:13] offset:3584 nt
	s_cmp_lt_u32 s0, 14
	s_cbranch_scc0 .Lrm3_nopf_o
	s_lshr_b32 s1, s5, 9
	s_lshl_b32 s1, s1, 13
	s_and_b32 s8, s5, 0x1ff
	s_add_u32 s1, s1, s8
	s_add_u32 s8, s0, 2
	s_lshl_b32 s8, s8, 9
	s_add_u32 s1, s1, s8
	s_lshl_b32 s8, s1, 13
	s_add_u32 s6, s58, s8
	s_addc_u32 s7, s59, 0
	global_load_dwordx4 v[0:3], v80, s[6:7] offset:0 nt
	global_load_dwordx4 v[4:7], v80, s[6:7] offset:1024 nt
	global_load_dwordx4 v[8:11], v80, s[6:7] offset:2048 nt
	global_load_dwordx4 v[12:15], v80, s[6:7] offset:3072 nt
	global_load_dwordx4 v[16:19], v168, s[6:7] offset:0 nt
	global_load_dwordx4 v[20:23], v168, s[6:7] offset:1024 nt
	global_load_dwordx4 v[24:27], v168, s[6:7] offset:2048 nt
	global_load_dwordx4 v[28:31], v168, s[6:7] offset:3072 nt
	s_waitcnt vmcnt(8)
	s_branch .Lrm3_pfd_o

.Lrm3_pfd_o:
	v_lshlrev_b32_e32 v146, 16, v32
	v_and_b32_e32 v147, 0xffff0000, v32
	v_pk_mul_f32 v[154:155], v[146:147], v[146:147]
	v_lshlrev_b32_e32 v148, 16, v33
	v_and_b32_e32 v149, 0xffff0000, v33
	v_pk_mul_f32 v[156:157], v[148:149], v[148:149]
	v_lshlrev_b32_e32 v150, 16, v34
	v_and_b32_e32 v151, 0xffff0000, v34
	v_pk_fma_f32 v[154:155], v[150:151], v[150:151], v[154:155]
	v_lshlrev_b32_e32 v152, 16, v35
	v_and_b32_e32 v153, 0xffff0000, v35
	v_pk_fma_f32 v[156:157], v[152:153], v[152:153], v[156:157]
	v_lshlrev_b32_e32 v146, 16, v36
	v_and_b32_e32 v147, 0xffff0000, v36
	v_pk_fma_f32 v[154:155], v[146:147], v[146:147], v[154:155]
	v_lshlrev_b32_e32 v148, 16, v37
	v_and_b32_e32 v149, 0xffff0000, v37
	v_pk_fma_f32 v[156:157], v[148:149], v[148:149], v[156:157]
	v_lshlrev_b32_e32 v150, 16, v38
	v_and_b32_e32 v151, 0xffff0000, v38
	v_pk_fma_f32 v[154:155], v[150:151], v[150:151], v[154:155]
	v_lshlrev_b32_e32 v152, 16, v39
	v_and_b32_e32 v153, 0xffff0000, v39
	v_pk_fma_f32 v[156:157], v[152:153], v[152:153], v[156:157]
	v_lshlrev_b32_e32 v146, 16, v40
	v_and_b32_e32 v147, 0xffff0000, v40
	v_pk_fma_f32 v[154:155], v[146:147], v[146:147], v[154:155]
	v_lshlrev_b32_e32 v148, 16, v41
	v_and_b32_e32 v149, 0xffff0000, v41
	v_pk_fma_f32 v[156:157], v[148:149], v[148:149], v[156:157]
	v_lshlrev_b32_e32 v150, 16, v42
	v_and_b32_e32 v151, 0xffff0000, v42
	v_pk_fma_f32 v[154:155], v[150:151], v[150:151], v[154:155]
	v_lshlrev_b32_e32 v152, 16, v43
	v_and_b32_e32 v153, 0xffff0000, v43
	v_pk_fma_f32 v[156:157], v[152:153], v[152:153], v[156:157]
	v_lshlrev_b32_e32 v146, 16, v44
	v_and_b32_e32 v147, 0xffff0000, v44
	v_pk_fma_f32 v[154:155], v[146:147], v[146:147], v[154:155]
	v_lshlrev_b32_e32 v148, 16, v45
	v_and_b32_e32 v149, 0xffff0000, v45
	v_pk_fma_f32 v[156:157], v[148:149], v[148:149], v[156:157]
	v_lshlrev_b32_e32 v150, 16, v46
	v_and_b32_e32 v151, 0xffff0000, v46
	v_pk_fma_f32 v[154:155], v[150:151], v[150:151], v[154:155]
	v_lshlrev_b32_e32 v152, 16, v47
	v_and_b32_e32 v153, 0xffff0000, v47
	v_pk_fma_f32 v[156:157], v[152:153], v[152:153], v[156:157]
	v_pk_add_f32 v[154:155], v[154:155], v[156:157]
	s_nop 0
	v_add_f32_e32 v173, v154, v155
	s_nop 1
	v_add_f32_dpp v173, v173, v173 quad_perm:[1,0,3,2] row_mask:0xf bank_mask:0xf
	s_nop 1
	v_add_f32_dpp v173, v173, v173 quad_perm:[2,3,0,1] row_mask:0xf bank_mask:0xf
	s_nop 1
	v_add_f32_dpp v173, v173, v173 row_half_mirror row_mask:0xf bank_mask:0xf
	s_nop 1
	v_add_f32_dpp v173, v173, v173 row_mirror row_mask:0xf bank_mask:0xf
	s_nop 1
	v_add_f32_dpp v173, v173, v173 row_bcast:15 row_mask:0xa bank_mask:0xf
	s_nop 1
	v_add_f32_dpp v173, v173, v173 row_bcast:31 row_mask:0xc bank_mask:0xf
	s_nop 1
	v_readlane_b32 s8, v173, 63
	s_nop 3
	v_mov_b32_e32 v158, s8
	v_fma_f32 v158, v158, v171, v172
	v_rsq_f32_e32 v158, v158
	s_nop 1
	v_lshlrev_b32_e32 v146, 16, v32
	v_and_b32_e32 v147, 0xffff0000, v32
	v_pk_mul_f32 v[146:147], v[146:147], v[158:159] op_sel_hi:[1,0]
	v_pk_fma_f32 v[178:179], v[48:49], v[146:147], v[178:179]
	v_lshlrev_b32_e32 v148, 16, v33
	v_and_b32_e32 v149, 0xffff0000, v33
	v_pk_mul_f32 v[148:149], v[148:149], v[158:159] op_sel_hi:[1,0]
	v_pk_fma_f32 v[180:181], v[50:51], v[148:149], v[180:181]
	v_lshlrev_b32_e32 v150, 16, v34
	v_and_b32_e32 v151, 0xffff0000, v34
	v_pk_mul_f32 v[150:151], v[150:151], v[158:159] op_sel_hi:[1,0]
	v_pk_fma_f32 v[182:183], v[52:53], v[150:151], v[182:183]
	v_lshlrev_b32_e32 v152, 16, v35
	v_and_b32_e32 v153, 0xffff0000, v35
	v_pk_mul_f32 v[152:153], v[152:153], v[158:159] op_sel_hi:[1,0]
	v_pk_fma_f32 v[184:185], v[54:55], v[152:153], v[184:185]
	v_lshlrev_b32_e32 v146, 16, v36
	v_and_b32_e32 v147, 0xffff0000, v36
	v_pk_mul_f32 v[146:147], v[146:147], v[158:159] op_sel_hi:[1,0]
	v_pk_fma_f32 v[192:193], v[56:57], v[146:147], v[192:193]
	v_lshlrev_b32_e32 v148, 16, v37
	v_and_b32_e32 v149, 0xffff0000, v37
	v_pk_mul_f32 v[148:149], v[148:149], v[158:159] op_sel_hi:[1,0]
	v_pk_fma_f32 v[194:195], v[58:59], v[148:149], v[194:195]
	v_lshlrev_b32_e32 v150, 16, v38
	v_and_b32_e32 v151, 0xffff0000, v38
	v_pk_mul_f32 v[150:151], v[150:151], v[158:159] op_sel_hi:[1,0]
	v_pk_fma_f32 v[198:199], v[60:61], v[150:151], v[198:199]
	v_lshlrev_b32_e32 v152, 16, v39
	v_and_b32_e32 v153, 0xffff0000, v39
	v_pk_mul_f32 v[152:153], v[152:153], v[158:159] op_sel_hi:[1,0]
	v_pk_fma_f32 v[200:201], v[62:63], v[152:153], v[200:201]
	v_lshlrev_b32_e32 v146, 16, v40
	v_and_b32_e32 v147, 0xffff0000, v40
	v_pk_mul_f32 v[146:147], v[146:147], v[158:159] op_sel_hi:[1,0]
	v_pk_fma_f32 v[202:203], v[64:65], v[146:147], v[202:203]
	v_lshlrev_b32_e32 v148, 16, v41
	v_and_b32_e32 v149, 0xffff0000, v41
	v_pk_mul_f32 v[148:149], v[148:149], v[158:159] op_sel_hi:[1,0]
	v_pk_fma_f32 v[204:205], v[66:67], v[148:149], v[204:205]
	v_lshlrev_b32_e32 v150, 16, v42
	v_and_b32_e32 v151, 0xffff0000, v42
	v_pk_mul_f32 v[150:151], v[150:151], v[158:159] op_sel_hi:[1,0]
	v_pk_fma_f32 v[206:207], v[68:69], v[150:151], v[206:207]
	v_lshlrev_b32_e32 v152, 16, v43
	v_and_b32_e32 v153, 0xffff0000, v43
	v_pk_mul_f32 v[152:153], v[152:153], v[158:159] op_sel_hi:[1,0]
	v_pk_fma_f32 v[208:209], v[70:71], v[152:153], v[208:209]
	v_lshlrev_b32_e32 v146, 16, v44
	v_and_b32_e32 v147, 0xffff0000, v44
	v_pk_mul_f32 v[146:147], v[146:147], v[158:159] op_sel_hi:[1,0]
	v_pk_fma_f32 v[210:211], v[72:73], v[146:147], v[210:211]
	v_lshlrev_b32_e32 v148, 16, v45
	v_and_b32_e32 v149, 0xffff0000, v45
	v_pk_mul_f32 v[148:149], v[148:149], v[158:159] op_sel_hi:[1,0]
	v_pk_fma_f32 v[212:213], v[74:75], v[148:149], v[212:213]
	v_lshlrev_b32_e32 v150, 16, v46
	v_and_b32_e32 v151, 0xffff0000, v46
	v_pk_mul_f32 v[150:151], v[150:151], v[158:159] op_sel_hi:[1,0]
	v_pk_fma_f32 v[214:215], v[76:77], v[150:151], v[214:215]
	v_lshlrev_b32_e32 v152, 16, v47
	v_and_b32_e32 v153, 0xffff0000, v47
	v_pk_mul_f32 v[152:153], v[152:153], v[158:159] op_sel_hi:[1,0]
	v_pk_fma_f32 v[216:217], v[78:79], v[152:153], v[216:217]
	s_nop 0
	global_store_dwordx4 v80, v[178:181], s[10:11] offset:0 nt
	global_store_dwordx4 v80, v[182:185], s[10:11] offset:1024 nt
	global_store_dwordx4 v80, v[192:195], s[10:11] offset:2048 nt
	global_store_dwordx4 v80, v[198:201], s[10:11] offset:3072 nt
	global_store_dwordx4 v168, v[202:205], s[10:11] offset:0 nt
	global_store_dwordx4 v168, v[206:209], s[10:11] offset:1024 nt
	global_store_dwordx4 v168, v[210:213], s[10:11] offset:2048 nt
	global_store_dwordx4 v168, v[214:217], s[10:11] offset:3072 nt
	v_pk_mul_f32 v[154:155], v[178:179], v[178:179]
	v_pk_mul_f32 v[156:157], v[180:181], v[180:181]
	v_pk_fma_f32 v[154:155], v[182:183], v[182:183], v[154:155]
	v_pk_fma_f32 v[156:157], v[184:185], v[184:185], v[156:157]
	v_pk_fma_f32 v[154:155], v[192:193], v[192:193], v[154:155]
	v_pk_fma_f32 v[156:157], v[194:195], v[194:195], v[156:157]
	v_pk_fma_f32 v[154:155], v[198:199], v[198:199], v[154:155]
	v_pk_fma_f32 v[156:157], v[200:201], v[200:201], v[156:157]
	v_pk_fma_f32 v[154:155], v[202:203], v[202:203], v[154:155]
	v_pk_fma_f32 v[156:157], v[204:205], v[204:205], v[156:157]
	v_pk_fma_f32 v[154:155], v[206:207], v[206:207], v[154:155]
	v_pk_fma_f32 v[156:157], v[208:209], v[208:209], v[156:157]
	v_pk_fma_f32 v[154:155], v[210:211], v[210:211], v[154:155]
	v_pk_fma_f32 v[156:157], v[212:213], v[212:213], v[156:157]
	v_pk_fma_f32 v[154:155], v[214:215], v[214:215], v[154:155]
	v_pk_fma_f32 v[156:157], v[216:217], v[216:217], v[156:157]
	v_pk_add_f32 v[154:155], v[154:155], v[156:157]
	s_nop 0
	v_add_f32_e32 v173, v154, v155
	s_nop 1
	v_add_f32_dpp v173, v173, v173 quad_perm:[1,0,3,2] row_mask:0xf bank_mask:0xf
	s_nop 1
	v_add_f32_dpp v173, v173, v173 quad_perm:[2,3,0,1] row_mask:0xf bank_mask:0xf
	s_nop 1
	v_add_f32_dpp v173, v173, v173 row_half_mirror row_mask:0xf bank_mask:0xf
	s_nop 1
	v_add_f32_dpp v173, v173, v173 row_mirror row_mask:0xf bank_mask:0xf
	s_nop 1
	v_add_f32_dpp v173, v173, v173 row_bcast:15 row_mask:0xa bank_mask:0xf
	s_nop 1
	v_add_f32_dpp v173, v173, v173 row_bcast:31 row_mask:0xc bank_mask:0xf
	s_nop 1
	v_readlane_b32 s8, v173, 63
	s_nop 3
	v_mov_b32_e32 v158, s8
	v_fma_f32 v158, v158, v171, v172
	v_rsq_f32_e32 v158, v158
	s_nop 1
	v_pk_mul_f32 v[146:147], v[178:179], v[158:159] op_sel_hi:[1,0]
	v_pk_fma_f32 v[146:147], v[146:147], v[82:83], v[114:115]
	v_cvt_pk_bf16_f32 v160, v146, v147
	v_pk_mul_f32 v[148:149], v[180:181], v[158:159] op_sel_hi:[1,0]
	v_pk_fma_f32 v[148:149], v[148:149], v[84:85], v[116:117]
	v_cvt_pk_bf16_f32 v161, v148, v149
	global_store_dwordx2 v169, v[160:161], s[14:15] offset:0 nt
	v_pk_mul_f32 v[150:151], v[182:183], v[158:159] op_sel_hi:[1,0]
	v_pk_fma_f32 v[150:151], v[150:151], v[86:87], v[118:119]
	v_cvt_pk_bf16_f32 v162, v150, v151
	v_pk_mul_f32 v[152:153], v[184:185], v[158:159] op_sel_hi:[1,0]
	v_pk_fma_f32 v[152:153], v[152:153], v[88:89], v[120:121]
	v_cvt_pk_bf16_f32 v163, v152, v153
	global_store_dwordx2 v169, v[162:163], s[14:15] offset:512 nt
	v_pk_mul_f32 v[146:147], v[192:193], v[158:159] op_sel_hi:[1,0]
	v_pk_fma_f32 v[146:147], v[146:147], v[90:91], v[122:123]
	v_cvt_pk_bf16_f32 v164, v146, v147
	v_pk_mul_f32 v[148:149], v[194:195], v[158:159] op_sel_hi:[1,0]
	v_pk_fma_f32 v[148:149], v[148:149], v[92:93], v[124:125]
	v_cvt_pk_bf16_f32 v165, v148, v149
	global_store_dwordx2 v169, v[164:165], s[14:15] offset:1024 nt
	v_pk_mul_f32 v[150:151], v[198:199], v[158:159] op_sel_hi:[1,0]
	v_pk_fma_f32 v[150:151], v[150:151], v[94:95], v[126:127]
	v_cvt_pk_bf16_f32 v166, v150, v151
	v_pk_mul_f32 v[152:153], v[200:201], v[158:159] op_sel_hi:[1,0]
	v_pk_fma_f32 v[152:153], v[152:153], v[96:97], v[128:129]
	v_cvt_pk_bf16_f32 v167, v152, v153
	global_store_dwordx2 v169, v[166:167], s[14:15] offset:1536 nt
	v_pk_mul_f32 v[146:147], v[202:203], v[158:159] op_sel_hi:[1,0]
	v_pk_fma_f32 v[146:147], v[146:147], v[98:99], v[130:131]
	v_cvt_pk_bf16_f32 v160, v146, v147
	v_pk_mul_f32 v[148:149], v[204:205], v[158:159] op_sel_hi:[1,0]
	v_pk_fma_f32 v[148:149], v[148:149], v[100:101], v[132:133]
	v_cvt_pk_bf16_f32 v161, v148, v149
	global_store_dwordx2 v169, v[160:161], s[14:15] offset:2048 nt
	v_pk_mul_f32 v[150:151], v[206:207], v[158:159] op_sel_hi:[1,0]
	v_pk_fma_f32 v[150:151], v[150:151], v[102:103], v[134:135]
	v_cvt_pk_bf16_f32 v162, v150, v151
	v_pk_mul_f32 v[152:153], v[208:209], v[158:159] op_sel_hi:[1,0]
	v_pk_fma_f32 v[152:153], v[152:153], v[104:105], v[136:137]
	v_cvt_pk_bf16_f32 v163, v152, v153
	global_store_dwordx2 v169, v[162:163], s[14:15] offset:2560 nt
	v_pk_mul_f32 v[146:147], v[210:211], v[158:159] op_sel_hi:[1,0]
	v_pk_fma_f32 v[146:147], v[146:147], v[106:107], v[138:139]
	v_cvt_pk_bf16_f32 v164, v146, v147
	v_pk_mul_f32 v[148:149], v[212:213], v[158:159] op_sel_hi:[1,0]
	v_pk_fma_f32 v[148:149], v[148:149], v[108:109], v[140:141]
	v_cvt_pk_bf16_f32 v165, v148, v149
	global_store_dwordx2 v169, v[164:165], s[14:15] offset:3072 nt
	v_pk_mul_f32 v[150:151], v[214:215], v[158:159] op_sel_hi:[1,0]
	v_pk_fma_f32 v[150:151], v[150:151], v[110:111], v[142:143]
	v_cvt_pk_bf16_f32 v166, v150, v151
	v_pk_mul_f32 v[152:153], v[216:217], v[158:159] op_sel_hi:[1,0]
	v_pk_fma_f32 v[152:153], v[152:153], v[112:113], v[144:145]
	v_cvt_pk_bf16_f32 v167, v152, v153
	global_store_dwordx2 v169, v[166:167], s[14:15] offset:3584 nt
	s_add_u32 s0, s0, 2
	s_cmp_lt_u32 s0, 16
	s_cbranch_scc1 .Lrm3_loop
	s_branch .Lrm3_done
